# v051 + SGU: wait for the first u value moved from right after the first four u loads down to its first use (all 32 loads in flight)
# baseline (speedup 1.0000x reference)
; __device__ __forceinline__ unsigned cvt_pk_bf16(float lo, float hi) { unsigned r; asm volatile("v_cvt_pk_bf16_f32 %0, %1, %2" : "=v"(r) : "v"(lo), "v"(hi)); return r; }
; __device__ __forceinline__ float bf_lo(unsigned w) { return __uint_as_float(w << 16); }
; __device__ __forceinline__ float bf_hi(unsigned w) { return __uint_as_float(w & 0xffff0000u); }
; #define LAS __attribute__((address_space(3)))
; __device__ __forceinline__ void sgu_unit(LAS unsigned char* lds, bf16* U, const bf16* VS, const float* SGS, const float* lnw, const float* lnb, const v4u* WF, const float* bsl, int unit, int tid) {
;     ...
;     {
;         const int c8 = lane & 7, rp = lane >> 3, col = colbase + 8 * c8;
;         v4u sl[8][2];
; #pragma unroll
;         for (int i = 0; i < 8; ++i) { const int s0 = 2 * (rp + 8 * i); sl[i][0] = *(const v4u*)(VS + (size_t)(r0 + s0) * 1024 + col); sl[i][1] = *(const v4u*)(VS + (size_t)(r0 + s0 + 1) * 1024 + col); }
;         const f32x4 lw0 = *(const f32x4*)(lnw + col), lw1 = *(const f32x4*)(lnw + col + 4), lb0 = *(const f32x4*)(lnb + col), lb1 = *(const f32x4*)(lnb + col + 4);
;         const float lw[8] = {lw0.x, lw0.y, lw0.z, lw0.w, lw1.x, lw1.y, lw1.z, lw1.w}, lb[8] = {lb0.x, lb0.y, lb0.z, lb0.w, lb1.x, lb1.y, lb1.z, lb1.w};
;         __syncthreads();
;         LAS unsigned char* wbase = vt + c8 * SGU_VP + rp * 4;
; #pragma unroll
;         for (int i = 0; i < 8; ++i) {
;             const f32x4 st4 = *(const LAS f32x4*)(stat + 4 * (rp + 8 * i));
;             const v4u w0 = sl[i][0], w1 = sl[i][1];
;             const unsigned A0[4] = {w0.x, w0.y, w0.z, w0.w}, A1[4] = {w1.x, w1.y, w1.z, w1.w};
; #pragma unroll
;             for (int e = 0; e < 8; ++e) { typedef float f32x2p __attribute__((ext_vector_type(2)));
;                 f32x2p v; v.x = (e & 1) ? bf_hi(A0[e >> 1]) : bf_lo(A0[e >> 1]); v.y = (e & 1) ? bf_hi(A1[e >> 1]) : bf_lo(A1[e >> 1]);
;                 const f32x2p mn = {st4.x, st4.z}, rs = {st4.y, st4.w};
;                 const f32x2p o = ((v - mn) * rs) * lw[e] + lb[e];
;                 *(LAS unsigned*)(wbase + e * 8 * SGU_VP + i * 32) = cvt_pk_bf16(o.x, o.y); }
;         }
;     }
.LBB0_498:
	s_or_b64 exec, exec, s[14:15]
	v_mov_b32_e32 v122, v222
	v_mov_b32_e32 v123, v223
	v_mov_b32_e32 v124, v224
	v_mov_b32_e32 v125, v225
	v_mov_b32_e32 v126, v226
	v_mov_b32_e32 v127, v227
	v_mov_b32_e32 v128, v228
	v_mov_b32_e32 v129, v229
	v_mov_b32_e32 v114, v230
	v_mov_b32_e32 v115, v231
	v_mov_b32_e32 v116, v232
	v_mov_b32_e32 v117, v233
	v_mov_b32_e32 v118, v234
	v_mov_b32_e32 v119, v235
	v_mov_b32_e32 v120, v236
	v_mov_b32_e32 v121, v237
	v_mov_b32_e32 v106, v238
	v_mov_b32_e32 v107, v239
	v_mov_b32_e32 v108, v240
	v_mov_b32_e32 v109, v241
	v_mov_b32_e32 v110, v242
	v_mov_b32_e32 v111, v243
	v_mov_b32_e32 v112, v244
	v_mov_b32_e32 v113, v245
	v_or_b32_e32 v158, v82, v168
	v_or_b32_e32 v82, v158, v170
	v_lshl_or_b32 v84, s16, 11, v181
	v_mov_b32_e32 v85, v147
	v_ashrrev_i32_e32 v83, 31, v82
	v_lshl_add_u64 v[84:85], s[48:49], 0, v[84:85]
	v_lshl_add_u64 v[90:91], v[82:83], 1, v[84:85]
	v_lshlrev_b64 v[82:83], 2, v[82:83]
	s_waitcnt lgkmcnt(0)
	v_lshl_add_u64 v[84:85], s[30:31], 0, v[82:83]
	v_lshl_add_u64 v[86:87], s[50:51], 0, v[82:83]
	global_load_dwordx4 v[98:101], v[86:87], off
	global_load_dwordx4 v[102:105], v[84:85], off
	s_nop 0
	global_load_dwordx4 v[82:85], v[84:85], off offset:16
	s_nop 0
	global_load_dwordx4 v[86:89], v[86:87], off offset:16
	v_add_co_u32_e32 v92, vcc, 0x8000, v90
	s_mov_b64 s[14:15], 0
	s_nop 0
	v_addc_co_u32_e32 v93, vcc, 0, v91, vcc
	v_add_co_u32_e32 v94, vcc, 0x10000, v90
	s_waitcnt vmcnt(7)
	v_and_b32_e32 v228, 0xffff0000, v206
	v_addc_co_u32_e32 v95, vcc, 0, v91, vcc
	v_add_co_u32_e32 v92, vcc, 0x18000, v90
	s_waitcnt vmcnt(8)
	v_and_b32_e32 v229, 0xffff0000, v210
	v_addc_co_u32_e32 v93, vcc, 0, v91, vcc
	v_add_co_u32_e32 v94, vcc, 0x20000, v90
	v_addc_co_u32_e32 v95, vcc, 0, v91, vcc
	v_add_co_u32_e32 v92, vcc, 0x28000, v90
	v_addc_co_u32_e32 v93, vcc, 0, v91, vcc
	v_add_co_u32_e32 v94, vcc, 0x30000, v90
	v_addc_co_u32_e32 v95, vcc, 0, v91, vcc
	v_add_co_u32_e32 v96, vcc, 0x38000, v90
	v_addc_co_u32_e32 v97, vcc, 0, v91, vcc
	v_mov_b32_e32 v90, v248
	v_mov_b32_e32 v91, v249
	v_mov_b32_e32 v92, v250
	v_mov_b32_e32 v93, v251
	s_nop 0
	v_mov_b32_e32 v94, v252
	v_mov_b32_e32 v95, v253
	v_mov_b32_e32 v96, v254
	v_mov_b32_e32 v97, v255
	s_barrier
	ds_read_b128 v[222:225], v182
	v_lshlrev_b32_e32 v230, 16, v207
	v_lshlrev_b32_e32 v231, 16, v211
	s_waitcnt vmcnt(2)
	v_mov_b32_e32 v160, v105
	v_mov_b32_e32 v162, v101
	s_waitcnt lgkmcnt(0)
	v_mov_b32_e32 v226, v222
	v_mov_b32_e32 v227, v224
	v_mov_b32_e32 v224, v223
	v_lshlrev_b32_e32 v222, 16, v206
	v_lshlrev_b32_e32 v223, 16, v210
	v_pk_add_f32 v[222:223], v[222:223], v[226:227] neg_lo:[0,1] neg_hi:[0,1]
	v_and_b32_e32 v206, 0xffff0000, v207
	v_and_b32_e32 v207, 0xffff0000, v211
	v_pk_add_f32 v[228:229], v[228:229], v[226:227] neg_lo:[0,1] neg_hi:[0,1]
	v_pk_mul_f32 v[222:223], v[224:225], v[222:223]
	v_pk_add_f32 v[206:207], v[206:207], v[226:227] neg_lo:[0,1] neg_hi:[0,1]
	v_pk_add_f32 v[230:231], v[230:231], v[226:227] neg_lo:[0,1] neg_hi:[0,1]
	v_pk_mul_f32 v[228:229], v[224:225], v[228:229]
	v_pk_fma_f32 v[222:223], v[102:103], v[222:223], v[98:99] op_sel_hi:[0,1,0]
	v_cvt_pk_bf16_f32 v159, v222, v223
	v_pk_mul_f32 v[206:207], v[224:225], v[206:207]
	v_pk_mul_f32 v[230:231], v[224:225], v[230:231]
	v_pk_fma_f32 v[228:229], v[102:103], v[228:229], v[98:99] op_sel:[1,0,1]
	ds_write_b32 v178, v159 offset:1024
	v_cvt_pk_bf16_f32 v159, v228, v229
	v_pk_fma_f32 v[206:207], v[160:161], v[206:207], v[162:163] op_sel_hi:[0,1,0]
	v_pk_fma_f32 v[230:231], v[104:105], v[230:231], v[100:101] op_sel_hi:[0,1,0]
	ds_write_b32 v178, v159 offset:3200
	v_cvt_pk_bf16_f32 v159, v230, v231
	ds_write_b32 v178, v159 offset:5376
	v_cvt_pk_bf16_f32 v101, v206, v207
	v_lshlrev_b32_e32 v206, 16, v208
	v_lshlrev_b32_e32 v207, 16, v212
	v_pk_add_f32 v[206:207], v[206:207], v[226:227] neg_lo:[0,1] neg_hi:[0,1]
	ds_write_b32 v178, v101 offset:7552
	v_pk_mul_f32 v[206:207], v[224:225], v[206:207]
	s_waitcnt vmcnt(1)
	v_mov_b32_e32 v164, v85
	s_waitcnt vmcnt(0)
	v_pk_fma_f32 v[206:207], v[82:83], v[206:207], v[86:87] op_sel_hi:[0,1,0]
	v_cvt_pk_bf16_f32 v101, v206, v207
	v_and_b32_e32 v206, 0xffff0000, v208
	v_and_b32_e32 v207, 0xffff0000, v212
	v_pk_add_f32 v[206:207], v[206:207], v[226:227] neg_lo:[0,1] neg_hi:[0,1]
	ds_write_b32 v178, v101 offset:9728
	v_pk_mul_f32 v[206:207], v[224:225], v[206:207]
	v_mov_b32_e32 v166, v89
	v_pk_fma_f32 v[206:207], v[82:83], v[206:207], v[86:87] op_sel:[1,0,1]
	v_ashrrev_i32_e32 v159, 31, v158
	v_cvt_pk_bf16_f32 v101, v206, v207
	v_lshlrev_b32_e32 v206, 16, v209
	v_lshlrev_b32_e32 v207, 16, v213
	v_pk_add_f32 v[206:207], v[206:207], v[226:227] neg_lo:[0,1] neg_hi:[0,1]
	ds_write_b32 v178, v101 offset:11904
	v_pk_mul_f32 v[206:207], v[224:225], v[206:207]
	s_nop 0
	v_pk_fma_f32 v[206:207], v[84:85], v[206:207], v[88:89] op_sel_hi:[0,1,0]
	v_cvt_pk_bf16_f32 v101, v206, v207
	v_and_b32_e32 v206, 0xffff0000, v209
	v_and_b32_e32 v207, 0xffff0000, v213
	v_pk_add_f32 v[206:207], v[206:207], v[226:227] neg_lo:[0,1] neg_hi:[0,1]
	ds_write_b32 v178, v101 offset:14080
	v_pk_mul_f32 v[206:207], v[224:225], v[206:207]
	s_nop 0
	v_pk_fma_f32 v[206:207], v[164:165], v[206:207], v[166:167] op_sel_hi:[0,1,0]
	v_cvt_pk_bf16_f32 v85, v206, v207
	ds_write_b32 v178, v85 offset:16256
	ds_read_b128 v[206:209], v182 offset:128
	s_waitcnt lgkmcnt(0)
	v_mov_b32_e32 v210, v206
	v_mov_b32_e32 v211, v208
	v_mov_b32_e32 v208, v207
	s_waitcnt vmcnt(13)
	v_lshlrev_b32_e32 v206, 16, v214
	s_waitcnt vmcnt(12)
; __device__ __forceinline__ unsigned cvt_pk_bf16(float lo, float hi) { unsigned r; asm volatile("v_cvt_pk_bf16_f32 %0, %1, %2" : "=v"(r) : "v"(lo), "v"(hi)); return r; }
; __device__ __forceinline__ float bf_lo(unsigned w) { return __uint_as_float(w << 16); }
; __device__ __forceinline__ float bf_hi(unsigned w) { return __uint_as_float(w & 0xffff0000u); }
; #define LAS __attribute__((address_space(3)))
; __device__ __forceinline__ void sgu_unit(LAS unsigned char* lds, bf16* U, const bf16* VS, const float* SGS, const float* lnw, const float* lnb, const v4u* WF, const float* bsl, int unit, int tid) {
;     ...
;         LAS unsigned char* wbase = vt + c8 * SGU_VP + rp * 4;
; #pragma unroll
;         for (int i = 0; i < 8; ++i) {
;             const f32x4 st4 = *(const LAS f32x4*)(stat + 4 * (rp + 8 * i));
;             const v4u w0 = sl[i][0], w1 = sl[i][1];
;             const unsigned A0[4] = {w0.x, w0.y, w0.z, w0.w}, A1[4] = {w1.x, w1.y, w1.z, w1.w};
; #pragma unroll
;             for (int e = 0; e < 8; ++e) { typedef float f32x2p __attribute__((ext_vector_type(2)));
;                 f32x2p v; v.x = (e & 1) ? bf_hi(A0[e >> 1]) : bf_lo(A0[e >> 1]); v.y = (e & 1) ? bf_hi(A1[e >> 1]) : bf_lo(A1[e >> 1]);
;                 const f32x2p mn = {st4.x, st4.z}, rs = {st4.y, st4.w};
;                 const f32x2p o = ((v - mn) * rs) * lw[e] + lb[e];
;                 *(LAS unsigned*)(wbase + e * 8 * SGU_VP + i * 32) = cvt_pk_bf16(o.x, o.y); }
;         }
;     }
	v_lshlrev_b32_e32 v207, 16, v218
	v_pk_add_f32 v[206:207], v[206:207], v[210:211] neg_lo:[0,1] neg_hi:[0,1]
	s_nop 0
	v_pk_mul_f32 v[206:207], v[208:209], v[206:207]
	s_nop 0
	v_pk_fma_f32 v[206:207], v[102:103], v[206:207], v[98:99] op_sel_hi:[0,1,0]
	v_cvt_pk_bf16_f32 v85, v206, v207
	v_and_b32_e32 v206, 0xffff0000, v214
	v_and_b32_e32 v207, 0xffff0000, v218
	v_pk_add_f32 v[206:207], v[206:207], v[210:211] neg_lo:[0,1] neg_hi:[0,1]
	ds_write_b32 v178, v85 offset:1056
	v_pk_mul_f32 v[206:207], v[208:209], v[206:207]
	s_nop 0
	v_pk_fma_f32 v[206:207], v[102:103], v[206:207], v[98:99] op_sel:[1,0,1]
	s_nop 0
	v_cvt_pk_bf16_f32 v85, v206, v207
	v_lshlrev_b32_e32 v206, 16, v215
	v_lshlrev_b32_e32 v207, 16, v219
	v_pk_add_f32 v[206:207], v[206:207], v[210:211] neg_lo:[0,1] neg_hi:[0,1]
	ds_write_b32 v178, v85 offset:3232
	v_pk_mul_f32 v[206:207], v[208:209], v[206:207]
	s_nop 0
	v_pk_fma_f32 v[206:207], v[104:105], v[206:207], v[100:101] op_sel_hi:[0,1,0]
	v_cvt_pk_bf16_f32 v85, v206, v207
	v_and_b32_e32 v206, 0xffff0000, v215
	v_and_b32_e32 v207, 0xffff0000, v219
	v_pk_add_f32 v[206:207], v[206:207], v[210:211] neg_lo:[0,1] neg_hi:[0,1]
	ds_write_b32 v178, v85 offset:5408
	v_pk_mul_f32 v[206:207], v[208:209], v[206:207]
	s_nop 0
	v_pk_fma_f32 v[206:207], v[160:161], v[206:207], v[162:163] op_sel_hi:[0,1,0]
	v_cvt_pk_bf16_f32 v85, v206, v207
	v_lshlrev_b32_e32 v206, 16, v216
	v_lshlrev_b32_e32 v207, 16, v220
	v_pk_add_f32 v[206:207], v[206:207], v[210:211] neg_lo:[0,1] neg_hi:[0,1]
	ds_write_b32 v178, v85 offset:7584
	v_pk_mul_f32 v[206:207], v[208:209], v[206:207]
	s_nop 0
	v_pk_fma_f32 v[206:207], v[82:83], v[206:207], v[86:87] op_sel_hi:[0,1,0]
	v_cvt_pk_bf16_f32 v85, v206, v207
	v_and_b32_e32 v206, 0xffff0000, v216
	v_and_b32_e32 v207, 0xffff0000, v220
	v_pk_add_f32 v[206:207], v[206:207], v[210:211] neg_lo:[0,1] neg_hi:[0,1]
	ds_write_b32 v178, v85 offset:9760
	v_pk_mul_f32 v[206:207], v[208:209], v[206:207]
	s_nop 0
	v_pk_fma_f32 v[206:207], v[82:83], v[206:207], v[86:87] op_sel:[1,0,1]
	s_nop 0
	v_cvt_pk_bf16_f32 v85, v206, v207
	v_lshlrev_b32_e32 v206, 16, v217
	v_lshlrev_b32_e32 v207, 16, v221
	v_pk_add_f32 v[206:207], v[206:207], v[210:211] neg_lo:[0,1] neg_hi:[0,1]
	ds_write_b32 v178, v85 offset:11936
	v_pk_mul_f32 v[206:207], v[208:209], v[206:207]
	s_nop 0
	v_pk_fma_f32 v[206:207], v[84:85], v[206:207], v[88:89] op_sel_hi:[0,1,0]
	v_cvt_pk_bf16_f32 v85, v206, v207
	v_and_b32_e32 v206, 0xffff0000, v217
	v_and_b32_e32 v207, 0xffff0000, v221
	v_pk_add_f32 v[206:207], v[206:207], v[210:211] neg_lo:[0,1] neg_hi:[0,1]
	ds_write_b32 v178, v85 offset:14112
	v_pk_mul_f32 v[206:207], v[208:209], v[206:207]
	s_nop 0
	v_pk_fma_f32 v[206:207], v[164:165], v[206:207], v[166:167] op_sel_hi:[0,1,0]
	v_cvt_pk_bf16_f32 v85, v206, v207
	ds_write_b32 v178, v85 offset:16288
	ds_read_b128 v[206:209], v182 offset:256
	s_waitcnt lgkmcnt(0)
	v_mov_b32_e32 v210, v206
	v_mov_b32_e32 v211, v208
	v_mov_b32_e32 v208, v207
	s_waitcnt vmcnt(11)
	v_lshlrev_b32_e32 v206, 16, v138
	s_waitcnt vmcnt(10)
	v_lshlrev_b32_e32 v207, 16, v142
	v_pk_add_f32 v[206:207], v[206:207], v[210:211] neg_lo:[0,1] neg_hi:[0,1]
	s_nop 0
	v_pk_mul_f32 v[206:207], v[208:209], v[206:207]
	s_nop 0
	v_pk_fma_f32 v[206:207], v[102:103], v[206:207], v[98:99] op_sel_hi:[0,1,0]
	v_cvt_pk_bf16_f32 v85, v206, v207
	v_and_b32_e32 v206, 0xffff0000, v138
	v_and_b32_e32 v207, 0xffff0000, v142
	v_pk_add_f32 v[206:207], v[206:207], v[210:211] neg_lo:[0,1] neg_hi:[0,1]
	ds_write_b32 v178, v85 offset:1088
	v_pk_mul_f32 v[206:207], v[208:209], v[206:207]
	v_and_b32_e32 v138, 0xffff0000, v139
	v_pk_fma_f32 v[206:207], v[102:103], v[206:207], v[98:99] op_sel:[1,0,1]
	s_nop 0
	v_cvt_pk_bf16_f32 v85, v206, v207
	v_lshlrev_b32_e32 v206, 16, v139
	v_lshlrev_b32_e32 v207, 16, v143
	v_and_b32_e32 v139, 0xffff0000, v143
	v_pk_add_f32 v[206:207], v[206:207], v[210:211] neg_lo:[0,1] neg_hi:[0,1]
	v_pk_add_f32 v[138:139], v[138:139], v[210:211] neg_lo:[0,1] neg_hi:[0,1]
	v_pk_mul_f32 v[206:207], v[208:209], v[206:207]
	v_pk_mul_f32 v[138:139], v[208:209], v[138:139]
	ds_write_b32 v178, v85 offset:3264
	v_pk_fma_f32 v[206:207], v[104:105], v[206:207], v[100:101] op_sel_hi:[0,1,0]
	v_cvt_pk_bf16_f32 v85, v206, v207
	v_pk_fma_f32 v[138:139], v[160:161], v[138:139], v[162:163] op_sel_hi:[0,1,0]
	ds_write_b32 v178, v85 offset:5440
	v_cvt_pk_bf16_f32 v85, v138, v139
	v_lshlrev_b32_e32 v138, 16, v140
	v_lshlrev_b32_e32 v139, 16, v144
	v_pk_add_f32 v[138:139], v[138:139], v[210:211] neg_lo:[0,1] neg_hi:[0,1]
	ds_write_b32 v178, v85 offset:7616
	v_pk_mul_f32 v[138:139], v[208:209], v[138:139]
	s_nop 0
	v_pk_fma_f32 v[138:139], v[82:83], v[138:139], v[86:87] op_sel_hi:[0,1,0]
	v_cvt_pk_bf16_f32 v85, v138, v139
	v_and_b32_e32 v138, 0xffff0000, v140
	v_and_b32_e32 v139, 0xffff0000, v144
	v_pk_add_f32 v[138:139], v[138:139], v[210:211] neg_lo:[0,1] neg_hi:[0,1]
	ds_write_b32 v178, v85 offset:9792
	v_pk_mul_f32 v[138:139], v[208:209], v[138:139]
	s_nop 0
	v_pk_fma_f32 v[138:139], v[82:83], v[138:139], v[86:87] op_sel:[1,0,1]
	s_nop 0
	v_cvt_pk_bf16_f32 v85, v138, v139
	v_lshlrev_b32_e32 v138, 16, v141
	v_lshlrev_b32_e32 v139, 16, v145
	v_pk_add_f32 v[138:139], v[138:139], v[210:211] neg_lo:[0,1] neg_hi:[0,1]
	ds_write_b32 v178, v85 offset:11968
	v_pk_mul_f32 v[138:139], v[208:209], v[138:139]
	s_nop 0
	v_pk_fma_f32 v[138:139], v[84:85], v[138:139], v[88:89] op_sel_hi:[0,1,0]
	v_cvt_pk_bf16_f32 v85, v138, v139
	v_and_b32_e32 v138, 0xffff0000, v141
	v_and_b32_e32 v139, 0xffff0000, v145
	v_pk_add_f32 v[138:139], v[138:139], v[210:211] neg_lo:[0,1] neg_hi:[0,1]
	ds_write_b32 v178, v85 offset:14144
	v_pk_mul_f32 v[138:139], v[208:209], v[138:139]
	s_nop 0
	v_pk_fma_f32 v[138:139], v[164:165], v[138:139], v[166:167] op_sel_hi:[0,1,0]
	v_cvt_pk_bf16_f32 v85, v138, v139
	ds_write_b32 v178, v85 offset:16320
	ds_read_b128 v[138:141], v182 offset:384
	s_waitcnt lgkmcnt(0)
; __device__ __forceinline__ unsigned cvt_pk_bf16(float lo, float hi) { unsigned r; asm volatile("v_cvt_pk_bf16_f32 %0, %1, %2" : "=v"(r) : "v"(lo), "v"(hi)); return r; }
; __device__ __forceinline__ float bf_lo(unsigned w) { return __uint_as_float(w << 16); }
; __device__ __forceinline__ float bf_hi(unsigned w) { return __uint_as_float(w & 0xffff0000u); }
; #define LAS __attribute__((address_space(3)))
; __device__ __forceinline__ void sgu_unit(LAS unsigned char* lds, bf16* U, const bf16* VS, const float* SGS, const float* lnw, const float* lnb, const v4u* WF, const float* bsl, int unit, int tid) {
;     ...
;         LAS unsigned char* wbase = vt + c8 * SGU_VP + rp * 4;
; #pragma unroll
;         for (int i = 0; i < 8; ++i) {
;             const f32x4 st4 = *(const LAS f32x4*)(stat + 4 * (rp + 8 * i));
;             const v4u w0 = sl[i][0], w1 = sl[i][1];
;             const unsigned A0[4] = {w0.x, w0.y, w0.z, w0.w}, A1[4] = {w1.x, w1.y, w1.z, w1.w};
; #pragma unroll
;             for (int e = 0; e < 8; ++e) { typedef float f32x2p __attribute__((ext_vector_type(2)));
;                 f32x2p v; v.x = (e & 1) ? bf_hi(A0[e >> 1]) : bf_lo(A0[e >> 1]); v.y = (e & 1) ? bf_hi(A1[e >> 1]) : bf_lo(A1[e >> 1]);
;                 const f32x2p mn = {st4.x, st4.z}, rs = {st4.y, st4.w};
;                 const f32x2p o = ((v - mn) * rs) * lw[e] + lb[e];
;                 *(LAS unsigned*)(wbase + e * 8 * SGU_VP + i * 32) = cvt_pk_bf16(o.x, o.y); }
;         }
;     }
	v_mov_b32_e32 v142, v138
	v_mov_b32_e32 v143, v140
	v_mov_b32_e32 v140, v139
	s_waitcnt vmcnt(9)
	v_lshlrev_b32_e32 v138, 16, v130
	s_waitcnt vmcnt(8)
	v_lshlrev_b32_e32 v139, 16, v134
	v_pk_add_f32 v[138:139], v[138:139], v[142:143] neg_lo:[0,1] neg_hi:[0,1]
	s_nop 0
	v_pk_mul_f32 v[138:139], v[140:141], v[138:139]
	s_nop 0
	v_pk_fma_f32 v[138:139], v[102:103], v[138:139], v[98:99] op_sel_hi:[0,1,0]
	v_cvt_pk_bf16_f32 v85, v138, v139
	v_and_b32_e32 v138, 0xffff0000, v130
	v_and_b32_e32 v139, 0xffff0000, v134
	v_pk_add_f32 v[138:139], v[138:139], v[142:143] neg_lo:[0,1] neg_hi:[0,1]
	ds_write_b32 v178, v85 offset:1120
	v_pk_mul_f32 v[138:139], v[140:141], v[138:139]
	v_and_b32_e32 v130, 0xffff0000, v131
	v_pk_fma_f32 v[138:139], v[102:103], v[138:139], v[98:99] op_sel:[1,0,1]
	s_nop 0
	v_cvt_pk_bf16_f32 v85, v138, v139
	v_lshlrev_b32_e32 v138, 16, v131
	v_lshlrev_b32_e32 v139, 16, v135
	v_and_b32_e32 v131, 0xffff0000, v135
	v_pk_add_f32 v[138:139], v[138:139], v[142:143] neg_lo:[0,1] neg_hi:[0,1]
	v_pk_add_f32 v[130:131], v[130:131], v[142:143] neg_lo:[0,1] neg_hi:[0,1]
	v_pk_mul_f32 v[138:139], v[140:141], v[138:139]
	v_pk_mul_f32 v[130:131], v[140:141], v[130:131]
	ds_write_b32 v178, v85 offset:3296
	v_pk_fma_f32 v[138:139], v[104:105], v[138:139], v[100:101] op_sel_hi:[0,1,0]
	v_cvt_pk_bf16_f32 v85, v138, v139
	v_pk_fma_f32 v[130:131], v[160:161], v[130:131], v[162:163] op_sel_hi:[0,1,0]
	ds_write_b32 v178, v85 offset:5472
	v_cvt_pk_bf16_f32 v85, v130, v131
	v_lshlrev_b32_e32 v130, 16, v132
	v_lshlrev_b32_e32 v131, 16, v136
	v_pk_add_f32 v[130:131], v[130:131], v[142:143] neg_lo:[0,1] neg_hi:[0,1]
	ds_write_b32 v178, v85 offset:7648
	v_pk_mul_f32 v[130:131], v[140:141], v[130:131]
	s_nop 0
	v_pk_fma_f32 v[130:131], v[82:83], v[130:131], v[86:87] op_sel_hi:[0,1,0]
	v_cvt_pk_bf16_f32 v85, v130, v131
	v_and_b32_e32 v130, 0xffff0000, v132
	v_and_b32_e32 v131, 0xffff0000, v136
	v_pk_add_f32 v[130:131], v[130:131], v[142:143] neg_lo:[0,1] neg_hi:[0,1]
	ds_write_b32 v178, v85 offset:9824
	v_pk_mul_f32 v[130:131], v[140:141], v[130:131]
	s_nop 0
	v_pk_fma_f32 v[130:131], v[82:83], v[130:131], v[86:87] op_sel:[1,0,1]
	s_nop 0
	v_cvt_pk_bf16_f32 v85, v130, v131
	v_lshlrev_b32_e32 v130, 16, v133
	v_lshlrev_b32_e32 v131, 16, v137
	v_pk_add_f32 v[130:131], v[130:131], v[142:143] neg_lo:[0,1] neg_hi:[0,1]
	ds_write_b32 v178, v85 offset:12000
	v_pk_mul_f32 v[130:131], v[140:141], v[130:131]
	s_nop 0
	v_pk_fma_f32 v[130:131], v[84:85], v[130:131], v[88:89] op_sel_hi:[0,1,0]
	v_cvt_pk_bf16_f32 v85, v130, v131
	v_and_b32_e32 v130, 0xffff0000, v133
	v_and_b32_e32 v131, 0xffff0000, v137
	v_pk_add_f32 v[130:131], v[130:131], v[142:143] neg_lo:[0,1] neg_hi:[0,1]
	ds_write_b32 v178, v85 offset:14176
	v_pk_mul_f32 v[130:131], v[140:141], v[130:131]
	s_nop 0
	v_pk_fma_f32 v[130:131], v[164:165], v[130:131], v[166:167] op_sel_hi:[0,1,0]
	v_cvt_pk_bf16_f32 v85, v130, v131
	ds_write_b32 v178, v85 offset:16352
	ds_read_b128 v[130:133], v182 offset:512
	s_waitcnt lgkmcnt(0)
	v_mov_b32_e32 v134, v130
	v_mov_b32_e32 v135, v132
	v_mov_b32_e32 v132, v131
	s_waitcnt vmcnt(7)
	v_lshlrev_b32_e32 v130, 16, v122
	s_waitcnt vmcnt(6)
	v_lshlrev_b32_e32 v131, 16, v126
	v_pk_add_f32 v[130:131], v[130:131], v[134:135] neg_lo:[0,1] neg_hi:[0,1]
	s_nop 0
	v_pk_mul_f32 v[130:131], v[132:133], v[130:131]
	s_nop 0
	v_pk_fma_f32 v[130:131], v[102:103], v[130:131], v[98:99] op_sel_hi:[0,1,0]
	v_cvt_pk_bf16_f32 v85, v130, v131
	v_and_b32_e32 v130, 0xffff0000, v122
	v_and_b32_e32 v131, 0xffff0000, v126
	v_pk_add_f32 v[130:131], v[130:131], v[134:135] neg_lo:[0,1] neg_hi:[0,1]
	ds_write_b32 v178, v85 offset:1152
	v_pk_mul_f32 v[130:131], v[132:133], v[130:131]
	v_and_b32_e32 v122, 0xffff0000, v123
	v_pk_fma_f32 v[130:131], v[102:103], v[130:131], v[98:99] op_sel:[1,0,1]
	s_nop 0
	v_cvt_pk_bf16_f32 v85, v130, v131
	v_lshlrev_b32_e32 v130, 16, v123
	v_lshlrev_b32_e32 v131, 16, v127
	v_and_b32_e32 v123, 0xffff0000, v127
	v_pk_add_f32 v[130:131], v[130:131], v[134:135] neg_lo:[0,1] neg_hi:[0,1]
	v_pk_add_f32 v[122:123], v[122:123], v[134:135] neg_lo:[0,1] neg_hi:[0,1]
	v_pk_mul_f32 v[130:131], v[132:133], v[130:131]
	v_pk_mul_f32 v[122:123], v[132:133], v[122:123]
	ds_write_b32 v178, v85 offset:3328
	v_pk_fma_f32 v[130:131], v[104:105], v[130:131], v[100:101] op_sel_hi:[0,1,0]
	v_cvt_pk_bf16_f32 v85, v130, v131
	v_pk_fma_f32 v[122:123], v[160:161], v[122:123], v[162:163] op_sel_hi:[0,1,0]
	ds_write_b32 v178, v85 offset:5504
	v_cvt_pk_bf16_f32 v85, v122, v123
	v_lshlrev_b32_e32 v122, 16, v124
	v_lshlrev_b32_e32 v123, 16, v128
	v_pk_add_f32 v[122:123], v[122:123], v[134:135] neg_lo:[0,1] neg_hi:[0,1]
	ds_write_b32 v178, v85 offset:7680
	v_pk_mul_f32 v[122:123], v[132:133], v[122:123]
	s_nop 0
	v_pk_fma_f32 v[122:123], v[82:83], v[122:123], v[86:87] op_sel_hi:[0,1,0]
	v_cvt_pk_bf16_f32 v85, v122, v123
	v_and_b32_e32 v122, 0xffff0000, v124
	v_and_b32_e32 v123, 0xffff0000, v128
	v_pk_add_f32 v[122:123], v[122:123], v[134:135] neg_lo:[0,1] neg_hi:[0,1]
	ds_write_b32 v178, v85 offset:9856
	v_pk_mul_f32 v[122:123], v[132:133], v[122:123]
	s_nop 0
	v_pk_fma_f32 v[122:123], v[82:83], v[122:123], v[86:87] op_sel:[1,0,1]
	s_nop 0
	v_cvt_pk_bf16_f32 v85, v122, v123
	v_lshlrev_b32_e32 v122, 16, v125
	v_lshlrev_b32_e32 v123, 16, v129
	v_pk_add_f32 v[122:123], v[122:123], v[134:135] neg_lo:[0,1] neg_hi:[0,1]
	ds_write_b32 v178, v85 offset:12032
	v_pk_mul_f32 v[122:123], v[132:133], v[122:123]
	s_nop 0
	v_pk_fma_f32 v[122:123], v[84:85], v[122:123], v[88:89] op_sel_hi:[0,1,0]
	v_cvt_pk_bf16_f32 v85, v122, v123
	v_and_b32_e32 v122, 0xffff0000, v125
	v_and_b32_e32 v123, 0xffff0000, v129
	v_pk_add_f32 v[122:123], v[122:123], v[134:135] neg_lo:[0,1] neg_hi:[0,1]
	ds_write_b32 v178, v85 offset:14208
	v_pk_mul_f32 v[122:123], v[132:133], v[122:123]
	s_nop 0
	v_pk_fma_f32 v[122:123], v[164:165], v[122:123], v[166:167] op_sel_hi:[0,1,0]
	v_cvt_pk_bf16_f32 v85, v122, v123
	ds_write_b32 v178, v85 offset:16384
	ds_read_b128 v[122:125], v182 offset:640
	s_waitcnt lgkmcnt(0)
; __device__ __forceinline__ unsigned cvt_pk_bf16(float lo, float hi) { unsigned r; asm volatile("v_cvt_pk_bf16_f32 %0, %1, %2" : "=v"(r) : "v"(lo), "v"(hi)); return r; }
; __device__ __forceinline__ float bf_lo(unsigned w) { return __uint_as_float(w << 16); }
; __device__ __forceinline__ float bf_hi(unsigned w) { return __uint_as_float(w & 0xffff0000u); }
; #define LAS __attribute__((address_space(3)))
; __device__ __forceinline__ void sgu_unit(LAS unsigned char* lds, bf16* U, const bf16* VS, const float* SGS, const float* lnw, const float* lnb, const v4u* WF, const float* bsl, int unit, int tid) {
;     ...
;         LAS unsigned char* wbase = vt + c8 * SGU_VP + rp * 4;
; #pragma unroll
;         for (int i = 0; i < 8; ++i) {
;             const f32x4 st4 = *(const LAS f32x4*)(stat + 4 * (rp + 8 * i));
;             const v4u w0 = sl[i][0], w1 = sl[i][1];
;             const unsigned A0[4] = {w0.x, w0.y, w0.z, w0.w}, A1[4] = {w1.x, w1.y, w1.z, w1.w};
; #pragma unroll
;             for (int e = 0; e < 8; ++e) { typedef float f32x2p __attribute__((ext_vector_type(2)));
;                 f32x2p v; v.x = (e & 1) ? bf_hi(A0[e >> 1]) : bf_lo(A0[e >> 1]); v.y = (e & 1) ? bf_hi(A1[e >> 1]) : bf_lo(A1[e >> 1]);
;                 const f32x2p mn = {st4.x, st4.z}, rs = {st4.y, st4.w};
;                 const f32x2p o = ((v - mn) * rs) * lw[e] + lb[e];
;                 *(LAS unsigned*)(wbase + e * 8 * SGU_VP + i * 32) = cvt_pk_bf16(o.x, o.y); }
;         }
;     }
	v_mov_b32_e32 v126, v122
	v_mov_b32_e32 v127, v124
	v_mov_b32_e32 v124, v123
	s_waitcnt vmcnt(5)
	v_lshlrev_b32_e32 v122, 16, v114
	s_waitcnt vmcnt(4)
	v_lshlrev_b32_e32 v123, 16, v118
	v_pk_add_f32 v[122:123], v[122:123], v[126:127] neg_lo:[0,1] neg_hi:[0,1]
	s_nop 0
	v_pk_mul_f32 v[122:123], v[124:125], v[122:123]
	s_nop 0
	v_pk_fma_f32 v[122:123], v[102:103], v[122:123], v[98:99] op_sel_hi:[0,1,0]
	v_cvt_pk_bf16_f32 v85, v122, v123
	v_and_b32_e32 v122, 0xffff0000, v114
	v_and_b32_e32 v123, 0xffff0000, v118
	v_pk_add_f32 v[122:123], v[122:123], v[126:127] neg_lo:[0,1] neg_hi:[0,1]
	ds_write_b32 v178, v85 offset:1184
	v_pk_mul_f32 v[122:123], v[124:125], v[122:123]
	v_and_b32_e32 v114, 0xffff0000, v115
	v_pk_fma_f32 v[122:123], v[102:103], v[122:123], v[98:99] op_sel:[1,0,1]
	s_nop 0
	v_cvt_pk_bf16_f32 v85, v122, v123
	v_lshlrev_b32_e32 v122, 16, v115
	v_lshlrev_b32_e32 v123, 16, v119
	v_and_b32_e32 v115, 0xffff0000, v119
	v_pk_add_f32 v[122:123], v[122:123], v[126:127] neg_lo:[0,1] neg_hi:[0,1]
	v_pk_add_f32 v[114:115], v[114:115], v[126:127] neg_lo:[0,1] neg_hi:[0,1]
	v_pk_mul_f32 v[122:123], v[124:125], v[122:123]
	v_pk_mul_f32 v[114:115], v[124:125], v[114:115]
	ds_write_b32 v178, v85 offset:3360
	v_pk_fma_f32 v[122:123], v[104:105], v[122:123], v[100:101] op_sel_hi:[0,1,0]
	v_cvt_pk_bf16_f32 v85, v122, v123
	v_pk_fma_f32 v[114:115], v[160:161], v[114:115], v[162:163] op_sel_hi:[0,1,0]
	ds_write_b32 v178, v85 offset:5536
	v_cvt_pk_bf16_f32 v85, v114, v115
	v_lshlrev_b32_e32 v114, 16, v116
	v_lshlrev_b32_e32 v115, 16, v120
	v_pk_add_f32 v[114:115], v[114:115], v[126:127] neg_lo:[0,1] neg_hi:[0,1]
	ds_write_b32 v178, v85 offset:7712
	v_pk_mul_f32 v[114:115], v[124:125], v[114:115]
	s_nop 0
	v_pk_fma_f32 v[114:115], v[82:83], v[114:115], v[86:87] op_sel_hi:[0,1,0]
	v_cvt_pk_bf16_f32 v85, v114, v115
	v_and_b32_e32 v114, 0xffff0000, v116
	v_and_b32_e32 v115, 0xffff0000, v120
	v_pk_add_f32 v[114:115], v[114:115], v[126:127] neg_lo:[0,1] neg_hi:[0,1]
	ds_write_b32 v178, v85 offset:9888
	v_pk_mul_f32 v[114:115], v[124:125], v[114:115]
	s_nop 0
	v_pk_fma_f32 v[114:115], v[82:83], v[114:115], v[86:87] op_sel:[1,0,1]
	s_nop 0
	v_cvt_pk_bf16_f32 v85, v114, v115
	v_lshlrev_b32_e32 v114, 16, v117
	v_lshlrev_b32_e32 v115, 16, v121
	v_pk_add_f32 v[114:115], v[114:115], v[126:127] neg_lo:[0,1] neg_hi:[0,1]
	ds_write_b32 v178, v85 offset:12064
	v_pk_mul_f32 v[114:115], v[124:125], v[114:115]
	s_nop 0
	v_pk_fma_f32 v[114:115], v[84:85], v[114:115], v[88:89] op_sel_hi:[0,1,0]
	v_cvt_pk_bf16_f32 v85, v114, v115
	v_and_b32_e32 v114, 0xffff0000, v117
	v_and_b32_e32 v115, 0xffff0000, v121
	v_pk_add_f32 v[114:115], v[114:115], v[126:127] neg_lo:[0,1] neg_hi:[0,1]
	ds_write_b32 v178, v85 offset:14240
	v_pk_mul_f32 v[114:115], v[124:125], v[114:115]
	s_nop 0
	v_pk_fma_f32 v[114:115], v[164:165], v[114:115], v[166:167] op_sel_hi:[0,1,0]
	v_cvt_pk_bf16_f32 v85, v114, v115
	ds_write_b32 v178, v85 offset:16416
	ds_read_b128 v[114:117], v182 offset:768
	s_waitcnt lgkmcnt(0)
	v_mov_b32_e32 v118, v114
	v_mov_b32_e32 v119, v116
	v_mov_b32_e32 v116, v115
	s_waitcnt vmcnt(3)
	v_lshlrev_b32_e32 v114, 16, v106
	s_waitcnt vmcnt(2)
	v_lshlrev_b32_e32 v115, 16, v110
	v_pk_add_f32 v[114:115], v[114:115], v[118:119] neg_lo:[0,1] neg_hi:[0,1]
	s_nop 0
	v_pk_mul_f32 v[114:115], v[116:117], v[114:115]
	s_nop 0
	v_pk_fma_f32 v[114:115], v[102:103], v[114:115], v[98:99] op_sel_hi:[0,1,0]
	v_cvt_pk_bf16_f32 v85, v114, v115
	v_and_b32_e32 v114, 0xffff0000, v106
	v_and_b32_e32 v115, 0xffff0000, v110
	v_pk_add_f32 v[114:115], v[114:115], v[118:119] neg_lo:[0,1] neg_hi:[0,1]
	ds_write_b32 v178, v85 offset:1216
	v_pk_mul_f32 v[114:115], v[116:117], v[114:115]
	v_and_b32_e32 v106, 0xffff0000, v107
	v_pk_fma_f32 v[114:115], v[102:103], v[114:115], v[98:99] op_sel:[1,0,1]
	s_nop 0
	v_cvt_pk_bf16_f32 v85, v114, v115
	v_lshlrev_b32_e32 v114, 16, v107
	v_lshlrev_b32_e32 v115, 16, v111
	v_and_b32_e32 v107, 0xffff0000, v111
	v_pk_add_f32 v[114:115], v[114:115], v[118:119] neg_lo:[0,1] neg_hi:[0,1]
	v_pk_add_f32 v[106:107], v[106:107], v[118:119] neg_lo:[0,1] neg_hi:[0,1]
	v_pk_mul_f32 v[114:115], v[116:117], v[114:115]
	v_pk_mul_f32 v[106:107], v[116:117], v[106:107]
	ds_write_b32 v178, v85 offset:3392
	v_pk_fma_f32 v[114:115], v[104:105], v[114:115], v[100:101] op_sel_hi:[0,1,0]
	v_cvt_pk_bf16_f32 v85, v114, v115
	v_pk_fma_f32 v[106:107], v[160:161], v[106:107], v[162:163] op_sel_hi:[0,1,0]
	ds_write_b32 v178, v85 offset:5568
	v_cvt_pk_bf16_f32 v85, v106, v107
	v_lshlrev_b32_e32 v106, 16, v108
	v_lshlrev_b32_e32 v107, 16, v112
	v_pk_add_f32 v[106:107], v[106:107], v[118:119] neg_lo:[0,1] neg_hi:[0,1]
	ds_write_b32 v178, v85 offset:7744
	v_pk_mul_f32 v[106:107], v[116:117], v[106:107]
	s_nop 0
	v_pk_fma_f32 v[106:107], v[82:83], v[106:107], v[86:87] op_sel_hi:[0,1,0]
	v_cvt_pk_bf16_f32 v85, v106, v107
	v_and_b32_e32 v106, 0xffff0000, v108
	v_and_b32_e32 v107, 0xffff0000, v112
	v_pk_add_f32 v[106:107], v[106:107], v[118:119] neg_lo:[0,1] neg_hi:[0,1]
	ds_write_b32 v178, v85 offset:9920
	v_pk_mul_f32 v[106:107], v[116:117], v[106:107]
	s_nop 0
	v_pk_fma_f32 v[106:107], v[82:83], v[106:107], v[86:87] op_sel:[1,0,1]
	s_nop 0
	v_cvt_pk_bf16_f32 v85, v106, v107
	v_lshlrev_b32_e32 v106, 16, v109
	v_lshlrev_b32_e32 v107, 16, v113
	v_pk_add_f32 v[106:107], v[106:107], v[118:119] neg_lo:[0,1] neg_hi:[0,1]
	ds_write_b32 v178, v85 offset:12096
	v_pk_mul_f32 v[106:107], v[116:117], v[106:107]
	s_nop 0
	v_pk_fma_f32 v[106:107], v[84:85], v[106:107], v[88:89] op_sel_hi:[0,1,0]
	v_cvt_pk_bf16_f32 v85, v106, v107
	v_and_b32_e32 v106, 0xffff0000, v109
	v_and_b32_e32 v107, 0xffff0000, v113
	v_pk_add_f32 v[106:107], v[106:107], v[118:119] neg_lo:[0,1] neg_hi:[0,1]
	ds_write_b32 v178, v85 offset:14272
	v_pk_mul_f32 v[106:107], v[116:117], v[106:107]
	s_nop 0
	v_pk_fma_f32 v[106:107], v[164:165], v[106:107], v[166:167] op_sel_hi:[0,1,0]
	v_cvt_pk_bf16_f32 v85, v106, v107
	ds_write_b32 v178, v85 offset:16448
	ds_read_b128 v[106:109], v182 offset:896
	s_waitcnt lgkmcnt(0)
; __device__ __forceinline__ unsigned cvt_pk_bf16(float lo, float hi) { unsigned r; asm volatile("v_cvt_pk_bf16_f32 %0, %1, %2" : "=v"(r) : "v"(lo), "v"(hi)); return r; }
; __device__ __forceinline__ float bf_lo(unsigned w) { return __uint_as_float(w << 16); }
; __device__ __forceinline__ void sgu_unit(LAS unsigned char* lds, bf16* U, const bf16* VS, const float* SGS, const float* lnw, const float* lnb, const v4u* WF, const float* bsl, int unit, int tid) {
;     ...
;         LAS unsigned char* wbase = vt + c8 * SGU_VP + rp * 4;
; #pragma unroll
;         for (int i = 0; i < 8; ++i) {
;             const f32x4 st4 = *(const LAS f32x4*)(stat + 4 * (rp + 8 * i));
;             const v4u w0 = sl[i][0], w1 = sl[i][1];
;             const unsigned A0[4] = {w0.x, w0.y, w0.z, w0.w}, A1[4] = {w1.x, w1.y, w1.z, w1.w};
; #pragma unroll
;             for (int e = 0; e < 8; ++e) { typedef float f32x2p __attribute__((ext_vector_type(2)));
;                 f32x2p v; v.x = (e & 1) ? bf_hi(A0[e >> 1]) : bf_lo(A0[e >> 1]); v.y = (e & 1) ? bf_hi(A1[e >> 1]) : bf_lo(A1[e >> 1]);
;                 const f32x2p mn = {st4.x, st4.z}, rs = {st4.y, st4.w};
;                 const f32x2p o = ((v - mn) * rs) * lw[e] + lb[e];
;                 *(LAS unsigned*)(wbase + e * 8 * SGU_VP + i * 32) = cvt_pk_bf16(o.x, o.y); }
;         }
;     }
;     v2u uu[8][4];
; #pragma unroll
;     for (int mt = 0; mt < 8; ++mt)
; #pragma unroll
;         for (int nt = 0; nt < 4; ++nt) uu[mt][nt] = *(const v2u*)(U + (size_t)(r0 + 16 * mt + fr) * 1024 + colbase + 16 * nt + 4 * fq);
;     LDS_WAIT(); asm volatile("" ::: "memory");
;     {
;         int q = 0;
; #pragma unroll
;         for (int mt = 0; mt < 8; ++mt) {
;             const int t = 16 * mt + fr;
;             f32x4 acc[4];
; #pragma unroll
;             for (int nt = 0; nt < 4; ++nt) acc[nt] = (f32x4){0.f, 0.f, 0.f, 0.f};
; #pragma unroll
;             for (int ks = 0; ks <= (mt >> 1); ++ks) {
;                 const int sb = 32 * ks + 8 * fq; const bf16x8_t wf = __builtin_bit_cast(bf16x8_t, wfr[q++]);
; #pragma unroll
;                 for (int nt = 0; nt < 4; ++nt) { const bf16x8_t vf = *(const LAS bf16x8_t*)(vt + ((fr >> 3) + 8 * (fr & 7) + 2 * nt) * SGU_VP + sb * 2);
;                     acc[nt] = __builtin_amdgcn_mfma_f32_16x16x32_bf16(vf, wf, acc[nt], 0, 0, 0); }
;             }
;             const float bb = bbv[mt];
	v_mov_b32_e32 v110, v106
	v_mov_b32_e32 v111, v108
	v_mov_b32_e32 v108, v107
	s_waitcnt vmcnt(1)
	v_lshlrev_b32_e32 v106, 16, v90
	s_waitcnt vmcnt(0)
	v_lshlrev_b32_e32 v107, 16, v94
	v_pk_add_f32 v[106:107], v[106:107], v[110:111] neg_lo:[0,1] neg_hi:[0,1]
	s_nop 0
	v_pk_mul_f32 v[106:107], v[108:109], v[106:107]
	s_nop 0
	v_pk_fma_f32 v[106:107], v[102:103], v[106:107], v[98:99] op_sel_hi:[0,1,0]
	v_cvt_pk_bf16_f32 v85, v106, v107
	v_and_b32_e32 v106, 0xffff0000, v90
	v_and_b32_e32 v107, 0xffff0000, v94
	v_pk_add_f32 v[106:107], v[106:107], v[110:111] neg_lo:[0,1] neg_hi:[0,1]
	ds_write_b32 v178, v85 offset:1248
	v_pk_mul_f32 v[106:107], v[108:109], v[106:107]
	v_and_b32_e32 v90, 0xffff0000, v91
	v_pk_fma_f32 v[98:99], v[102:103], v[106:107], v[98:99] op_sel:[1,0,1]
	s_nop 0
	v_cvt_pk_bf16_f32 v85, v98, v99
	v_lshlrev_b32_e32 v98, 16, v91
	v_lshlrev_b32_e32 v99, 16, v95
	v_and_b32_e32 v91, 0xffff0000, v95
	v_pk_add_f32 v[98:99], v[98:99], v[110:111] neg_lo:[0,1] neg_hi:[0,1]
	v_pk_add_f32 v[90:91], v[90:91], v[110:111] neg_lo:[0,1] neg_hi:[0,1]
	v_pk_mul_f32 v[98:99], v[108:109], v[98:99]
	v_pk_mul_f32 v[90:91], v[108:109], v[90:91]
	ds_write_b32 v178, v85 offset:3424
	v_pk_fma_f32 v[98:99], v[104:105], v[98:99], v[100:101] op_sel_hi:[0,1,0]
	v_cvt_pk_bf16_f32 v85, v98, v99
	v_pk_fma_f32 v[90:91], v[160:161], v[90:91], v[162:163] op_sel_hi:[0,1,0]
	ds_write_b32 v178, v85 offset:5600
	v_cvt_pk_bf16_f32 v85, v90, v91
	v_lshlrev_b32_e32 v90, 16, v92
	v_lshlrev_b32_e32 v91, 16, v96
	v_pk_add_f32 v[90:91], v[90:91], v[110:111] neg_lo:[0,1] neg_hi:[0,1]
	ds_write_b32 v178, v85 offset:7776
	v_pk_mul_f32 v[90:91], v[108:109], v[90:91]
	s_nop 0
	v_pk_fma_f32 v[90:91], v[82:83], v[90:91], v[86:87] op_sel_hi:[0,1,0]
	v_cvt_pk_bf16_f32 v85, v90, v91
	v_and_b32_e32 v90, 0xffff0000, v92
	v_and_b32_e32 v91, 0xffff0000, v96
	v_pk_add_f32 v[90:91], v[90:91], v[110:111] neg_lo:[0,1] neg_hi:[0,1]
	ds_write_b32 v178, v85 offset:9952
	v_pk_mul_f32 v[90:91], v[108:109], v[90:91]
	s_nop 0
	v_pk_fma_f32 v[82:83], v[82:83], v[90:91], v[86:87] op_sel:[1,0,1]
	s_nop 0
	v_cvt_pk_bf16_f32 v82, v82, v83
	ds_write_b32 v178, v82 offset:12128
	v_lshlrev_b32_e32 v82, 16, v93
	v_lshlrev_b32_e32 v83, 16, v97
	v_pk_add_f32 v[82:83], v[82:83], v[110:111] neg_lo:[0,1] neg_hi:[0,1]
	s_nop 0
	v_pk_mul_f32 v[82:83], v[108:109], v[82:83]
	s_nop 0
	v_pk_fma_f32 v[82:83], v[84:85], v[82:83], v[88:89] op_sel_hi:[0,1,0]
	v_cvt_pk_bf16_f32 v82, v82, v83
	ds_write_b32 v178, v82 offset:14304
	v_and_b32_e32 v82, 0xffff0000, v93
	v_and_b32_e32 v83, 0xffff0000, v97
	v_pk_add_f32 v[82:83], v[82:83], v[110:111] neg_lo:[0,1] neg_hi:[0,1]
	v_or_b32_e32 v84, s16, v163
	v_pk_mul_f32 v[82:83], v[108:109], v[82:83]
	v_lshlrev_b32_e32 v84, 11, v84
	v_pk_fma_f32 v[82:83], v[164:165], v[82:83], v[166:167] op_sel_hi:[0,1,0]
	v_cvt_pk_bf16_f32 v82, v82, v83
	ds_write_b32 v178, v82 offset:16480
	v_lshl_add_u64 v[82:83], v[158:159], 1, v[150:151]
	v_mov_b32_e32 v85, v147
	v_lshl_add_u64 v[144:145], v[82:83], 0, v[84:85]
	global_load_dwordx2 v[158:159], v[144:145], off
	global_load_dwordx2 v[218:219], v[144:145], off offset:32
	global_load_dwordx2 v[220:221], v[144:145], off offset:64
	global_load_dwordx2 v[222:223], v[144:145], off offset:96
	v_add_co_u32_e32 v226, vcc, s40, v144
	v_addc_co_u32_e32 v227, vcc, 0, v145, vcc
	global_load_dwordx2 v[224:225], v[226:227], off
	global_load_dwordx2 v[228:229], v[226:227], off offset:32
	global_load_dwordx2 v[230:231], v[226:227], off offset:64
	global_load_dwordx2 v[232:233], v[226:227], off offset:96
	v_add_co_u32_e32 v130, vcc, s41, v144
	s_nop 0
	v_addc_co_u32_e32 v131, vcc, 0, v145, vcc
	v_add_co_u32_e32 v120, vcc, s44, v144
	global_load_dwordx2 v[234:235], v[130:131], off
	global_load_dwordx2 v[138:139], v[130:131], off offset:32
	global_load_dwordx2 v[136:137], v[130:131], off offset:64
	global_load_dwordx2 v[134:135], v[130:131], off offset:96
	v_addc_co_u32_e32 v121, vcc, 0, v145, vcc
	v_add_co_u32_e32 v110, vcc, s45, v144
	global_load_dwordx2 v[132:133], v[120:121], off
	global_load_dwordx2 v[128:129], v[120:121], off offset:32
	global_load_dwordx2 v[126:127], v[120:121], off offset:64
	global_load_dwordx2 v[124:125], v[120:121], off offset:96
	v_addc_co_u32_e32 v111, vcc, 0, v145, vcc
	v_add_co_u32_e32 v100, vcc, s46, v144
	global_load_dwordx2 v[122:123], v[110:111], off
	global_load_dwordx2 v[118:119], v[110:111], off offset:32
	global_load_dwordx2 v[116:117], v[110:111], off offset:64
	global_load_dwordx2 v[114:115], v[110:111], off offset:96
	v_addc_co_u32_e32 v101, vcc, 0, v145, vcc
	v_add_co_u32_e32 v90, vcc, s47, v144
	global_load_dwordx2 v[112:113], v[100:101], off
	global_load_dwordx2 v[108:109], v[100:101], off offset:32
	global_load_dwordx2 v[106:107], v[100:101], off offset:64
	global_load_dwordx2 v[104:105], v[100:101], off offset:96
	v_addc_co_u32_e32 v91, vcc, 0, v145, vcc
	v_add_co_u32_e32 v82, vcc, s59, v144
	global_load_dwordx2 v[102:103], v[90:91], off
	global_load_dwordx2 v[98:99], v[90:91], off offset:32
	global_load_dwordx2 v[96:97], v[90:91], off offset:64
	global_load_dwordx2 v[94:95], v[90:91], off offset:96
	v_addc_co_u32_e32 v83, vcc, 0, v145, vcc
	global_load_dwordx2 v[92:93], v[82:83], off
	global_load_dwordx2 v[88:89], v[82:83], off offset:32
	global_load_dwordx2 v[86:87], v[82:83], off offset:64
	global_load_dwordx2 v[84:85], v[82:83], off offset:96
	s_waitcnt lgkmcnt(0)
	ds_read_b128 v[140:143], v183 offset:1024
	ds_read_b128 v[206:209], v183 offset:1568
	s_waitcnt lgkmcnt(1)
	v_mfma_f32_16x16x32_bf16 v[140:143], v[140:143], v[78:81], 0
	ds_read_b128 v[210:213], v183 offset:2112
	ds_read_b128 v[214:217], v183 offset:2656
	s_nop 5
	v_add_f32_e32 v140, v198, v140
	v_add_f32_e32 v141, v198, v141
	s_waitcnt lgkmcnt(2)
; __device__ __forceinline__ unsigned cvt_pk_bf16(float lo, float hi) { unsigned r; asm volatile("v_cvt_pk_bf16_f32 %0, %1, %2" : "=v"(r) : "v"(lo), "v"(hi)); return r; }
; __device__ __forceinline__ float bf_lo(unsigned w) { return __uint_as_float(w << 16); }
; __device__ __forceinline__ float bf_hi(unsigned w) { return __uint_as_float(w & 0xffff0000u); }
; #define LAS __attribute__((address_space(3)))
; __device__ __forceinline__ void sgu_unit(LAS unsigned char* lds, bf16* U, const bf16* VS, const float* SGS, const float* lnw, const float* lnb, const v4u* WF, const float* bsl, int unit, int tid) {
;     ...
;         for (int mt = 0; mt < 8; ++mt) {
;             const int t = 16 * mt + fr;
;             f32x4 acc[4];
; #pragma unroll
;             for (int nt = 0; nt < 4; ++nt) acc[nt] = (f32x4){0.f, 0.f, 0.f, 0.f};
; #pragma unroll
;             for (int ks = 0; ks <= (mt >> 1); ++ks) {
;                 const int sb = 32 * ks + 8 * fq; const bf16x8_t wf = __builtin_bit_cast(bf16x8_t, wfr[q++]);
; #pragma unroll
;                 for (int nt = 0; nt < 4; ++nt) { const bf16x8_t vf = *(const LAS bf16x8_t*)(vt + ((fr >> 3) + 8 * (fr & 7) + 2 * nt) * SGU_VP + sb * 2);
;                     acc[nt] = __builtin_amdgcn_mfma_f32_16x16x32_bf16(vf, wf, acc[nt], 0, 0, 0); }
;             }
;             const float bb = bbv[mt];
; #pragma unroll
;             for (int nt = 0; nt < 4; ++nt) { const v2u u2 = uu[mt][nt]; v2u w; w.x = cvt_pk_bf16(bf_lo(u2.x) * (acc[nt][0] + bb), bf_hi(u2.x) * (acc[nt][1] + bb)); w.y = cvt_pk_bf16(bf_lo(u2.y) * (acc[nt][2] + bb), bf_hi(u2.y) * (acc[nt][3] + bb));
;                 *(v2u*)(U + (size_t)(r0 + t) * 1024 + colbase + 16 * nt + 4 * fq) = w; }
	v_mfma_f32_16x16x32_bf16 v[206:209], v[206:209], v[78:81], 0
	s_waitcnt vmcnt(31)
	v_lshlrev_b32_e32 v160, 16, v158
	v_and_b32_e32 v158, 0xffff0000, v158
	s_nop 0
	v_mul_f32_e32 v140, v140, v160
	v_mul_f32_e32 v141, v141, v158
	v_cvt_pk_bf16_f32 v140, v140, v141
	v_lshlrev_b32_e32 v141, 16, v159
	v_add_f32_e32 v142, v198, v142
	v_mul_f32_e32 v141, v142, v141
	v_and_b32_e32 v142, 0xffff0000, v159
	v_add_f32_e32 v143, v198, v143
	v_mul_f32_e32 v142, v143, v142
	v_cvt_pk_bf16_f32 v141, v141, v142
	global_store_dwordx2 v[144:145], v[140:141], off
	s_waitcnt vmcnt(31)
	v_lshlrev_b32_e32 v140, 16, v218
	v_add_f32_e32 v141, v198, v206
	v_mul_f32_e32 v140, v141, v140
	v_and_b32_e32 v141, 0xffff0000, v218
	v_add_f32_e32 v142, v198, v207
	s_waitcnt lgkmcnt(1)
	v_mfma_f32_16x16x32_bf16 v[210:213], v[210:213], v[78:81], 0
	v_mul_f32_e32 v141, v142, v141
	v_cvt_pk_bf16_f32 v140, v140, v141
	v_lshlrev_b32_e32 v141, 16, v219
	v_add_f32_e32 v142, v198, v208
	v_mul_f32_e32 v141, v142, v141
	v_and_b32_e32 v142, 0xffff0000, v219
	v_add_f32_e32 v143, v198, v209
	v_mul_f32_e32 v142, v143, v142
	v_cvt_pk_bf16_f32 v141, v141, v142
	global_store_dwordx2 v[144:145], v[140:141], off offset:32
	s_waitcnt vmcnt(31)
	v_lshlrev_b32_e32 v140, 16, v220
	v_add_f32_e32 v141, v198, v210
	s_waitcnt lgkmcnt(0)
	v_mfma_f32_16x16x32_bf16 v[78:81], v[214:217], v[78:81], 0
	v_mul_f32_e32 v140, v141, v140
	v_and_b32_e32 v141, 0xffff0000, v220
	v_add_f32_e32 v142, v198, v211
	v_mul_f32_e32 v141, v142, v141
	v_cvt_pk_bf16_f32 v140, v140, v141
	v_lshlrev_b32_e32 v141, 16, v221
	v_add_f32_e32 v142, v198, v212
	v_mul_f32_e32 v141, v142, v141
	v_and_b32_e32 v142, 0xffff0000, v221
	v_add_f32_e32 v143, v198, v213
	v_mul_f32_e32 v142, v143, v142
	v_cvt_pk_bf16_f32 v141, v141, v142
	global_store_dwordx2 v[144:145], v[140:141], off offset:64
	s_waitcnt vmcnt(31)
	v_lshlrev_b32_e32 v140, 16, v222
	v_add_f32_e32 v78, v198, v78
	v_mul_f32_e32 v78, v78, v140
	v_and_b32_e32 v140, 0xffff0000, v222
	v_add_f32_e32 v79, v198, v79
	v_mul_f32_e32 v79, v79, v140
	v_cvt_pk_bf16_f32 v158, v78, v79
	v_lshlrev_b32_e32 v78, 16, v223
	v_add_f32_e32 v79, v198, v80
	v_mul_f32_e32 v78, v79, v78
	v_and_b32_e32 v79, 0xffff0000, v223
	v_add_f32_e32 v80, v198, v81
	v_mul_f32_e32 v79, v80, v79
	v_cvt_pk_bf16_f32 v159, v78, v79
	ds_read_b128 v[78:81], v183 offset:1024
	ds_read_b128 v[140:143], v183 offset:1568
	s_waitcnt lgkmcnt(1)
	v_mfma_f32_16x16x32_bf16 v[78:81], v[78:81], v[74:77], 0
	ds_read_b128 v[206:209], v183 offset:2112
	ds_read_b128 v[210:213], v183 offset:2656
	global_store_dwordx2 v[144:145], v[158:159], off offset:96
	s_waitcnt vmcnt(31)
	v_lshlrev_b32_e32 v144, 16, v224
	s_nop 2
	v_add_f32_e32 v78, v197, v78
	v_mul_f32_e32 v78, v78, v144
	v_and_b32_e32 v144, 0xffff0000, v224
	v_add_f32_e32 v79, v197, v79
	s_waitcnt lgkmcnt(2)
	v_mfma_f32_16x16x32_bf16 v[140:143], v[140:143], v[74:77], 0
	v_mul_f32_e32 v79, v79, v144
	v_cvt_pk_bf16_f32 v78, v78, v79
	v_lshlrev_b32_e32 v79, 16, v225
	v_add_f32_e32 v80, v197, v80
	v_mul_f32_e32 v79, v80, v79
	v_and_b32_e32 v80, 0xffff0000, v225
	v_add_f32_e32 v81, v197, v81
	v_mul_f32_e32 v80, v81, v80
	v_cvt_pk_bf16_f32 v79, v79, v80
	global_store_dwordx2 v[226:227], v[78:79], off
	s_waitcnt vmcnt(31)
	v_lshlrev_b32_e32 v78, 16, v228
	v_add_f32_e32 v79, v197, v140
	v_mul_f32_e32 v78, v79, v78
	v_and_b32_e32 v79, 0xffff0000, v228
	v_add_f32_e32 v80, v197, v141
	s_waitcnt lgkmcnt(1)
	v_mfma_f32_16x16x32_bf16 v[206:209], v[206:209], v[74:77], 0
	v_mul_f32_e32 v79, v80, v79
	v_cvt_pk_bf16_f32 v78, v78, v79
	v_lshlrev_b32_e32 v79, 16, v229
	v_add_f32_e32 v80, v197, v142
	v_mul_f32_e32 v79, v80, v79
	v_and_b32_e32 v80, 0xffff0000, v229
	v_add_f32_e32 v81, v197, v143
	v_mul_f32_e32 v80, v81, v80
	v_cvt_pk_bf16_f32 v79, v79, v80
	global_store_dwordx2 v[226:227], v[78:79], off offset:32
	s_waitcnt vmcnt(31)
	v_lshlrev_b32_e32 v78, 16, v230
	v_add_f32_e32 v79, v197, v206
	s_waitcnt lgkmcnt(0)
	v_mfma_f32_16x16x32_bf16 v[74:77], v[210:213], v[74:77], 0
	v_mul_f32_e32 v78, v79, v78
	v_and_b32_e32 v79, 0xffff0000, v230
	v_add_f32_e32 v80, v197, v207
	v_mul_f32_e32 v79, v80, v79
	v_cvt_pk_bf16_f32 v78, v78, v79
	v_lshlrev_b32_e32 v79, 16, v231
	v_add_f32_e32 v80, v197, v208
	v_mul_f32_e32 v79, v80, v79
	v_and_b32_e32 v80, 0xffff0000, v231
	v_add_f32_e32 v81, v197, v209
	v_mul_f32_e32 v80, v81, v80
	v_cvt_pk_bf16_f32 v79, v79, v80
	global_store_dwordx2 v[226:227], v[78:79], off offset:64
	s_waitcnt vmcnt(31)
	v_lshlrev_b32_e32 v78, 16, v232
	v_add_f32_e32 v74, v197, v74
	v_mul_f32_e32 v74, v74, v78
	v_and_b32_e32 v78, 0xffff0000, v232
	v_add_f32_e32 v75, v197, v75
	v_mul_f32_e32 v75, v75, v78
	v_cvt_pk_bf16_f32 v144, v74, v75
	v_lshlrev_b32_e32 v74, 16, v233
	v_add_f32_e32 v75, v197, v76
	v_mul_f32_e32 v74, v75, v74
	v_and_b32_e32 v75, 0xffff0000, v233
	v_add_f32_e32 v76, v197, v77
	v_mul_f32_e32 v75, v76, v75
	v_cvt_pk_bf16_f32 v145, v74, v75
	ds_read_b128 v[74:77], v183 offset:1024
	ds_read_b128 v[78:81], v183 offset:1088
	s_waitcnt lgkmcnt(1)
	v_mfma_f32_16x16x32_bf16 v[74:77], v[74:77], v[70:73], 0
	ds_read_b128 v[140:143], v183 offset:1568
	ds_read_b128 v[206:209], v183 offset:1632
	ds_read_b128 v[210:213], v183 offset:2112
	ds_read_b128 v[214:217], v183 offset:2176
	ds_read_b128 v[218:221], v183 offset:2656
	ds_read_b128 v[222:225], v183 offset:2720
	s_waitcnt lgkmcnt(5)
	v_mfma_f32_16x16x32_bf16 v[140:143], v[140:143], v[70:73], 0
	global_store_dwordx2 v[226:227], v[144:145], off offset:96
	s_waitcnt lgkmcnt(3)
	v_mfma_f32_16x16x32_bf16 v[210:213], v[210:213], v[70:73], 0
	s_waitcnt lgkmcnt(1)
; __device__ __forceinline__ unsigned cvt_pk_bf16(float lo, float hi) { unsigned r; asm volatile("v_cvt_pk_bf16_f32 %0, %1, %2" : "=v"(r) : "v"(lo), "v"(hi)); return r; }
; __device__ __forceinline__ float bf_lo(unsigned w) { return __uint_as_float(w << 16); }
; __device__ __forceinline__ float bf_hi(unsigned w) { return __uint_as_float(w & 0xffff0000u); }
; #define LAS __attribute__((address_space(3)))
; __device__ __forceinline__ void sgu_unit(LAS unsigned char* lds, bf16* U, const bf16* VS, const float* SGS, const float* lnw, const float* lnb, const v4u* WF, const float* bsl, int unit, int tid) {
;     ...
;         for (int mt = 0; mt < 8; ++mt) {
;             const int t = 16 * mt + fr;
;             f32x4 acc[4];
; #pragma unroll
;             for (int nt = 0; nt < 4; ++nt) acc[nt] = (f32x4){0.f, 0.f, 0.f, 0.f};
; #pragma unroll
;             for (int ks = 0; ks <= (mt >> 1); ++ks) {
;                 const int sb = 32 * ks + 8 * fq; const bf16x8_t wf = __builtin_bit_cast(bf16x8_t, wfr[q++]);
; #pragma unroll
;                 for (int nt = 0; nt < 4; ++nt) { const bf16x8_t vf = *(const LAS bf16x8_t*)(vt + ((fr >> 3) + 8 * (fr & 7) + 2 * nt) * SGU_VP + sb * 2);
;                     acc[nt] = __builtin_amdgcn_mfma_f32_16x16x32_bf16(vf, wf, acc[nt], 0, 0, 0); }
;             }
;             const float bb = bbv[mt];
; #pragma unroll
;             for (int nt = 0; nt < 4; ++nt) { const v2u u2 = uu[mt][nt]; v2u w; w.x = cvt_pk_bf16(bf_lo(u2.x) * (acc[nt][0] + bb), bf_hi(u2.x) * (acc[nt][1] + bb)); w.y = cvt_pk_bf16(bf_lo(u2.y) * (acc[nt][2] + bb), bf_hi(u2.y) * (acc[nt][3] + bb));
;                 *(v2u*)(U + (size_t)(r0 + t) * 1024 + colbase + 16 * nt + 4 * fq) = w; }
	v_mfma_f32_16x16x32_bf16 v[70:73], v[218:221], v[70:73], 0
	v_mfma_f32_16x16x32_bf16 v[74:77], v[78:81], v[66:69], v[74:77]
	v_mfma_f32_16x16x32_bf16 v[78:81], v[206:209], v[66:69], v[140:143]
	v_mfma_f32_16x16x32_bf16 v[140:143], v[214:217], v[66:69], v[210:213]
	s_waitcnt lgkmcnt(0)
	v_mfma_f32_16x16x32_bf16 v[66:69], v[222:225], v[66:69], v[70:73]
	s_waitcnt vmcnt(31)
	s_nop 1
	v_lshlrev_b32_e32 v70, 16, v234
	v_add_f32_e32 v71, v196, v74
	v_mul_f32_e32 v70, v71, v70
	v_and_b32_e32 v71, 0xffff0000, v234
	v_add_f32_e32 v72, v196, v75
	v_mul_f32_e32 v71, v72, v71
	v_cvt_pk_bf16_f32 v70, v70, v71
	v_lshlrev_b32_e32 v71, 16, v235
	v_add_f32_e32 v72, v196, v76
	v_mul_f32_e32 v71, v72, v71
	v_and_b32_e32 v72, 0xffff0000, v235
	v_add_f32_e32 v73, v196, v77
	v_mul_f32_e32 v72, v73, v72
	v_cvt_pk_bf16_f32 v71, v71, v72
	global_store_dwordx2 v[130:131], v[70:71], off
	s_waitcnt vmcnt(31)
	v_lshlrev_b32_e32 v70, 16, v138
	v_add_f32_e32 v71, v196, v78
	v_mul_f32_e32 v70, v71, v70
	v_and_b32_e32 v71, 0xffff0000, v138
	v_add_f32_e32 v72, v196, v79
	v_mul_f32_e32 v71, v72, v71
	v_cvt_pk_bf16_f32 v70, v70, v71
	v_lshlrev_b32_e32 v71, 16, v139
	v_add_f32_e32 v72, v196, v80
	v_mul_f32_e32 v71, v72, v71
	v_and_b32_e32 v72, 0xffff0000, v139
	v_add_f32_e32 v73, v196, v81
	v_mul_f32_e32 v72, v73, v72
	v_cvt_pk_bf16_f32 v71, v71, v72
	global_store_dwordx2 v[130:131], v[70:71], off offset:32
	s_waitcnt vmcnt(31)
	v_lshlrev_b32_e32 v70, 16, v136
	v_add_f32_e32 v71, v196, v140
	v_mul_f32_e32 v70, v71, v70
	v_and_b32_e32 v71, 0xffff0000, v136
	v_add_f32_e32 v72, v196, v141
	v_mul_f32_e32 v71, v72, v71
	v_cvt_pk_bf16_f32 v70, v70, v71
	v_lshlrev_b32_e32 v71, 16, v137
	v_add_f32_e32 v72, v196, v142
	v_mul_f32_e32 v71, v72, v71
	v_and_b32_e32 v72, 0xffff0000, v137
	v_add_f32_e32 v73, v196, v143
	v_mul_f32_e32 v72, v73, v72
	v_cvt_pk_bf16_f32 v71, v71, v72
	global_store_dwordx2 v[130:131], v[70:71], off offset:64
	s_waitcnt vmcnt(31)
	v_lshlrev_b32_e32 v70, 16, v134
	v_add_f32_e32 v66, v196, v66
	v_mul_f32_e32 v66, v66, v70
	v_and_b32_e32 v70, 0xffff0000, v134
	v_add_f32_e32 v67, v196, v67
	v_mul_f32_e32 v67, v67, v70
	v_cvt_pk_bf16_f32 v158, v66, v67
	v_lshlrev_b32_e32 v66, 16, v135
	v_add_f32_e32 v67, v196, v68
	v_mul_f32_e32 v66, v67, v66
	v_and_b32_e32 v67, 0xffff0000, v135
	v_add_f32_e32 v68, v196, v69
	v_mul_f32_e32 v67, v68, v67
	v_cvt_pk_bf16_f32 v159, v66, v67
	ds_read_b128 v[66:69], v183 offset:1024
	ds_read_b128 v[70:73], v183 offset:1088
	s_waitcnt lgkmcnt(1)
	v_mfma_f32_16x16x32_bf16 v[66:69], v[66:69], v[62:65], 0
	ds_read_b128 v[74:77], v183 offset:1568
	ds_read_b128 v[78:81], v183 offset:1632
	ds_read_b128 v[134:137], v183 offset:2112
	ds_read_b128 v[138:141], v183 offset:2176
	ds_read_b128 v[142:145], v183 offset:2656
	ds_read_b128 v[196:199], v183 offset:2720
	s_waitcnt lgkmcnt(5)
	v_mfma_f32_16x16x32_bf16 v[74:77], v[74:77], v[62:65], 0
	global_store_dwordx2 v[130:131], v[158:159], off offset:96
	s_waitcnt lgkmcnt(3)
	v_mfma_f32_16x16x32_bf16 v[134:137], v[134:137], v[62:65], 0
	s_waitcnt lgkmcnt(1)
	v_mfma_f32_16x16x32_bf16 v[62:65], v[142:145], v[62:65], 0
	v_mfma_f32_16x16x32_bf16 v[66:69], v[70:73], v[58:61], v[66:69]
	v_mfma_f32_16x16x32_bf16 v[70:73], v[78:81], v[58:61], v[74:77]
	v_mfma_f32_16x16x32_bf16 v[74:77], v[138:141], v[58:61], v[134:137]
	s_waitcnt lgkmcnt(0)
	v_mfma_f32_16x16x32_bf16 v[58:61], v[196:199], v[58:61], v[62:65]
	s_waitcnt vmcnt(31)
	s_nop 1
	v_lshlrev_b32_e32 v62, 16, v132
	v_add_f32_e32 v63, v195, v66
	v_mul_f32_e32 v62, v63, v62
	v_and_b32_e32 v63, 0xffff0000, v132
	v_add_f32_e32 v64, v195, v67
	v_mul_f32_e32 v63, v64, v63
	v_cvt_pk_bf16_f32 v62, v62, v63
	v_lshlrev_b32_e32 v63, 16, v133
	v_add_f32_e32 v64, v195, v68
	v_mul_f32_e32 v63, v64, v63
	v_and_b32_e32 v64, 0xffff0000, v133
	v_add_f32_e32 v65, v195, v69
	v_mul_f32_e32 v64, v65, v64
	v_cvt_pk_bf16_f32 v63, v63, v64
	global_store_dwordx2 v[120:121], v[62:63], off
	s_waitcnt vmcnt(31)
	v_lshlrev_b32_e32 v62, 16, v128
	v_add_f32_e32 v63, v195, v70
	v_mul_f32_e32 v62, v63, v62
	v_and_b32_e32 v63, 0xffff0000, v128
	v_add_f32_e32 v64, v195, v71
	v_mul_f32_e32 v63, v64, v63
	v_cvt_pk_bf16_f32 v62, v62, v63
	v_lshlrev_b32_e32 v63, 16, v129
	v_add_f32_e32 v64, v195, v72
	v_mul_f32_e32 v63, v64, v63
	v_and_b32_e32 v64, 0xffff0000, v129
	v_add_f32_e32 v65, v195, v73
	v_mul_f32_e32 v64, v65, v64
	v_cvt_pk_bf16_f32 v63, v63, v64
	global_store_dwordx2 v[120:121], v[62:63], off offset:32
	s_waitcnt vmcnt(31)
	v_lshlrev_b32_e32 v62, 16, v126
	v_add_f32_e32 v63, v195, v74
	v_mul_f32_e32 v62, v63, v62
	v_and_b32_e32 v63, 0xffff0000, v126
	v_add_f32_e32 v64, v195, v75
	v_mul_f32_e32 v63, v64, v63
	v_cvt_pk_bf16_f32 v62, v62, v63
	v_lshlrev_b32_e32 v63, 16, v127
	v_add_f32_e32 v64, v195, v76
	v_mul_f32_e32 v63, v64, v63
	v_and_b32_e32 v64, 0xffff0000, v127
	v_add_f32_e32 v65, v195, v77
	v_mul_f32_e32 v64, v65, v64
	v_cvt_pk_bf16_f32 v63, v63, v64
	global_store_dwordx2 v[120:121], v[62:63], off offset:64
	s_waitcnt vmcnt(31)
	v_lshlrev_b32_e32 v62, 16, v124
	v_add_f32_e32 v58, v195, v58
	v_mul_f32_e32 v58, v58, v62
	v_and_b32_e32 v62, 0xffff0000, v124
	v_add_f32_e32 v59, v195, v59
	v_mul_f32_e32 v59, v59, v62
	v_cvt_pk_bf16_f32 v132, v58, v59
	v_lshlrev_b32_e32 v58, 16, v125
	v_add_f32_e32 v59, v195, v60
	v_mul_f32_e32 v58, v59, v58
	v_and_b32_e32 v59, 0xffff0000, v125
	v_add_f32_e32 v60, v195, v61
	v_mul_f32_e32 v59, v60, v59
	v_cvt_pk_bf16_f32 v133, v58, v59
	ds_read_b128 v[58:61], v183 offset:1024
	ds_read_b128 v[62:65], v183 offset:1088
	s_waitcnt lgkmcnt(1)
; __device__ __forceinline__ unsigned cvt_pk_bf16(float lo, float hi) { unsigned r; asm volatile("v_cvt_pk_bf16_f32 %0, %1, %2" : "=v"(r) : "v"(lo), "v"(hi)); return r; }
; __device__ __forceinline__ float bf_lo(unsigned w) { return __uint_as_float(w << 16); }
; __device__ __forceinline__ float bf_hi(unsigned w) { return __uint_as_float(w & 0xffff0000u); }
; #define LAS __attribute__((address_space(3)))
; __device__ __forceinline__ void sgu_unit(LAS unsigned char* lds, bf16* U, const bf16* VS, const float* SGS, const float* lnw, const float* lnb, const v4u* WF, const float* bsl, int unit, int tid) {
;     ...
;         for (int mt = 0; mt < 8; ++mt) {
;             const int t = 16 * mt + fr;
;             f32x4 acc[4];
; #pragma unroll
;             for (int nt = 0; nt < 4; ++nt) acc[nt] = (f32x4){0.f, 0.f, 0.f, 0.f};
; #pragma unroll
;             for (int ks = 0; ks <= (mt >> 1); ++ks) {
;                 const int sb = 32 * ks + 8 * fq; const bf16x8_t wf = __builtin_bit_cast(bf16x8_t, wfr[q++]);
; #pragma unroll
;                 for (int nt = 0; nt < 4; ++nt) { const bf16x8_t vf = *(const LAS bf16x8_t*)(vt + ((fr >> 3) + 8 * (fr & 7) + 2 * nt) * SGU_VP + sb * 2);
;                     acc[nt] = __builtin_amdgcn_mfma_f32_16x16x32_bf16(vf, wf, acc[nt], 0, 0, 0); }
;             }
;             const float bb = bbv[mt];
; #pragma unroll
;             for (int nt = 0; nt < 4; ++nt) { const v2u u2 = uu[mt][nt]; v2u w; w.x = cvt_pk_bf16(bf_lo(u2.x) * (acc[nt][0] + bb), bf_hi(u2.x) * (acc[nt][1] + bb)); w.y = cvt_pk_bf16(bf_lo(u2.y) * (acc[nt][2] + bb), bf_hi(u2.y) * (acc[nt][3] + bb));
;                 *(v2u*)(U + (size_t)(r0 + t) * 1024 + colbase + 16 * nt + 4 * fq) = w; }
	v_mfma_f32_16x16x32_bf16 v[58:61], v[58:61], v[50:53], 0
	ds_read_b128 v[66:69], v183 offset:1568
	ds_read_b128 v[70:73], v183 offset:1152
	ds_read_b128 v[74:77], v183 offset:2112
	ds_read_b128 v[78:81], v183 offset:2176
	ds_read_b128 v[124:127], v183 offset:2656
	ds_read_b128 v[128:131], v183 offset:2240
	s_waitcnt lgkmcnt(5)
	v_mfma_f32_16x16x32_bf16 v[66:69], v[66:69], v[50:53], 0
	s_waitcnt lgkmcnt(3)
	v_mfma_f32_16x16x32_bf16 v[74:77], v[74:77], v[50:53], 0
	s_waitcnt lgkmcnt(1)
	v_mfma_f32_16x16x32_bf16 v[50:53], v[124:127], v[50:53], 0
	v_mfma_f32_16x16x32_bf16 v[58:61], v[62:65], v[54:57], v[58:61]
	ds_read_b128 v[62:65], v183 offset:1632
	ds_read_b128 v[124:127], v183 offset:1696
	s_waitcnt lgkmcnt(1)
	v_mfma_f32_16x16x32_bf16 v[62:65], v[62:65], v[54:57], v[66:69]
	v_mfma_f32_16x16x32_bf16 v[66:69], v[78:81], v[54:57], v[74:77]
	s_nop 2
	ds_read_b128 v[74:77], v183 offset:2720
	ds_read_b128 v[78:81], v183 offset:2784
	global_store_dwordx2 v[120:121], v[132:133], off offset:96
	s_waitcnt lgkmcnt(1)
	v_mfma_f32_16x16x32_bf16 v[50:53], v[74:77], v[54:57], v[50:53]
	v_mfma_f32_16x16x32_bf16 v[54:57], v[70:73], v[46:49], v[58:61]
	v_mfma_f32_16x16x32_bf16 v[58:61], v[124:127], v[46:49], v[62:65]
	v_mfma_f32_16x16x32_bf16 v[62:65], v[128:131], v[46:49], v[66:69]
	s_waitcnt lgkmcnt(0)
	v_mfma_f32_16x16x32_bf16 v[46:49], v[78:81], v[46:49], v[50:53]
	s_waitcnt vmcnt(31)
	s_nop 1
	v_lshlrev_b32_e32 v50, 16, v122
	v_add_f32_e32 v51, v194, v54
	v_mul_f32_e32 v50, v51, v50
	v_and_b32_e32 v51, 0xffff0000, v122
	v_add_f32_e32 v52, v194, v55
	v_mul_f32_e32 v51, v52, v51
	v_cvt_pk_bf16_f32 v50, v50, v51
	v_lshlrev_b32_e32 v51, 16, v123
	v_add_f32_e32 v52, v194, v56
	v_mul_f32_e32 v51, v52, v51
	v_and_b32_e32 v52, 0xffff0000, v123
	v_add_f32_e32 v53, v194, v57
	v_mul_f32_e32 v52, v53, v52
	v_cvt_pk_bf16_f32 v51, v51, v52
	global_store_dwordx2 v[110:111], v[50:51], off
	s_waitcnt vmcnt(31)
	v_lshlrev_b32_e32 v50, 16, v118
	v_add_f32_e32 v51, v194, v58
	v_mul_f32_e32 v50, v51, v50
	v_and_b32_e32 v51, 0xffff0000, v118
	v_add_f32_e32 v52, v194, v59
	v_mul_f32_e32 v51, v52, v51
	v_cvt_pk_bf16_f32 v50, v50, v51
	v_lshlrev_b32_e32 v51, 16, v119
	v_add_f32_e32 v52, v194, v60
	v_mul_f32_e32 v51, v52, v51
	v_and_b32_e32 v52, 0xffff0000, v119
	v_add_f32_e32 v53, v194, v61
	v_mul_f32_e32 v52, v53, v52
	v_cvt_pk_bf16_f32 v51, v51, v52
	global_store_dwordx2 v[110:111], v[50:51], off offset:32
	s_waitcnt vmcnt(31)
	v_lshlrev_b32_e32 v50, 16, v116
	v_add_f32_e32 v51, v194, v62
	v_mul_f32_e32 v50, v51, v50
	v_and_b32_e32 v51, 0xffff0000, v116
	v_add_f32_e32 v52, v194, v63
	v_mul_f32_e32 v51, v52, v51
	v_cvt_pk_bf16_f32 v50, v50, v51
	v_lshlrev_b32_e32 v51, 16, v117
	v_add_f32_e32 v52, v194, v64
	v_mul_f32_e32 v51, v52, v51
	v_and_b32_e32 v52, 0xffff0000, v117
	v_add_f32_e32 v53, v194, v65
	v_mul_f32_e32 v52, v53, v52
	v_cvt_pk_bf16_f32 v51, v51, v52
	global_store_dwordx2 v[110:111], v[50:51], off offset:64
	s_waitcnt vmcnt(31)
	v_lshlrev_b32_e32 v50, 16, v114
	v_add_f32_e32 v46, v194, v46
	v_mul_f32_e32 v46, v46, v50
	v_and_b32_e32 v50, 0xffff0000, v114
	v_add_f32_e32 v47, v194, v47
	v_mul_f32_e32 v47, v47, v50
	v_cvt_pk_bf16_f32 v78, v46, v47
	v_lshlrev_b32_e32 v46, 16, v115
	v_add_f32_e32 v47, v194, v48
	v_mul_f32_e32 v46, v47, v46
	v_and_b32_e32 v47, 0xffff0000, v115
	v_add_f32_e32 v48, v194, v49
	v_mul_f32_e32 v47, v48, v47
	v_cvt_pk_bf16_f32 v79, v46, v47
	ds_read_b128 v[46:49], v183 offset:1024
	ds_read_b128 v[50:53], v183 offset:1088
	s_waitcnt lgkmcnt(1)
	v_mfma_f32_16x16x32_bf16 v[46:49], v[46:49], v[42:45], 0
	ds_read_b128 v[54:57], v183 offset:1568
	ds_read_b128 v[58:61], v183 offset:1152
	ds_read_b128 v[62:65], v183 offset:2112
	ds_read_b128 v[66:69], v183 offset:2176
	ds_read_b128 v[70:73], v183 offset:2656
	ds_read_b128 v[74:77], v183 offset:2240
	s_waitcnt lgkmcnt(5)
	v_mfma_f32_16x16x32_bf16 v[54:57], v[54:57], v[42:45], 0
	s_waitcnt lgkmcnt(3)
	v_mfma_f32_16x16x32_bf16 v[62:65], v[62:65], v[42:45], 0
	s_waitcnt lgkmcnt(1)
	v_mfma_f32_16x16x32_bf16 v[42:45], v[70:73], v[42:45], 0
	v_mfma_f32_16x16x32_bf16 v[46:49], v[50:53], v[34:37], v[46:49]
	ds_read_b128 v[50:53], v183 offset:1632
	ds_read_b128 v[70:73], v183 offset:1696
	s_waitcnt lgkmcnt(1)
	v_mfma_f32_16x16x32_bf16 v[50:53], v[50:53], v[34:37], v[54:57]
	v_mfma_f32_16x16x32_bf16 v[54:57], v[66:69], v[34:37], v[62:65]
	s_nop 2
	ds_read_b128 v[62:65], v183 offset:2720
	ds_read_b128 v[66:69], v183 offset:2784
	global_store_dwordx2 v[110:111], v[78:79], off offset:96
	s_waitcnt lgkmcnt(1)
	v_mfma_f32_16x16x32_bf16 v[34:37], v[62:65], v[34:37], v[42:45]
	v_mfma_f32_16x16x32_bf16 v[42:45], v[58:61], v[38:41], v[46:49]
	v_mfma_f32_16x16x32_bf16 v[46:49], v[70:73], v[38:41], v[50:53]
	v_mfma_f32_16x16x32_bf16 v[50:53], v[74:77], v[38:41], v[54:57]
	s_waitcnt lgkmcnt(0)
	v_mfma_f32_16x16x32_bf16 v[34:37], v[66:69], v[38:41], v[34:37]
	s_waitcnt vmcnt(31)
	v_lshlrev_b32_e32 v38, 16, v112
	s_nop 1
	v_add_f32_e32 v39, v193, v42
	v_mul_f32_e32 v38, v39, v38
	v_and_b32_e32 v39, 0xffff0000, v112
	v_add_f32_e32 v40, v193, v43
	v_mul_f32_e32 v39, v40, v39
	v_cvt_pk_bf16_f32 v38, v38, v39
	v_lshlrev_b32_e32 v39, 16, v113
	v_add_f32_e32 v40, v193, v44
	v_mul_f32_e32 v39, v40, v39
	v_and_b32_e32 v40, 0xffff0000, v113
	v_add_f32_e32 v41, v193, v45
	v_mul_f32_e32 v40, v41, v40
	v_cvt_pk_bf16_f32 v39, v39, v40
	global_store_dwordx2 v[100:101], v[38:39], off
	s_waitcnt vmcnt(31)
; __device__ __forceinline__ unsigned cvt_pk_bf16(float lo, float hi) { unsigned r; asm volatile("v_cvt_pk_bf16_f32 %0, %1, %2" : "=v"(r) : "v"(lo), "v"(hi)); return r; }
; __device__ __forceinline__ float bf_lo(unsigned w) { return __uint_as_float(w << 16); }
; __device__ __forceinline__ float bf_hi(unsigned w) { return __uint_as_float(w & 0xffff0000u); }
; #define LAS __attribute__((address_space(3)))
; __device__ __forceinline__ void sgu_unit(LAS unsigned char* lds, bf16* U, const bf16* VS, const float* SGS, const float* lnw, const float* lnb, const v4u* WF, const float* bsl, int unit, int tid) {
;     ...
;         for (int mt = 0; mt < 8; ++mt) {
;             const int t = 16 * mt + fr;
;             f32x4 acc[4];
; #pragma unroll
;             for (int nt = 0; nt < 4; ++nt) acc[nt] = (f32x4){0.f, 0.f, 0.f, 0.f};
; #pragma unroll
;             for (int ks = 0; ks <= (mt >> 1); ++ks) {
;                 const int sb = 32 * ks + 8 * fq; const bf16x8_t wf = __builtin_bit_cast(bf16x8_t, wfr[q++]);
; #pragma unroll
;                 for (int nt = 0; nt < 4; ++nt) { const bf16x8_t vf = *(const LAS bf16x8_t*)(vt + ((fr >> 3) + 8 * (fr & 7) + 2 * nt) * SGU_VP + sb * 2);
;                     acc[nt] = __builtin_amdgcn_mfma_f32_16x16x32_bf16(vf, wf, acc[nt], 0, 0, 0); }
;             }
;             const float bb = bbv[mt];
; #pragma unroll
;             for (int nt = 0; nt < 4; ++nt) { const v2u u2 = uu[mt][nt]; v2u w; w.x = cvt_pk_bf16(bf_lo(u2.x) * (acc[nt][0] + bb), bf_hi(u2.x) * (acc[nt][1] + bb)); w.y = cvt_pk_bf16(bf_lo(u2.y) * (acc[nt][2] + bb), bf_hi(u2.y) * (acc[nt][3] + bb));
;                 *(v2u*)(U + (size_t)(r0 + t) * 1024 + colbase + 16 * nt + 4 * fq) = w; }
	v_lshlrev_b32_e32 v38, 16, v108
	v_add_f32_e32 v39, v193, v46
	v_mul_f32_e32 v38, v39, v38
	v_and_b32_e32 v39, 0xffff0000, v108
	v_add_f32_e32 v40, v193, v47
	v_mul_f32_e32 v39, v40, v39
	v_cvt_pk_bf16_f32 v38, v38, v39
	v_lshlrev_b32_e32 v39, 16, v109
	v_add_f32_e32 v40, v193, v48
	v_mul_f32_e32 v39, v40, v39
	v_and_b32_e32 v40, 0xffff0000, v109
	v_add_f32_e32 v41, v193, v49
	v_mul_f32_e32 v40, v41, v40
	v_cvt_pk_bf16_f32 v39, v39, v40
	global_store_dwordx2 v[100:101], v[38:39], off offset:32
	s_waitcnt vmcnt(31)
	v_lshlrev_b32_e32 v38, 16, v106
	v_add_f32_e32 v39, v193, v50
	v_mul_f32_e32 v38, v39, v38
	v_and_b32_e32 v39, 0xffff0000, v106
	v_add_f32_e32 v40, v193, v51
	v_mul_f32_e32 v39, v40, v39
	v_cvt_pk_bf16_f32 v38, v38, v39
	v_lshlrev_b32_e32 v39, 16, v107
	v_add_f32_e32 v40, v193, v52
	v_mul_f32_e32 v39, v40, v39
	v_and_b32_e32 v40, 0xffff0000, v107
	v_add_f32_e32 v41, v193, v53
	v_mul_f32_e32 v40, v41, v40
	v_cvt_pk_bf16_f32 v39, v39, v40
	global_store_dwordx2 v[100:101], v[38:39], off offset:64
	s_waitcnt vmcnt(31)
	v_lshlrev_b32_e32 v38, 16, v104
	v_add_f32_e32 v34, v193, v34
	v_mul_f32_e32 v34, v34, v38
	v_and_b32_e32 v38, 0xffff0000, v104
	v_add_f32_e32 v35, v193, v35
	v_mul_f32_e32 v35, v35, v38
	v_cvt_pk_bf16_f32 v66, v34, v35
	v_lshlrev_b32_e32 v34, 16, v105
	v_add_f32_e32 v35, v193, v36
	v_mul_f32_e32 v34, v35, v34
	v_and_b32_e32 v35, 0xffff0000, v105
	v_add_f32_e32 v36, v193, v37
	v_mul_f32_e32 v35, v36, v35
	v_cvt_pk_bf16_f32 v67, v34, v35
	ds_read_b128 v[34:37], v183 offset:1024
	ds_read_b128 v[38:41], v183 offset:1088
	ds_read_b128 v[42:45], v183 offset:1568
	ds_read_b128 v[46:49], v183 offset:1632
	ds_read_b128 v[50:53], v183 offset:2112
	ds_read_b128 v[54:57], v183 offset:2176
	ds_read_b128 v[58:61], v183 offset:2656
	ds_read_b128 v[62:65], v183 offset:2720
	s_waitcnt lgkmcnt(7)
	v_mfma_f32_16x16x32_bf16 v[34:37], v[34:37], v[30:33], 0
	s_waitcnt lgkmcnt(5)
	v_mfma_f32_16x16x32_bf16 v[42:45], v[42:45], v[30:33], 0
	s_waitcnt lgkmcnt(3)
	v_mfma_f32_16x16x32_bf16 v[50:53], v[50:53], v[30:33], 0
	s_waitcnt lgkmcnt(1)
	v_mfma_f32_16x16x32_bf16 v[30:33], v[58:61], v[30:33], 0
	v_mfma_f32_16x16x32_bf16 v[34:37], v[38:41], v[26:29], v[34:37]
	v_mfma_f32_16x16x32_bf16 v[38:41], v[46:49], v[26:29], v[42:45]
	v_mfma_f32_16x16x32_bf16 v[42:45], v[54:57], v[26:29], v[50:53]
	s_waitcnt lgkmcnt(0)
	v_mfma_f32_16x16x32_bf16 v[26:29], v[62:65], v[26:29], v[30:33]
	s_nop 2
	ds_read_b128 v[30:33], v183 offset:1152
	ds_read_b128 v[46:49], v183 offset:1216
	s_waitcnt lgkmcnt(1)
	v_mfma_f32_16x16x32_bf16 v[30:33], v[30:33], v[22:25], v[34:37]
	s_nop 2
	ds_read_b128 v[34:37], v183 offset:1696
	ds_read_b128 v[50:53], v183 offset:1760
	s_waitcnt lgkmcnt(1)
	v_mfma_f32_16x16x32_bf16 v[34:37], v[34:37], v[22:25], v[38:41]
	s_nop 2
	ds_read_b128 v[38:41], v183 offset:2240
	ds_read_b128 v[54:57], v183 offset:2304
	s_waitcnt lgkmcnt(1)
	v_mfma_f32_16x16x32_bf16 v[38:41], v[38:41], v[22:25], v[42:45]
	s_nop 2
	ds_read_b128 v[42:45], v183 offset:2784
	ds_read_b128 v[58:61], v183 offset:2848
	global_store_dwordx2 v[100:101], v[66:67], off offset:96
	s_waitcnt lgkmcnt(1)
	v_mfma_f32_16x16x32_bf16 v[22:25], v[42:45], v[22:25], v[26:29]
	v_mfma_f32_16x16x32_bf16 v[26:29], v[46:49], v[18:21], v[30:33]
	v_mfma_f32_16x16x32_bf16 v[30:33], v[50:53], v[18:21], v[34:37]
	v_mfma_f32_16x16x32_bf16 v[34:37], v[54:57], v[18:21], v[38:41]
	s_waitcnt lgkmcnt(0)
	v_mfma_f32_16x16x32_bf16 v[18:21], v[58:61], v[18:21], v[22:25]
	s_waitcnt vmcnt(31)
	s_nop 1
	v_lshlrev_b32_e32 v22, 16, v102
	v_add_f32_e32 v23, v192, v26
	v_mul_f32_e32 v22, v23, v22
	v_and_b32_e32 v23, 0xffff0000, v102
	v_add_f32_e32 v24, v192, v27
	v_mul_f32_e32 v23, v24, v23
	v_cvt_pk_bf16_f32 v22, v22, v23
	v_lshlrev_b32_e32 v23, 16, v103
	v_add_f32_e32 v24, v192, v28
	v_mul_f32_e32 v23, v24, v23
	v_and_b32_e32 v24, 0xffff0000, v103
	v_add_f32_e32 v25, v192, v29
	v_mul_f32_e32 v24, v25, v24
	v_cvt_pk_bf16_f32 v23, v23, v24
	global_store_dwordx2 v[90:91], v[22:23], off
	s_waitcnt vmcnt(31)
	v_lshlrev_b32_e32 v22, 16, v98
	v_add_f32_e32 v23, v192, v30
	v_mul_f32_e32 v22, v23, v22
	v_and_b32_e32 v23, 0xffff0000, v98
	v_add_f32_e32 v24, v192, v31
	v_mul_f32_e32 v23, v24, v23
	v_cvt_pk_bf16_f32 v22, v22, v23
	v_lshlrev_b32_e32 v23, 16, v99
	v_add_f32_e32 v24, v192, v32
	v_mul_f32_e32 v23, v24, v23
	v_and_b32_e32 v24, 0xffff0000, v99
	v_add_f32_e32 v25, v192, v33
	v_mul_f32_e32 v24, v25, v24
	v_cvt_pk_bf16_f32 v23, v23, v24
	global_store_dwordx2 v[90:91], v[22:23], off offset:32
	s_waitcnt vmcnt(31)
; __device__ __forceinline__ unsigned cvt_pk_bf16(float lo, float hi) { unsigned r; asm volatile("v_cvt_pk_bf16_f32 %0, %1, %2" : "=v"(r) : "v"(lo), "v"(hi)); return r; }
; __device__ __forceinline__ float bf_lo(unsigned w) { return __uint_as_float(w << 16); }
; __device__ __forceinline__ float bf_hi(unsigned w) { return __uint_as_float(w & 0xffff0000u); }
; #define LAS __attribute__((address_space(3)))
; __device__ __forceinline__ void sgu_unit(LAS unsigned char* lds, bf16* U, const bf16* VS, const float* SGS, const float* lnw, const float* lnb, const v4u* WF, const float* bsl, int unit, int tid) {
;     ...
;         for (int mt = 0; mt < 8; ++mt) {
;             const int t = 16 * mt + fr;
;             f32x4 acc[4];
; #pragma unroll
;             for (int nt = 0; nt < 4; ++nt) acc[nt] = (f32x4){0.f, 0.f, 0.f, 0.f};
; #pragma unroll
;             for (int ks = 0; ks <= (mt >> 1); ++ks) {
;                 const int sb = 32 * ks + 8 * fq; const bf16x8_t wf = __builtin_bit_cast(bf16x8_t, wfr[q++]);
; #pragma unroll
;                 for (int nt = 0; nt < 4; ++nt) { const bf16x8_t vf = *(const LAS bf16x8_t*)(vt + ((fr >> 3) + 8 * (fr & 7) + 2 * nt) * SGU_VP + sb * 2);
;                     acc[nt] = __builtin_amdgcn_mfma_f32_16x16x32_bf16(vf, wf, acc[nt], 0, 0, 0); }
;             }
;             const float bb = bbv[mt];
; #pragma unroll
;             for (int nt = 0; nt < 4; ++nt) { const v2u u2 = uu[mt][nt]; v2u w; w.x = cvt_pk_bf16(bf_lo(u2.x) * (acc[nt][0] + bb), bf_hi(u2.x) * (acc[nt][1] + bb)); w.y = cvt_pk_bf16(bf_lo(u2.y) * (acc[nt][2] + bb), bf_hi(u2.y) * (acc[nt][3] + bb));
;                 *(v2u*)(U + (size_t)(r0 + t) * 1024 + colbase + 16 * nt + 4 * fq) = w; }
;         }
;     }
;     __syncthreads();
	v_lshlrev_b32_e32 v22, 16, v96
	v_add_f32_e32 v23, v192, v34
	v_mul_f32_e32 v22, v23, v22
	v_and_b32_e32 v23, 0xffff0000, v96
	v_add_f32_e32 v24, v192, v35
	v_mul_f32_e32 v23, v24, v23
	v_cvt_pk_bf16_f32 v22, v22, v23
	v_lshlrev_b32_e32 v23, 16, v97
	v_add_f32_e32 v24, v192, v36
	v_mul_f32_e32 v23, v24, v23
	v_and_b32_e32 v24, 0xffff0000, v97
	v_add_f32_e32 v25, v192, v37
	v_mul_f32_e32 v24, v25, v24
	v_cvt_pk_bf16_f32 v23, v23, v24
	global_store_dwordx2 v[90:91], v[22:23], off offset:64
	s_waitcnt vmcnt(31)
	v_lshlrev_b32_e32 v22, 16, v94
	v_add_f32_e32 v18, v192, v18
	v_mul_f32_e32 v18, v18, v22
	v_and_b32_e32 v22, 0xffff0000, v94
	v_add_f32_e32 v19, v192, v19
	v_mul_f32_e32 v19, v19, v22
	v_cvt_pk_bf16_f32 v50, v18, v19
	v_lshlrev_b32_e32 v18, 16, v95
	v_add_f32_e32 v19, v192, v20
	v_mul_f32_e32 v18, v19, v18
	v_and_b32_e32 v19, 0xffff0000, v95
	v_add_f32_e32 v20, v192, v21
	v_mul_f32_e32 v19, v20, v19
	v_cvt_pk_bf16_f32 v51, v18, v19
	ds_read_b128 v[18:21], v183 offset:1024
	ds_read_b128 v[22:25], v183 offset:1088
	ds_read_b128 v[26:29], v183 offset:1568
	ds_read_b128 v[30:33], v183 offset:1632
	ds_read_b128 v[34:37], v183 offset:2112
	ds_read_b128 v[38:41], v183 offset:2176
	ds_read_b128 v[42:45], v183 offset:2656
	ds_read_b128 v[46:49], v183 offset:2720
	s_waitcnt lgkmcnt(7)
	v_mfma_f32_16x16x32_bf16 v[18:21], v[18:21], v[14:17], 0
	s_waitcnt lgkmcnt(5)
	v_mfma_f32_16x16x32_bf16 v[26:29], v[26:29], v[14:17], 0
	s_waitcnt lgkmcnt(3)
	v_mfma_f32_16x16x32_bf16 v[34:37], v[34:37], v[14:17], 0
	s_waitcnt lgkmcnt(1)
	v_mfma_f32_16x16x32_bf16 v[14:17], v[42:45], v[14:17], 0
	v_mfma_f32_16x16x32_bf16 v[18:21], v[22:25], v[10:13], v[18:21]
	v_mfma_f32_16x16x32_bf16 v[22:25], v[30:33], v[10:13], v[26:29]
	v_mfma_f32_16x16x32_bf16 v[26:29], v[38:41], v[10:13], v[34:37]
	s_waitcnt lgkmcnt(0)
	v_mfma_f32_16x16x32_bf16 v[10:13], v[46:49], v[10:13], v[14:17]
	s_nop 2
	ds_read_b128 v[14:17], v183 offset:1152
	ds_read_b128 v[30:33], v183 offset:1216
	s_waitcnt lgkmcnt(1)
	v_mfma_f32_16x16x32_bf16 v[14:17], v[14:17], v[6:9], v[18:21]
	s_nop 2
	ds_read_b128 v[18:21], v183 offset:1696
	ds_read_b128 v[34:37], v183 offset:1760
	s_waitcnt lgkmcnt(1)
	v_mfma_f32_16x16x32_bf16 v[18:21], v[18:21], v[6:9], v[22:25]
	s_nop 2
	ds_read_b128 v[22:25], v183 offset:2240
	ds_read_b128 v[38:41], v183 offset:2304
	s_waitcnt lgkmcnt(1)
	v_mfma_f32_16x16x32_bf16 v[22:25], v[22:25], v[6:9], v[26:29]
	s_nop 2
	ds_read_b128 v[26:29], v183 offset:2784
	ds_read_b128 v[42:45], v183 offset:2848
	global_store_dwordx2 v[90:91], v[50:51], off offset:96
	s_waitcnt lgkmcnt(1)
	v_mfma_f32_16x16x32_bf16 v[6:9], v[26:29], v[6:9], v[10:13]
	v_mfma_f32_16x16x32_bf16 v[10:13], v[30:33], v[2:5], v[14:17]
	v_mfma_f32_16x16x32_bf16 v[14:17], v[34:37], v[2:5], v[18:21]
	v_mfma_f32_16x16x32_bf16 v[18:21], v[38:41], v[2:5], v[22:25]
	s_waitcnt lgkmcnt(0)
	v_mfma_f32_16x16x32_bf16 v[2:5], v[42:45], v[2:5], v[6:9]
	s_waitcnt vmcnt(31)
	s_nop 1
	v_lshlrev_b32_e32 v6, 16, v92
	v_add_f32_e32 v7, v157, v10
	v_mul_f32_e32 v6, v7, v6
	v_and_b32_e32 v7, 0xffff0000, v92
	v_add_f32_e32 v8, v157, v11
	v_mul_f32_e32 v7, v8, v7
	v_cvt_pk_bf16_f32 v6, v6, v7
	v_lshlrev_b32_e32 v7, 16, v93
	v_add_f32_e32 v8, v157, v12
	v_mul_f32_e32 v7, v8, v7
	v_and_b32_e32 v8, 0xffff0000, v93
	v_add_f32_e32 v9, v157, v13
	v_mul_f32_e32 v8, v9, v8
	v_cvt_pk_bf16_f32 v7, v7, v8
	global_store_dwordx2 v[82:83], v[6:7], off
	s_waitcnt vmcnt(31)
	v_lshlrev_b32_e32 v6, 16, v88
	v_add_f32_e32 v7, v157, v14
	v_mul_f32_e32 v6, v7, v6
	v_and_b32_e32 v7, 0xffff0000, v88
	v_add_f32_e32 v8, v157, v15
	v_mul_f32_e32 v7, v8, v7
	v_cvt_pk_bf16_f32 v6, v6, v7
	v_lshlrev_b32_e32 v7, 16, v89
	v_add_f32_e32 v8, v157, v16
	v_mul_f32_e32 v7, v8, v7
	v_and_b32_e32 v8, 0xffff0000, v89
	v_add_f32_e32 v9, v157, v17
	v_mul_f32_e32 v8, v9, v8
	v_cvt_pk_bf16_f32 v7, v7, v8
	global_store_dwordx2 v[82:83], v[6:7], off offset:32
	s_waitcnt vmcnt(31)
	v_lshlrev_b32_e32 v6, 16, v86
	v_add_f32_e32 v7, v157, v18
	v_mul_f32_e32 v6, v7, v6
	v_and_b32_e32 v7, 0xffff0000, v86
	v_add_f32_e32 v8, v157, v19
	v_mul_f32_e32 v7, v8, v7
	v_cvt_pk_bf16_f32 v6, v6, v7
	v_lshlrev_b32_e32 v7, 16, v87
	v_add_f32_e32 v8, v157, v20
	v_mul_f32_e32 v7, v8, v7
	v_and_b32_e32 v8, 0xffff0000, v87
	v_add_f32_e32 v9, v157, v21
	v_mul_f32_e32 v8, v9, v8
	v_cvt_pk_bf16_f32 v7, v7, v8
	global_store_dwordx2 v[82:83], v[6:7], off offset:64
	s_waitcnt vmcnt(31)
	v_lshlrev_b32_e32 v6, 16, v84
	v_add_f32_e32 v2, v157, v2
	v_mul_f32_e32 v2, v2, v6
	v_and_b32_e32 v6, 0xffff0000, v84
	v_add_f32_e32 v3, v157, v3
	v_mul_f32_e32 v3, v3, v6
	v_cvt_pk_bf16_f32 v2, v2, v3
	v_lshlrev_b32_e32 v3, 16, v85
	v_add_f32_e32 v4, v157, v4
	v_mul_f32_e32 v3, v4, v3
	v_and_b32_e32 v4, 0xffff0000, v85
	v_add_f32_e32 v5, v157, v5
	v_mul_f32_e32 v4, v5, v4
	v_cvt_pk_bf16_f32 v3, v3, v4
	global_store_dwordx2 v[82:83], v[2:3], off offset:96
	s_barrier

; __device__ __forceinline__ unsigned cvt_pk_bf16(float lo, float hi) { unsigned r; asm volatile("v_cvt_pk_bf16_f32 %0, %1, %2" : "=v"(r) : "v"(lo), "v"(hi)); return r; }
; __device__ __forceinline__ float bf_lo(unsigned w) { return __uint_as_float(w << 16); }
; __device__ __forceinline__ float bf_hi(unsigned w) { return __uint_as_float(w & 0xffff0000u); }
; #define LAS __attribute__((address_space(3)))
; __device__ __forceinline__ void sgu_unit(LAS unsigned char* lds, bf16* U, const bf16* VS, const float* SGS, const float* lnw, const float* lnb, const v4u* WF, const float* bsl, int unit, int tid) {
;     ...
;     {
;         const int c8 = lane & 7, rp = lane >> 3, col = colbase + 8 * c8;
;         v4u sl[8][2];
; #pragma unroll
;         for (int i = 0; i < 8; ++i) { const int s0 = 2 * (rp + 8 * i); sl[i][0] = *(const v4u*)(VS + (size_t)(r0 + s0) * 1024 + col); sl[i][1] = *(const v4u*)(VS + (size_t)(r0 + s0 + 1) * 1024 + col); }
;         const f32x4 lw0 = *(const f32x4*)(lnw + col), lw1 = *(const f32x4*)(lnw + col + 4), lb0 = *(const f32x4*)(lnb + col), lb1 = *(const f32x4*)(lnb + col + 4);
;         const float lw[8] = {lw0.x, lw0.y, lw0.z, lw0.w, lw1.x, lw1.y, lw1.z, lw1.w}, lb[8] = {lb0.x, lb0.y, lb0.z, lb0.w, lb1.x, lb1.y, lb1.z, lb1.w};
;         __syncthreads();
;         LAS unsigned char* wbase = vt + c8 * SGU_VP + rp * 4;
; #pragma unroll
;         for (int i = 0; i < 8; ++i) {
;             const f32x4 st4 = *(const LAS f32x4*)(stat + 4 * (rp + 8 * i));
;             const v4u w0 = sl[i][0], w1 = sl[i][1];
;             const unsigned A0[4] = {w0.x, w0.y, w0.z, w0.w}, A1[4] = {w1.x, w1.y, w1.z, w1.w};
; #pragma unroll
;             for (int e = 0; e < 8; ++e) { typedef float f32x2p __attribute__((ext_vector_type(2)));
;                 f32x2p v; v.x = (e & 1) ? bf_hi(A0[e >> 1]) : bf_lo(A0[e >> 1]); v.y = (e & 1) ? bf_hi(A1[e >> 1]) : bf_lo(A1[e >> 1]);
;                 const f32x2p mn = {st4.x, st4.z}, rs = {st4.y, st4.w};
;                 const f32x2p o = ((v - mn) * rs) * lw[e] + lb[e];
;                 *(LAS unsigned*)(wbase + e * 8 * SGU_VP + i * 32) = cvt_pk_bf16(o.x, o.y); }
;         }
;     }
.LBB0_1401:
	s_or_b64 exec, exec, s[16:17]
	v_mov_b32_e32 v122, v214
	v_mov_b32_e32 v123, v215
	v_mov_b32_e32 v124, v216
	v_mov_b32_e32 v125, v217
	v_mov_b32_e32 v126, v218
	v_mov_b32_e32 v127, v219
	v_mov_b32_e32 v128, v220
	v_mov_b32_e32 v129, v221
	v_mov_b32_e32 v114, v222
	v_mov_b32_e32 v115, v223
	v_mov_b32_e32 v116, v224
	v_mov_b32_e32 v117, v225
	v_mov_b32_e32 v118, v226
	v_mov_b32_e32 v119, v227
	v_mov_b32_e32 v120, v228
	v_mov_b32_e32 v121, v229
	v_mov_b32_e32 v106, v230
	v_mov_b32_e32 v107, v231
	v_mov_b32_e32 v108, v232
	v_mov_b32_e32 v109, v233
	v_mov_b32_e32 v110, v234
	v_mov_b32_e32 v111, v235
	v_mov_b32_e32 v112, v236
	v_mov_b32_e32 v113, v237
	v_or_b32_e32 v158, v82, v168
	v_or_b32_e32 v82, v158, v170
	v_lshl_or_b32 v84, s18, 11, v180
	v_mov_b32_e32 v85, v147
	v_ashrrev_i32_e32 v83, 31, v82
	v_lshl_add_u64 v[84:85], s[38:39], 0, v[84:85]
	v_lshl_add_u64 v[90:91], v[82:83], 1, v[84:85]
	v_lshlrev_b64 v[82:83], 2, v[82:83]
	v_lshl_add_u64 v[84:85], s[30:31], 0, v[82:83]
	v_lshl_add_u64 v[86:87], s[40:41], 0, v[82:83]
	global_load_dwordx4 v[98:101], v[86:87], off
	global_load_dwordx4 v[102:105], v[84:85], off
	s_nop 0
	global_load_dwordx4 v[82:85], v[84:85], off offset:16
	s_nop 0
	global_load_dwordx4 v[86:89], v[86:87], off offset:16
	v_add_co_u32_e32 v92, vcc, 0x8000, v90
	s_mov_b64 s[16:17], 0
	s_nop 0
	v_addc_co_u32_e32 v93, vcc, 0, v91, vcc
	v_add_co_u32_e32 v94, vcc, 0x10000, v90
	s_waitcnt vmcnt(7)
	v_and_b32_e32 v220, 0xffff0000, v198
	v_addc_co_u32_e32 v95, vcc, 0, v91, vcc
	v_add_co_u32_e32 v92, vcc, 0x18000, v90
	s_waitcnt vmcnt(8)
	v_and_b32_e32 v221, 0xffff0000, v202
	v_addc_co_u32_e32 v93, vcc, 0, v91, vcc
	v_add_co_u32_e32 v94, vcc, 0x20000, v90
	v_addc_co_u32_e32 v95, vcc, 0, v91, vcc
	v_add_co_u32_e32 v92, vcc, 0x28000, v90
	v_addc_co_u32_e32 v93, vcc, 0, v91, vcc
	v_add_co_u32_e32 v94, vcc, 0x30000, v90
	v_addc_co_u32_e32 v95, vcc, 0, v91, vcc
	v_add_co_u32_e32 v96, vcc, 0x38000, v90
	v_addc_co_u32_e32 v97, vcc, 0, v91, vcc
	v_mov_b32_e32 v90, v248
	v_mov_b32_e32 v91, v249
	v_mov_b32_e32 v92, v250
	v_mov_b32_e32 v93, v251
	s_nop 0
	v_mov_b32_e32 v94, v252
	v_mov_b32_e32 v95, v253
	v_mov_b32_e32 v96, v254
	v_mov_b32_e32 v97, v255
	s_waitcnt lgkmcnt(0)
	s_barrier
	ds_read_b128 v[214:217], v181
	v_lshlrev_b32_e32 v222, 16, v199
	v_lshlrev_b32_e32 v223, 16, v203
	s_waitcnt vmcnt(2)
	v_mov_b32_e32 v160, v105
	v_mov_b32_e32 v162, v101
	s_waitcnt lgkmcnt(0)
	v_mov_b32_e32 v218, v214
	v_mov_b32_e32 v219, v216
	v_mov_b32_e32 v216, v215
	v_lshlrev_b32_e32 v214, 16, v198
	v_lshlrev_b32_e32 v215, 16, v202
	v_pk_add_f32 v[214:215], v[214:215], v[218:219] neg_lo:[0,1] neg_hi:[0,1]
	v_and_b32_e32 v198, 0xffff0000, v199
	v_and_b32_e32 v199, 0xffff0000, v203
	v_pk_add_f32 v[220:221], v[220:221], v[218:219] neg_lo:[0,1] neg_hi:[0,1]
	v_pk_mul_f32 v[214:215], v[216:217], v[214:215]
	v_pk_add_f32 v[198:199], v[198:199], v[218:219] neg_lo:[0,1] neg_hi:[0,1]
	v_pk_add_f32 v[222:223], v[222:223], v[218:219] neg_lo:[0,1] neg_hi:[0,1]
	v_pk_mul_f32 v[220:221], v[216:217], v[220:221]
	v_pk_fma_f32 v[214:215], v[102:103], v[214:215], v[98:99] op_sel_hi:[0,1,0]
	v_cvt_pk_bf16_f32 v159, v214, v215
	v_pk_mul_f32 v[198:199], v[216:217], v[198:199]
	v_pk_mul_f32 v[222:223], v[216:217], v[222:223]
	v_pk_fma_f32 v[220:221], v[102:103], v[220:221], v[98:99] op_sel:[1,0,1]
	ds_write_b32 v177, v159 offset:1024
	v_cvt_pk_bf16_f32 v159, v220, v221
	v_pk_fma_f32 v[198:199], v[160:161], v[198:199], v[162:163] op_sel_hi:[0,1,0]
	v_pk_fma_f32 v[222:223], v[104:105], v[222:223], v[100:101] op_sel_hi:[0,1,0]
	ds_write_b32 v177, v159 offset:3200
	v_cvt_pk_bf16_f32 v159, v222, v223
	ds_write_b32 v177, v159 offset:5376
	v_cvt_pk_bf16_f32 v101, v198, v199
	v_lshlrev_b32_e32 v198, 16, v200
	v_lshlrev_b32_e32 v199, 16, v204
	v_pk_add_f32 v[198:199], v[198:199], v[218:219] neg_lo:[0,1] neg_hi:[0,1]
	ds_write_b32 v177, v101 offset:7552
	v_pk_mul_f32 v[198:199], v[216:217], v[198:199]
	s_waitcnt vmcnt(1)
	v_mov_b32_e32 v164, v85
	s_waitcnt vmcnt(0)
	v_pk_fma_f32 v[198:199], v[82:83], v[198:199], v[86:87] op_sel_hi:[0,1,0]
	v_cvt_pk_bf16_f32 v101, v198, v199
	v_and_b32_e32 v198, 0xffff0000, v200
	v_and_b32_e32 v199, 0xffff0000, v204
	v_pk_add_f32 v[198:199], v[198:199], v[218:219] neg_lo:[0,1] neg_hi:[0,1]
	ds_write_b32 v177, v101 offset:9728
	v_pk_mul_f32 v[198:199], v[216:217], v[198:199]
	v_mov_b32_e32 v166, v89
	v_pk_fma_f32 v[198:199], v[82:83], v[198:199], v[86:87] op_sel:[1,0,1]
	v_ashrrev_i32_e32 v159, 31, v158
	v_cvt_pk_bf16_f32 v101, v198, v199
	v_lshlrev_b32_e32 v198, 16, v201
	v_lshlrev_b32_e32 v199, 16, v205
	v_pk_add_f32 v[198:199], v[198:199], v[218:219] neg_lo:[0,1] neg_hi:[0,1]
	ds_write_b32 v177, v101 offset:11904
	v_pk_mul_f32 v[198:199], v[216:217], v[198:199]
	s_nop 0
	v_pk_fma_f32 v[198:199], v[84:85], v[198:199], v[88:89] op_sel_hi:[0,1,0]
	v_cvt_pk_bf16_f32 v101, v198, v199
	v_and_b32_e32 v198, 0xffff0000, v201
	v_and_b32_e32 v199, 0xffff0000, v205
	v_pk_add_f32 v[198:199], v[198:199], v[218:219] neg_lo:[0,1] neg_hi:[0,1]
	ds_write_b32 v177, v101 offset:14080
	v_pk_mul_f32 v[198:199], v[216:217], v[198:199]
	s_nop 0
	v_pk_fma_f32 v[198:199], v[164:165], v[198:199], v[166:167] op_sel_hi:[0,1,0]
	v_cvt_pk_bf16_f32 v85, v198, v199
	ds_write_b32 v177, v85 offset:16256
	ds_read_b128 v[198:201], v181 offset:128
	s_waitcnt lgkmcnt(0)
	v_mov_b32_e32 v202, v198
	v_mov_b32_e32 v203, v200
	v_mov_b32_e32 v200, v199
	s_waitcnt vmcnt(13)
	v_lshlrev_b32_e32 v198, 16, v206
	s_waitcnt vmcnt(12)
; __device__ __forceinline__ unsigned cvt_pk_bf16(float lo, float hi) { unsigned r; asm volatile("v_cvt_pk_bf16_f32 %0, %1, %2" : "=v"(r) : "v"(lo), "v"(hi)); return r; }
; __device__ __forceinline__ float bf_lo(unsigned w) { return __uint_as_float(w << 16); }
; __device__ __forceinline__ float bf_hi(unsigned w) { return __uint_as_float(w & 0xffff0000u); }
; #define LAS __attribute__((address_space(3)))
; __device__ __forceinline__ void sgu_unit(LAS unsigned char* lds, bf16* U, const bf16* VS, const float* SGS, const float* lnw, const float* lnb, const v4u* WF, const float* bsl, int unit, int tid) {
;     ...
;         LAS unsigned char* wbase = vt + c8 * SGU_VP + rp * 4;
; #pragma unroll
;         for (int i = 0; i < 8; ++i) {
;             const f32x4 st4 = *(const LAS f32x4*)(stat + 4 * (rp + 8 * i));
;             const v4u w0 = sl[i][0], w1 = sl[i][1];
;             const unsigned A0[4] = {w0.x, w0.y, w0.z, w0.w}, A1[4] = {w1.x, w1.y, w1.z, w1.w};
; #pragma unroll
;             for (int e = 0; e < 8; ++e) { typedef float f32x2p __attribute__((ext_vector_type(2)));
;                 f32x2p v; v.x = (e & 1) ? bf_hi(A0[e >> 1]) : bf_lo(A0[e >> 1]); v.y = (e & 1) ? bf_hi(A1[e >> 1]) : bf_lo(A1[e >> 1]);
;                 const f32x2p mn = {st4.x, st4.z}, rs = {st4.y, st4.w};
;                 const f32x2p o = ((v - mn) * rs) * lw[e] + lb[e];
;                 *(LAS unsigned*)(wbase + e * 8 * SGU_VP + i * 32) = cvt_pk_bf16(o.x, o.y); }
;         }
;     }
	v_lshlrev_b32_e32 v199, 16, v210
	v_pk_add_f32 v[198:199], v[198:199], v[202:203] neg_lo:[0,1] neg_hi:[0,1]
	s_nop 0
	v_pk_mul_f32 v[198:199], v[200:201], v[198:199]
	s_nop 0
	v_pk_fma_f32 v[198:199], v[102:103], v[198:199], v[98:99] op_sel_hi:[0,1,0]
	v_cvt_pk_bf16_f32 v85, v198, v199
	v_and_b32_e32 v198, 0xffff0000, v206
	v_and_b32_e32 v199, 0xffff0000, v210
	v_pk_add_f32 v[198:199], v[198:199], v[202:203] neg_lo:[0,1] neg_hi:[0,1]
	ds_write_b32 v177, v85 offset:1056
	v_pk_mul_f32 v[198:199], v[200:201], v[198:199]
	s_nop 0
	v_pk_fma_f32 v[198:199], v[102:103], v[198:199], v[98:99] op_sel:[1,0,1]
	s_nop 0
	v_cvt_pk_bf16_f32 v85, v198, v199
	v_lshlrev_b32_e32 v198, 16, v207
	v_lshlrev_b32_e32 v199, 16, v211
	v_pk_add_f32 v[198:199], v[198:199], v[202:203] neg_lo:[0,1] neg_hi:[0,1]
	ds_write_b32 v177, v85 offset:3232
	v_pk_mul_f32 v[198:199], v[200:201], v[198:199]
	s_nop 0
	v_pk_fma_f32 v[198:199], v[104:105], v[198:199], v[100:101] op_sel_hi:[0,1,0]
	v_cvt_pk_bf16_f32 v85, v198, v199
	v_and_b32_e32 v198, 0xffff0000, v207
	v_and_b32_e32 v199, 0xffff0000, v211
	v_pk_add_f32 v[198:199], v[198:199], v[202:203] neg_lo:[0,1] neg_hi:[0,1]
	ds_write_b32 v177, v85 offset:5408
	v_pk_mul_f32 v[198:199], v[200:201], v[198:199]
	s_nop 0
	v_pk_fma_f32 v[198:199], v[160:161], v[198:199], v[162:163] op_sel_hi:[0,1,0]
	v_cvt_pk_bf16_f32 v85, v198, v199
	v_lshlrev_b32_e32 v198, 16, v208
	v_lshlrev_b32_e32 v199, 16, v212
	v_pk_add_f32 v[198:199], v[198:199], v[202:203] neg_lo:[0,1] neg_hi:[0,1]
	ds_write_b32 v177, v85 offset:7584
	v_pk_mul_f32 v[198:199], v[200:201], v[198:199]
	s_nop 0
	v_pk_fma_f32 v[198:199], v[82:83], v[198:199], v[86:87] op_sel_hi:[0,1,0]
	v_cvt_pk_bf16_f32 v85, v198, v199
	v_and_b32_e32 v198, 0xffff0000, v208
	v_and_b32_e32 v199, 0xffff0000, v212
	v_pk_add_f32 v[198:199], v[198:199], v[202:203] neg_lo:[0,1] neg_hi:[0,1]
	ds_write_b32 v177, v85 offset:9760
	v_pk_mul_f32 v[198:199], v[200:201], v[198:199]
	s_nop 0
	v_pk_fma_f32 v[198:199], v[82:83], v[198:199], v[86:87] op_sel:[1,0,1]
	s_nop 0
	v_cvt_pk_bf16_f32 v85, v198, v199
	v_lshlrev_b32_e32 v198, 16, v209
	v_lshlrev_b32_e32 v199, 16, v213
	v_pk_add_f32 v[198:199], v[198:199], v[202:203] neg_lo:[0,1] neg_hi:[0,1]
	ds_write_b32 v177, v85 offset:11936
	v_pk_mul_f32 v[198:199], v[200:201], v[198:199]
	s_nop 0
	v_pk_fma_f32 v[198:199], v[84:85], v[198:199], v[88:89] op_sel_hi:[0,1,0]
	v_cvt_pk_bf16_f32 v85, v198, v199
	v_and_b32_e32 v198, 0xffff0000, v209
	v_and_b32_e32 v199, 0xffff0000, v213
	v_pk_add_f32 v[198:199], v[198:199], v[202:203] neg_lo:[0,1] neg_hi:[0,1]
	ds_write_b32 v177, v85 offset:14112
	v_pk_mul_f32 v[198:199], v[200:201], v[198:199]
	s_nop 0
	v_pk_fma_f32 v[198:199], v[164:165], v[198:199], v[166:167] op_sel_hi:[0,1,0]
	v_cvt_pk_bf16_f32 v85, v198, v199
	ds_write_b32 v177, v85 offset:16288
	ds_read_b128 v[198:201], v181 offset:256
	s_waitcnt lgkmcnt(0)
	v_mov_b32_e32 v202, v198
	v_mov_b32_e32 v203, v200
	v_mov_b32_e32 v200, v199
	s_waitcnt vmcnt(11)
	v_lshlrev_b32_e32 v198, 16, v138
	s_waitcnt vmcnt(10)
	v_lshlrev_b32_e32 v199, 16, v142
	v_pk_add_f32 v[198:199], v[198:199], v[202:203] neg_lo:[0,1] neg_hi:[0,1]
	s_nop 0
	v_pk_mul_f32 v[198:199], v[200:201], v[198:199]
	s_nop 0
	v_pk_fma_f32 v[198:199], v[102:103], v[198:199], v[98:99] op_sel_hi:[0,1,0]
	v_cvt_pk_bf16_f32 v85, v198, v199
	v_and_b32_e32 v198, 0xffff0000, v138
	v_and_b32_e32 v199, 0xffff0000, v142
	v_pk_add_f32 v[198:199], v[198:199], v[202:203] neg_lo:[0,1] neg_hi:[0,1]
	ds_write_b32 v177, v85 offset:1088
	v_pk_mul_f32 v[198:199], v[200:201], v[198:199]
	v_and_b32_e32 v138, 0xffff0000, v139
	v_pk_fma_f32 v[198:199], v[102:103], v[198:199], v[98:99] op_sel:[1,0,1]
	s_nop 0
	v_cvt_pk_bf16_f32 v85, v198, v199
	v_lshlrev_b32_e32 v198, 16, v139
	v_lshlrev_b32_e32 v199, 16, v143
	v_and_b32_e32 v139, 0xffff0000, v143
	v_pk_add_f32 v[198:199], v[198:199], v[202:203] neg_lo:[0,1] neg_hi:[0,1]
	v_pk_add_f32 v[138:139], v[138:139], v[202:203] neg_lo:[0,1] neg_hi:[0,1]
	v_pk_mul_f32 v[198:199], v[200:201], v[198:199]
	v_pk_mul_f32 v[138:139], v[200:201], v[138:139]
	ds_write_b32 v177, v85 offset:3264
	v_pk_fma_f32 v[198:199], v[104:105], v[198:199], v[100:101] op_sel_hi:[0,1,0]
	v_cvt_pk_bf16_f32 v85, v198, v199
	v_pk_fma_f32 v[138:139], v[160:161], v[138:139], v[162:163] op_sel_hi:[0,1,0]
	ds_write_b32 v177, v85 offset:5440
	v_cvt_pk_bf16_f32 v85, v138, v139
	v_lshlrev_b32_e32 v138, 16, v140
	v_lshlrev_b32_e32 v139, 16, v144
	v_pk_add_f32 v[138:139], v[138:139], v[202:203] neg_lo:[0,1] neg_hi:[0,1]
	ds_write_b32 v177, v85 offset:7616
	v_pk_mul_f32 v[138:139], v[200:201], v[138:139]
	s_nop 0
	v_pk_fma_f32 v[138:139], v[82:83], v[138:139], v[86:87] op_sel_hi:[0,1,0]
	v_cvt_pk_bf16_f32 v85, v138, v139
	v_and_b32_e32 v138, 0xffff0000, v140
	v_and_b32_e32 v139, 0xffff0000, v144
	v_pk_add_f32 v[138:139], v[138:139], v[202:203] neg_lo:[0,1] neg_hi:[0,1]
	ds_write_b32 v177, v85 offset:9792
	v_pk_mul_f32 v[138:139], v[200:201], v[138:139]
	s_nop 0
	v_pk_fma_f32 v[138:139], v[82:83], v[138:139], v[86:87] op_sel:[1,0,1]
	s_nop 0
	v_cvt_pk_bf16_f32 v85, v138, v139
	v_lshlrev_b32_e32 v138, 16, v141
	v_lshlrev_b32_e32 v139, 16, v145
	v_pk_add_f32 v[138:139], v[138:139], v[202:203] neg_lo:[0,1] neg_hi:[0,1]
	ds_write_b32 v177, v85 offset:11968
	v_pk_mul_f32 v[138:139], v[200:201], v[138:139]
	s_nop 0
	v_pk_fma_f32 v[138:139], v[84:85], v[138:139], v[88:89] op_sel_hi:[0,1,0]
	v_cvt_pk_bf16_f32 v85, v138, v139
	v_and_b32_e32 v138, 0xffff0000, v141
	v_and_b32_e32 v139, 0xffff0000, v145
	v_pk_add_f32 v[138:139], v[138:139], v[202:203] neg_lo:[0,1] neg_hi:[0,1]
	ds_write_b32 v177, v85 offset:14144
	v_pk_mul_f32 v[138:139], v[200:201], v[138:139]
	s_nop 0
	v_pk_fma_f32 v[138:139], v[164:165], v[138:139], v[166:167] op_sel_hi:[0,1,0]
	v_cvt_pk_bf16_f32 v85, v138, v139
	ds_write_b32 v177, v85 offset:16320
	ds_read_b128 v[138:141], v181 offset:384
	s_waitcnt lgkmcnt(0)
; __device__ __forceinline__ unsigned cvt_pk_bf16(float lo, float hi) { unsigned r; asm volatile("v_cvt_pk_bf16_f32 %0, %1, %2" : "=v"(r) : "v"(lo), "v"(hi)); return r; }
; __device__ __forceinline__ float bf_lo(unsigned w) { return __uint_as_float(w << 16); }
; __device__ __forceinline__ float bf_hi(unsigned w) { return __uint_as_float(w & 0xffff0000u); }
; #define LAS __attribute__((address_space(3)))
; __device__ __forceinline__ void sgu_unit(LAS unsigned char* lds, bf16* U, const bf16* VS, const float* SGS, const float* lnw, const float* lnb, const v4u* WF, const float* bsl, int unit, int tid) {
;     ...
;         LAS unsigned char* wbase = vt + c8 * SGU_VP + rp * 4;
; #pragma unroll
;         for (int i = 0; i < 8; ++i) {
;             const f32x4 st4 = *(const LAS f32x4*)(stat + 4 * (rp + 8 * i));
;             const v4u w0 = sl[i][0], w1 = sl[i][1];
;             const unsigned A0[4] = {w0.x, w0.y, w0.z, w0.w}, A1[4] = {w1.x, w1.y, w1.z, w1.w};
; #pragma unroll
;             for (int e = 0; e < 8; ++e) { typedef float f32x2p __attribute__((ext_vector_type(2)));
;                 f32x2p v; v.x = (e & 1) ? bf_hi(A0[e >> 1]) : bf_lo(A0[e >> 1]); v.y = (e & 1) ? bf_hi(A1[e >> 1]) : bf_lo(A1[e >> 1]);
;                 const f32x2p mn = {st4.x, st4.z}, rs = {st4.y, st4.w};
;                 const f32x2p o = ((v - mn) * rs) * lw[e] + lb[e];
;                 *(LAS unsigned*)(wbase + e * 8 * SGU_VP + i * 32) = cvt_pk_bf16(o.x, o.y); }
;         }
;     }
	v_mov_b32_e32 v142, v138
	v_mov_b32_e32 v143, v140
	v_mov_b32_e32 v140, v139
	s_waitcnt vmcnt(9)
	v_lshlrev_b32_e32 v138, 16, v130
	s_waitcnt vmcnt(8)
	v_lshlrev_b32_e32 v139, 16, v134
	v_pk_add_f32 v[138:139], v[138:139], v[142:143] neg_lo:[0,1] neg_hi:[0,1]
	s_nop 0
	v_pk_mul_f32 v[138:139], v[140:141], v[138:139]
	s_nop 0
	v_pk_fma_f32 v[138:139], v[102:103], v[138:139], v[98:99] op_sel_hi:[0,1,0]
	v_cvt_pk_bf16_f32 v85, v138, v139
	v_and_b32_e32 v138, 0xffff0000, v130
	v_and_b32_e32 v139, 0xffff0000, v134
	v_pk_add_f32 v[138:139], v[138:139], v[142:143] neg_lo:[0,1] neg_hi:[0,1]
	ds_write_b32 v177, v85 offset:1120
	v_pk_mul_f32 v[138:139], v[140:141], v[138:139]
	v_and_b32_e32 v130, 0xffff0000, v131
	v_pk_fma_f32 v[138:139], v[102:103], v[138:139], v[98:99] op_sel:[1,0,1]
	s_nop 0
	v_cvt_pk_bf16_f32 v85, v138, v139
	v_lshlrev_b32_e32 v138, 16, v131
	v_lshlrev_b32_e32 v139, 16, v135
	v_and_b32_e32 v131, 0xffff0000, v135
	v_pk_add_f32 v[138:139], v[138:139], v[142:143] neg_lo:[0,1] neg_hi:[0,1]
	v_pk_add_f32 v[130:131], v[130:131], v[142:143] neg_lo:[0,1] neg_hi:[0,1]
	v_pk_mul_f32 v[138:139], v[140:141], v[138:139]
	v_pk_mul_f32 v[130:131], v[140:141], v[130:131]
	ds_write_b32 v177, v85 offset:3296
	v_pk_fma_f32 v[138:139], v[104:105], v[138:139], v[100:101] op_sel_hi:[0,1,0]
	v_cvt_pk_bf16_f32 v85, v138, v139
	v_pk_fma_f32 v[130:131], v[160:161], v[130:131], v[162:163] op_sel_hi:[0,1,0]
	ds_write_b32 v177, v85 offset:5472
	v_cvt_pk_bf16_f32 v85, v130, v131
	v_lshlrev_b32_e32 v130, 16, v132
	v_lshlrev_b32_e32 v131, 16, v136
	v_pk_add_f32 v[130:131], v[130:131], v[142:143] neg_lo:[0,1] neg_hi:[0,1]
	ds_write_b32 v177, v85 offset:7648
	v_pk_mul_f32 v[130:131], v[140:141], v[130:131]
	s_nop 0
	v_pk_fma_f32 v[130:131], v[82:83], v[130:131], v[86:87] op_sel_hi:[0,1,0]
	v_cvt_pk_bf16_f32 v85, v130, v131
	v_and_b32_e32 v130, 0xffff0000, v132
	v_and_b32_e32 v131, 0xffff0000, v136
	v_pk_add_f32 v[130:131], v[130:131], v[142:143] neg_lo:[0,1] neg_hi:[0,1]
	ds_write_b32 v177, v85 offset:9824
	v_pk_mul_f32 v[130:131], v[140:141], v[130:131]
	s_nop 0
	v_pk_fma_f32 v[130:131], v[82:83], v[130:131], v[86:87] op_sel:[1,0,1]
	s_nop 0
	v_cvt_pk_bf16_f32 v85, v130, v131
	v_lshlrev_b32_e32 v130, 16, v133
	v_lshlrev_b32_e32 v131, 16, v137
	v_pk_add_f32 v[130:131], v[130:131], v[142:143] neg_lo:[0,1] neg_hi:[0,1]
	ds_write_b32 v177, v85 offset:12000
	v_pk_mul_f32 v[130:131], v[140:141], v[130:131]
	s_nop 0
	v_pk_fma_f32 v[130:131], v[84:85], v[130:131], v[88:89] op_sel_hi:[0,1,0]
	v_cvt_pk_bf16_f32 v85, v130, v131
	v_and_b32_e32 v130, 0xffff0000, v133
	v_and_b32_e32 v131, 0xffff0000, v137
	v_pk_add_f32 v[130:131], v[130:131], v[142:143] neg_lo:[0,1] neg_hi:[0,1]
	ds_write_b32 v177, v85 offset:14176
	v_pk_mul_f32 v[130:131], v[140:141], v[130:131]
	s_nop 0
	v_pk_fma_f32 v[130:131], v[164:165], v[130:131], v[166:167] op_sel_hi:[0,1,0]
	v_cvt_pk_bf16_f32 v85, v130, v131
	ds_write_b32 v177, v85 offset:16352
	ds_read_b128 v[130:133], v181 offset:512
	s_waitcnt lgkmcnt(0)
	v_mov_b32_e32 v134, v130
	v_mov_b32_e32 v135, v132
	v_mov_b32_e32 v132, v131
	s_waitcnt vmcnt(7)
	v_lshlrev_b32_e32 v130, 16, v122
	s_waitcnt vmcnt(6)
	v_lshlrev_b32_e32 v131, 16, v126
	v_pk_add_f32 v[130:131], v[130:131], v[134:135] neg_lo:[0,1] neg_hi:[0,1]
	s_nop 0
	v_pk_mul_f32 v[130:131], v[132:133], v[130:131]
	s_nop 0
	v_pk_fma_f32 v[130:131], v[102:103], v[130:131], v[98:99] op_sel_hi:[0,1,0]
	v_cvt_pk_bf16_f32 v85, v130, v131
	v_and_b32_e32 v130, 0xffff0000, v122
	v_and_b32_e32 v131, 0xffff0000, v126
	v_pk_add_f32 v[130:131], v[130:131], v[134:135] neg_lo:[0,1] neg_hi:[0,1]
	ds_write_b32 v177, v85 offset:1152
	v_pk_mul_f32 v[130:131], v[132:133], v[130:131]
	v_and_b32_e32 v122, 0xffff0000, v123
	v_pk_fma_f32 v[130:131], v[102:103], v[130:131], v[98:99] op_sel:[1,0,1]
	s_nop 0
	v_cvt_pk_bf16_f32 v85, v130, v131
	v_lshlrev_b32_e32 v130, 16, v123
	v_lshlrev_b32_e32 v131, 16, v127
	v_and_b32_e32 v123, 0xffff0000, v127
	v_pk_add_f32 v[130:131], v[130:131], v[134:135] neg_lo:[0,1] neg_hi:[0,1]
	v_pk_add_f32 v[122:123], v[122:123], v[134:135] neg_lo:[0,1] neg_hi:[0,1]
	v_pk_mul_f32 v[130:131], v[132:133], v[130:131]
	v_pk_mul_f32 v[122:123], v[132:133], v[122:123]
	ds_write_b32 v177, v85 offset:3328
	v_pk_fma_f32 v[130:131], v[104:105], v[130:131], v[100:101] op_sel_hi:[0,1,0]
	v_cvt_pk_bf16_f32 v85, v130, v131
	v_pk_fma_f32 v[122:123], v[160:161], v[122:123], v[162:163] op_sel_hi:[0,1,0]
	ds_write_b32 v177, v85 offset:5504
	v_cvt_pk_bf16_f32 v85, v122, v123
	v_lshlrev_b32_e32 v122, 16, v124
	v_lshlrev_b32_e32 v123, 16, v128
	v_pk_add_f32 v[122:123], v[122:123], v[134:135] neg_lo:[0,1] neg_hi:[0,1]
	ds_write_b32 v177, v85 offset:7680
	v_pk_mul_f32 v[122:123], v[132:133], v[122:123]
	s_nop 0
	v_pk_fma_f32 v[122:123], v[82:83], v[122:123], v[86:87] op_sel_hi:[0,1,0]
	v_cvt_pk_bf16_f32 v85, v122, v123
	v_and_b32_e32 v122, 0xffff0000, v124
	v_and_b32_e32 v123, 0xffff0000, v128
	v_pk_add_f32 v[122:123], v[122:123], v[134:135] neg_lo:[0,1] neg_hi:[0,1]
	ds_write_b32 v177, v85 offset:9856
	v_pk_mul_f32 v[122:123], v[132:133], v[122:123]
	s_nop 0
	v_pk_fma_f32 v[122:123], v[82:83], v[122:123], v[86:87] op_sel:[1,0,1]
	s_nop 0
	v_cvt_pk_bf16_f32 v85, v122, v123
	v_lshlrev_b32_e32 v122, 16, v125
	v_lshlrev_b32_e32 v123, 16, v129
	v_pk_add_f32 v[122:123], v[122:123], v[134:135] neg_lo:[0,1] neg_hi:[0,1]
	ds_write_b32 v177, v85 offset:12032
	v_pk_mul_f32 v[122:123], v[132:133], v[122:123]
	s_nop 0
	v_pk_fma_f32 v[122:123], v[84:85], v[122:123], v[88:89] op_sel_hi:[0,1,0]
	v_cvt_pk_bf16_f32 v85, v122, v123
	v_and_b32_e32 v122, 0xffff0000, v125
	v_and_b32_e32 v123, 0xffff0000, v129
	v_pk_add_f32 v[122:123], v[122:123], v[134:135] neg_lo:[0,1] neg_hi:[0,1]
	ds_write_b32 v177, v85 offset:14208
	v_pk_mul_f32 v[122:123], v[132:133], v[122:123]
	s_nop 0
	v_pk_fma_f32 v[122:123], v[164:165], v[122:123], v[166:167] op_sel_hi:[0,1,0]
	v_cvt_pk_bf16_f32 v85, v122, v123
	ds_write_b32 v177, v85 offset:16384
	ds_read_b128 v[122:125], v181 offset:640
	s_waitcnt lgkmcnt(0)
; __device__ __forceinline__ unsigned cvt_pk_bf16(float lo, float hi) { unsigned r; asm volatile("v_cvt_pk_bf16_f32 %0, %1, %2" : "=v"(r) : "v"(lo), "v"(hi)); return r; }
; __device__ __forceinline__ float bf_lo(unsigned w) { return __uint_as_float(w << 16); }
; __device__ __forceinline__ float bf_hi(unsigned w) { return __uint_as_float(w & 0xffff0000u); }
; #define LAS __attribute__((address_space(3)))
; __device__ __forceinline__ void sgu_unit(LAS unsigned char* lds, bf16* U, const bf16* VS, const float* SGS, const float* lnw, const float* lnb, const v4u* WF, const float* bsl, int unit, int tid) {
;     ...
;         LAS unsigned char* wbase = vt + c8 * SGU_VP + rp * 4;
; #pragma unroll
;         for (int i = 0; i < 8; ++i) {
;             const f32x4 st4 = *(const LAS f32x4*)(stat + 4 * (rp + 8 * i));
;             const v4u w0 = sl[i][0], w1 = sl[i][1];
;             const unsigned A0[4] = {w0.x, w0.y, w0.z, w0.w}, A1[4] = {w1.x, w1.y, w1.z, w1.w};
; #pragma unroll
;             for (int e = 0; e < 8; ++e) { typedef float f32x2p __attribute__((ext_vector_type(2)));
;                 f32x2p v; v.x = (e & 1) ? bf_hi(A0[e >> 1]) : bf_lo(A0[e >> 1]); v.y = (e & 1) ? bf_hi(A1[e >> 1]) : bf_lo(A1[e >> 1]);
;                 const f32x2p mn = {st4.x, st4.z}, rs = {st4.y, st4.w};
;                 const f32x2p o = ((v - mn) * rs) * lw[e] + lb[e];
;                 *(LAS unsigned*)(wbase + e * 8 * SGU_VP + i * 32) = cvt_pk_bf16(o.x, o.y); }
;         }
;     }
	v_mov_b32_e32 v126, v122
	v_mov_b32_e32 v127, v124
	v_mov_b32_e32 v124, v123
	s_waitcnt vmcnt(5)
	v_lshlrev_b32_e32 v122, 16, v114
	s_waitcnt vmcnt(4)
	v_lshlrev_b32_e32 v123, 16, v118
	v_pk_add_f32 v[122:123], v[122:123], v[126:127] neg_lo:[0,1] neg_hi:[0,1]
	s_nop 0
	v_pk_mul_f32 v[122:123], v[124:125], v[122:123]
	s_nop 0
	v_pk_fma_f32 v[122:123], v[102:103], v[122:123], v[98:99] op_sel_hi:[0,1,0]
	v_cvt_pk_bf16_f32 v85, v122, v123
	v_and_b32_e32 v122, 0xffff0000, v114
	v_and_b32_e32 v123, 0xffff0000, v118
	v_pk_add_f32 v[122:123], v[122:123], v[126:127] neg_lo:[0,1] neg_hi:[0,1]
	ds_write_b32 v177, v85 offset:1184
	v_pk_mul_f32 v[122:123], v[124:125], v[122:123]
	v_and_b32_e32 v114, 0xffff0000, v115
	v_pk_fma_f32 v[122:123], v[102:103], v[122:123], v[98:99] op_sel:[1,0,1]
	s_nop 0
	v_cvt_pk_bf16_f32 v85, v122, v123
	v_lshlrev_b32_e32 v122, 16, v115
	v_lshlrev_b32_e32 v123, 16, v119
	v_and_b32_e32 v115, 0xffff0000, v119
	v_pk_add_f32 v[122:123], v[122:123], v[126:127] neg_lo:[0,1] neg_hi:[0,1]
	v_pk_add_f32 v[114:115], v[114:115], v[126:127] neg_lo:[0,1] neg_hi:[0,1]
	v_pk_mul_f32 v[122:123], v[124:125], v[122:123]
	v_pk_mul_f32 v[114:115], v[124:125], v[114:115]
	ds_write_b32 v177, v85 offset:3360
	v_pk_fma_f32 v[122:123], v[104:105], v[122:123], v[100:101] op_sel_hi:[0,1,0]
	v_cvt_pk_bf16_f32 v85, v122, v123
	v_pk_fma_f32 v[114:115], v[160:161], v[114:115], v[162:163] op_sel_hi:[0,1,0]
	ds_write_b32 v177, v85 offset:5536
	v_cvt_pk_bf16_f32 v85, v114, v115
	v_lshlrev_b32_e32 v114, 16, v116
	v_lshlrev_b32_e32 v115, 16, v120
	v_pk_add_f32 v[114:115], v[114:115], v[126:127] neg_lo:[0,1] neg_hi:[0,1]
	ds_write_b32 v177, v85 offset:7712
	v_pk_mul_f32 v[114:115], v[124:125], v[114:115]
	s_nop 0
	v_pk_fma_f32 v[114:115], v[82:83], v[114:115], v[86:87] op_sel_hi:[0,1,0]
	v_cvt_pk_bf16_f32 v85, v114, v115
	v_and_b32_e32 v114, 0xffff0000, v116
	v_and_b32_e32 v115, 0xffff0000, v120
	v_pk_add_f32 v[114:115], v[114:115], v[126:127] neg_lo:[0,1] neg_hi:[0,1]
	ds_write_b32 v177, v85 offset:9888
	v_pk_mul_f32 v[114:115], v[124:125], v[114:115]
	s_nop 0
	v_pk_fma_f32 v[114:115], v[82:83], v[114:115], v[86:87] op_sel:[1,0,1]
	s_nop 0
	v_cvt_pk_bf16_f32 v85, v114, v115
	v_lshlrev_b32_e32 v114, 16, v117
	v_lshlrev_b32_e32 v115, 16, v121
	v_pk_add_f32 v[114:115], v[114:115], v[126:127] neg_lo:[0,1] neg_hi:[0,1]
	ds_write_b32 v177, v85 offset:12064
	v_pk_mul_f32 v[114:115], v[124:125], v[114:115]
	s_nop 0
	v_pk_fma_f32 v[114:115], v[84:85], v[114:115], v[88:89] op_sel_hi:[0,1,0]
	v_cvt_pk_bf16_f32 v85, v114, v115
	v_and_b32_e32 v114, 0xffff0000, v117
	v_and_b32_e32 v115, 0xffff0000, v121
	v_pk_add_f32 v[114:115], v[114:115], v[126:127] neg_lo:[0,1] neg_hi:[0,1]
	ds_write_b32 v177, v85 offset:14240
	v_pk_mul_f32 v[114:115], v[124:125], v[114:115]
	s_nop 0
	v_pk_fma_f32 v[114:115], v[164:165], v[114:115], v[166:167] op_sel_hi:[0,1,0]
	v_cvt_pk_bf16_f32 v85, v114, v115
	ds_write_b32 v177, v85 offset:16416
	ds_read_b128 v[114:117], v181 offset:768
	s_waitcnt lgkmcnt(0)
	v_mov_b32_e32 v118, v114
	v_mov_b32_e32 v119, v116
	v_mov_b32_e32 v116, v115
	s_waitcnt vmcnt(3)
	v_lshlrev_b32_e32 v114, 16, v106
	s_waitcnt vmcnt(2)
	v_lshlrev_b32_e32 v115, 16, v110
	v_pk_add_f32 v[114:115], v[114:115], v[118:119] neg_lo:[0,1] neg_hi:[0,1]
	s_nop 0
	v_pk_mul_f32 v[114:115], v[116:117], v[114:115]
	s_nop 0
	v_pk_fma_f32 v[114:115], v[102:103], v[114:115], v[98:99] op_sel_hi:[0,1,0]
	v_cvt_pk_bf16_f32 v85, v114, v115
	v_and_b32_e32 v114, 0xffff0000, v106
	v_and_b32_e32 v115, 0xffff0000, v110
	v_pk_add_f32 v[114:115], v[114:115], v[118:119] neg_lo:[0,1] neg_hi:[0,1]
	ds_write_b32 v177, v85 offset:1216
	v_pk_mul_f32 v[114:115], v[116:117], v[114:115]
	v_and_b32_e32 v106, 0xffff0000, v107
	v_pk_fma_f32 v[114:115], v[102:103], v[114:115], v[98:99] op_sel:[1,0,1]
	s_nop 0
	v_cvt_pk_bf16_f32 v85, v114, v115
	v_lshlrev_b32_e32 v114, 16, v107
	v_lshlrev_b32_e32 v115, 16, v111
	v_and_b32_e32 v107, 0xffff0000, v111
	v_pk_add_f32 v[114:115], v[114:115], v[118:119] neg_lo:[0,1] neg_hi:[0,1]
	v_pk_add_f32 v[106:107], v[106:107], v[118:119] neg_lo:[0,1] neg_hi:[0,1]
	v_pk_mul_f32 v[114:115], v[116:117], v[114:115]
	v_pk_mul_f32 v[106:107], v[116:117], v[106:107]
	ds_write_b32 v177, v85 offset:3392
	v_pk_fma_f32 v[114:115], v[104:105], v[114:115], v[100:101] op_sel_hi:[0,1,0]
	v_cvt_pk_bf16_f32 v85, v114, v115
	v_pk_fma_f32 v[106:107], v[160:161], v[106:107], v[162:163] op_sel_hi:[0,1,0]
	ds_write_b32 v177, v85 offset:5568
	v_cvt_pk_bf16_f32 v85, v106, v107
	v_lshlrev_b32_e32 v106, 16, v108
	v_lshlrev_b32_e32 v107, 16, v112
	v_pk_add_f32 v[106:107], v[106:107], v[118:119] neg_lo:[0,1] neg_hi:[0,1]
	ds_write_b32 v177, v85 offset:7744
	v_pk_mul_f32 v[106:107], v[116:117], v[106:107]
	s_nop 0
	v_pk_fma_f32 v[106:107], v[82:83], v[106:107], v[86:87] op_sel_hi:[0,1,0]
	v_cvt_pk_bf16_f32 v85, v106, v107
	v_and_b32_e32 v106, 0xffff0000, v108
	v_and_b32_e32 v107, 0xffff0000, v112
	v_pk_add_f32 v[106:107], v[106:107], v[118:119] neg_lo:[0,1] neg_hi:[0,1]
	ds_write_b32 v177, v85 offset:9920
	v_pk_mul_f32 v[106:107], v[116:117], v[106:107]
	s_nop 0
	v_pk_fma_f32 v[106:107], v[82:83], v[106:107], v[86:87] op_sel:[1,0,1]
	s_nop 0
	v_cvt_pk_bf16_f32 v85, v106, v107
	v_lshlrev_b32_e32 v106, 16, v109
	v_lshlrev_b32_e32 v107, 16, v113
	v_pk_add_f32 v[106:107], v[106:107], v[118:119] neg_lo:[0,1] neg_hi:[0,1]
	ds_write_b32 v177, v85 offset:12096
	v_pk_mul_f32 v[106:107], v[116:117], v[106:107]
	s_nop 0
	v_pk_fma_f32 v[106:107], v[84:85], v[106:107], v[88:89] op_sel_hi:[0,1,0]
	v_cvt_pk_bf16_f32 v85, v106, v107
	v_and_b32_e32 v106, 0xffff0000, v109
	v_and_b32_e32 v107, 0xffff0000, v113
	v_pk_add_f32 v[106:107], v[106:107], v[118:119] neg_lo:[0,1] neg_hi:[0,1]
	ds_write_b32 v177, v85 offset:14272
	v_pk_mul_f32 v[106:107], v[116:117], v[106:107]
	s_nop 0
	v_pk_fma_f32 v[106:107], v[164:165], v[106:107], v[166:167] op_sel_hi:[0,1,0]
	v_cvt_pk_bf16_f32 v85, v106, v107
	ds_write_b32 v177, v85 offset:16448
	ds_read_b128 v[106:109], v181 offset:896
	s_waitcnt lgkmcnt(0)
; __device__ __forceinline__ unsigned cvt_pk_bf16(float lo, float hi) { unsigned r; asm volatile("v_cvt_pk_bf16_f32 %0, %1, %2" : "=v"(r) : "v"(lo), "v"(hi)); return r; }
; __device__ __forceinline__ float bf_lo(unsigned w) { return __uint_as_float(w << 16); }
; __device__ __forceinline__ void sgu_unit(LAS unsigned char* lds, bf16* U, const bf16* VS, const float* SGS, const float* lnw, const float* lnb, const v4u* WF, const float* bsl, int unit, int tid) {
;     ...
;         LAS unsigned char* wbase = vt + c8 * SGU_VP + rp * 4;
; #pragma unroll
;         for (int i = 0; i < 8; ++i) {
;             const f32x4 st4 = *(const LAS f32x4*)(stat + 4 * (rp + 8 * i));
;             const v4u w0 = sl[i][0], w1 = sl[i][1];
;             const unsigned A0[4] = {w0.x, w0.y, w0.z, w0.w}, A1[4] = {w1.x, w1.y, w1.z, w1.w};
; #pragma unroll
;             for (int e = 0; e < 8; ++e) { typedef float f32x2p __attribute__((ext_vector_type(2)));
;                 f32x2p v; v.x = (e & 1) ? bf_hi(A0[e >> 1]) : bf_lo(A0[e >> 1]); v.y = (e & 1) ? bf_hi(A1[e >> 1]) : bf_lo(A1[e >> 1]);
;                 const f32x2p mn = {st4.x, st4.z}, rs = {st4.y, st4.w};
;                 const f32x2p o = ((v - mn) * rs) * lw[e] + lb[e];
;                 *(LAS unsigned*)(wbase + e * 8 * SGU_VP + i * 32) = cvt_pk_bf16(o.x, o.y); }
;         }
;     }
;     v2u uu[8][4];
; #pragma unroll
;     for (int mt = 0; mt < 8; ++mt)
; #pragma unroll
;         for (int nt = 0; nt < 4; ++nt) uu[mt][nt] = *(const v2u*)(U + (size_t)(r0 + 16 * mt + fr) * 1024 + colbase + 16 * nt + 4 * fq);
;     LDS_WAIT(); asm volatile("" ::: "memory");
;     {
;         int q = 0;
; #pragma unroll
;         for (int mt = 0; mt < 8; ++mt) {
;             const int t = 16 * mt + fr;
;             f32x4 acc[4];
; #pragma unroll
;             for (int nt = 0; nt < 4; ++nt) acc[nt] = (f32x4){0.f, 0.f, 0.f, 0.f};
; #pragma unroll
;             for (int ks = 0; ks <= (mt >> 1); ++ks) {
;                 const int sb = 32 * ks + 8 * fq; const bf16x8_t wf = __builtin_bit_cast(bf16x8_t, wfr[q++]);
; #pragma unroll
;                 for (int nt = 0; nt < 4; ++nt) { const bf16x8_t vf = *(const LAS bf16x8_t*)(vt + ((fr >> 3) + 8 * (fr & 7) + 2 * nt) * SGU_VP + sb * 2);
;                     acc[nt] = __builtin_amdgcn_mfma_f32_16x16x32_bf16(vf, wf, acc[nt], 0, 0, 0); }
;             }
;             const float bb = bbv[mt];
	v_mov_b32_e32 v110, v106
	v_mov_b32_e32 v111, v108
	v_mov_b32_e32 v108, v107
	s_waitcnt vmcnt(1)
	v_lshlrev_b32_e32 v106, 16, v90
	s_waitcnt vmcnt(0)
	v_lshlrev_b32_e32 v107, 16, v94
	v_pk_add_f32 v[106:107], v[106:107], v[110:111] neg_lo:[0,1] neg_hi:[0,1]
	s_nop 0
	v_pk_mul_f32 v[106:107], v[108:109], v[106:107]
	s_nop 0
	v_pk_fma_f32 v[106:107], v[102:103], v[106:107], v[98:99] op_sel_hi:[0,1,0]
	v_cvt_pk_bf16_f32 v85, v106, v107
	v_and_b32_e32 v106, 0xffff0000, v90
	v_and_b32_e32 v107, 0xffff0000, v94
	v_pk_add_f32 v[106:107], v[106:107], v[110:111] neg_lo:[0,1] neg_hi:[0,1]
	ds_write_b32 v177, v85 offset:1248
	v_pk_mul_f32 v[106:107], v[108:109], v[106:107]
	v_and_b32_e32 v90, 0xffff0000, v91
	v_pk_fma_f32 v[98:99], v[102:103], v[106:107], v[98:99] op_sel:[1,0,1]
	s_nop 0
	v_cvt_pk_bf16_f32 v85, v98, v99
	v_lshlrev_b32_e32 v98, 16, v91
	v_lshlrev_b32_e32 v99, 16, v95
	v_and_b32_e32 v91, 0xffff0000, v95
	v_pk_add_f32 v[98:99], v[98:99], v[110:111] neg_lo:[0,1] neg_hi:[0,1]
	v_pk_add_f32 v[90:91], v[90:91], v[110:111] neg_lo:[0,1] neg_hi:[0,1]
	v_pk_mul_f32 v[98:99], v[108:109], v[98:99]
	v_pk_mul_f32 v[90:91], v[108:109], v[90:91]
	ds_write_b32 v177, v85 offset:3424
	v_pk_fma_f32 v[98:99], v[104:105], v[98:99], v[100:101] op_sel_hi:[0,1,0]
	v_cvt_pk_bf16_f32 v85, v98, v99
	v_pk_fma_f32 v[90:91], v[160:161], v[90:91], v[162:163] op_sel_hi:[0,1,0]
	ds_write_b32 v177, v85 offset:5600
	v_cvt_pk_bf16_f32 v85, v90, v91
	v_lshlrev_b32_e32 v90, 16, v92
	v_lshlrev_b32_e32 v91, 16, v96
	v_pk_add_f32 v[90:91], v[90:91], v[110:111] neg_lo:[0,1] neg_hi:[0,1]
	ds_write_b32 v177, v85 offset:7776
	v_pk_mul_f32 v[90:91], v[108:109], v[90:91]
	s_nop 0
	v_pk_fma_f32 v[90:91], v[82:83], v[90:91], v[86:87] op_sel_hi:[0,1,0]
	v_cvt_pk_bf16_f32 v85, v90, v91
	v_and_b32_e32 v90, 0xffff0000, v92
	v_and_b32_e32 v91, 0xffff0000, v96
	v_pk_add_f32 v[90:91], v[90:91], v[110:111] neg_lo:[0,1] neg_hi:[0,1]
	ds_write_b32 v177, v85 offset:9952
	v_pk_mul_f32 v[90:91], v[108:109], v[90:91]
	s_nop 0
	v_pk_fma_f32 v[82:83], v[82:83], v[90:91], v[86:87] op_sel:[1,0,1]
	s_nop 0
	v_cvt_pk_bf16_f32 v82, v82, v83
	ds_write_b32 v177, v82 offset:12128
	v_lshlrev_b32_e32 v82, 16, v93
	v_lshlrev_b32_e32 v83, 16, v97
	v_pk_add_f32 v[82:83], v[82:83], v[110:111] neg_lo:[0,1] neg_hi:[0,1]
	s_nop 0
	v_pk_mul_f32 v[82:83], v[108:109], v[82:83]
	s_nop 0
	v_pk_fma_f32 v[82:83], v[84:85], v[82:83], v[88:89] op_sel_hi:[0,1,0]
	v_cvt_pk_bf16_f32 v82, v82, v83
	ds_write_b32 v177, v82 offset:14304
	v_and_b32_e32 v82, 0xffff0000, v93
	v_and_b32_e32 v83, 0xffff0000, v97
	v_pk_add_f32 v[82:83], v[82:83], v[110:111] neg_lo:[0,1] neg_hi:[0,1]
	v_or_b32_e32 v84, s18, v163
	v_pk_mul_f32 v[82:83], v[108:109], v[82:83]
	v_lshlrev_b32_e32 v84, 11, v84
	v_pk_fma_f32 v[82:83], v[164:165], v[82:83], v[166:167] op_sel_hi:[0,1,0]
	v_cvt_pk_bf16_f32 v82, v82, v83
	ds_write_b32 v177, v82 offset:16480
	v_lshl_add_u64 v[82:83], v[158:159], 1, v[150:151]
	v_mov_b32_e32 v85, v147
	v_lshl_add_u64 v[144:145], v[82:83], 0, v[84:85]
	global_load_dwordx2 v[158:159], v[144:145], off
	global_load_dwordx2 v[210:211], v[144:145], off offset:32
	global_load_dwordx2 v[212:213], v[144:145], off offset:64
	global_load_dwordx2 v[214:215], v[144:145], off offset:96
	v_add_co_u32_e32 v216, vcc, s43, v144
	v_addc_co_u32_e32 v217, vcc, 0, v145, vcc
	global_load_dwordx2 v[218:219], v[216:217], off
	global_load_dwordx2 v[220:221], v[216:217], off offset:32
	global_load_dwordx2 v[222:223], v[216:217], off offset:64
	global_load_dwordx2 v[224:225], v[216:217], off offset:96
	v_add_co_u32_e32 v130, vcc, s53, v144
	s_nop 0
	v_addc_co_u32_e32 v131, vcc, 0, v145, vcc
	v_add_co_u32_e32 v120, vcc, s54, v144
	global_load_dwordx2 v[226:227], v[130:131], off
	global_load_dwordx2 v[138:139], v[130:131], off offset:32
	global_load_dwordx2 v[136:137], v[130:131], off offset:64
	global_load_dwordx2 v[134:135], v[130:131], off offset:96
	v_addc_co_u32_e32 v121, vcc, 0, v145, vcc
	v_add_co_u32_e32 v110, vcc, s55, v144
	global_load_dwordx2 v[132:133], v[120:121], off
	global_load_dwordx2 v[128:129], v[120:121], off offset:32
	global_load_dwordx2 v[126:127], v[120:121], off offset:64
	global_load_dwordx2 v[124:125], v[120:121], off offset:96
	v_addc_co_u32_e32 v111, vcc, 0, v145, vcc
	v_add_co_u32_e32 v100, vcc, s56, v144
	global_load_dwordx2 v[122:123], v[110:111], off
	global_load_dwordx2 v[118:119], v[110:111], off offset:32
	global_load_dwordx2 v[116:117], v[110:111], off offset:64
	global_load_dwordx2 v[114:115], v[110:111], off offset:96
	v_addc_co_u32_e32 v101, vcc, 0, v145, vcc
	v_add_co_u32_e32 v90, vcc, s57, v144
	global_load_dwordx2 v[112:113], v[100:101], off
	global_load_dwordx2 v[108:109], v[100:101], off offset:32
	global_load_dwordx2 v[106:107], v[100:101], off offset:64
	global_load_dwordx2 v[104:105], v[100:101], off offset:96
	v_addc_co_u32_e32 v91, vcc, 0, v145, vcc
	v_add_co_u32_e32 v82, vcc, s58, v144
	global_load_dwordx2 v[102:103], v[90:91], off
	global_load_dwordx2 v[98:99], v[90:91], off offset:32
	global_load_dwordx2 v[96:97], v[90:91], off offset:64
	global_load_dwordx2 v[94:95], v[90:91], off offset:96
	v_addc_co_u32_e32 v83, vcc, 0, v145, vcc
	global_load_dwordx2 v[92:93], v[82:83], off
	global_load_dwordx2 v[88:89], v[82:83], off offset:32
	global_load_dwordx2 v[86:87], v[82:83], off offset:64
	global_load_dwordx2 v[84:85], v[82:83], off offset:96
	s_waitcnt lgkmcnt(0)
	ds_read_b128 v[140:143], v182 offset:1024
	ds_read_b128 v[198:201], v182 offset:1568
	s_waitcnt lgkmcnt(1)
	v_mfma_f32_16x16x32_bf16 v[140:143], v[140:143], v[78:81], 0
	ds_read_b128 v[202:205], v182 offset:2112
	ds_read_b128 v[206:209], v182 offset:2656
	s_nop 5
	v_add_f32_e32 v140, v197, v140
	v_add_f32_e32 v141, v197, v141
	s_waitcnt lgkmcnt(2)
; __device__ __forceinline__ unsigned cvt_pk_bf16(float lo, float hi) { unsigned r; asm volatile("v_cvt_pk_bf16_f32 %0, %1, %2" : "=v"(r) : "v"(lo), "v"(hi)); return r; }
; __device__ __forceinline__ float bf_lo(unsigned w) { return __uint_as_float(w << 16); }
; __device__ __forceinline__ float bf_hi(unsigned w) { return __uint_as_float(w & 0xffff0000u); }
; #define LAS __attribute__((address_space(3)))
; __device__ __forceinline__ void sgu_unit(LAS unsigned char* lds, bf16* U, const bf16* VS, const float* SGS, const float* lnw, const float* lnb, const v4u* WF, const float* bsl, int unit, int tid) {
;     ...
;         for (int mt = 0; mt < 8; ++mt) {
;             const int t = 16 * mt + fr;
;             f32x4 acc[4];
; #pragma unroll
;             for (int nt = 0; nt < 4; ++nt) acc[nt] = (f32x4){0.f, 0.f, 0.f, 0.f};
; #pragma unroll
;             for (int ks = 0; ks <= (mt >> 1); ++ks) {
;                 const int sb = 32 * ks + 8 * fq; const bf16x8_t wf = __builtin_bit_cast(bf16x8_t, wfr[q++]);
; #pragma unroll
;                 for (int nt = 0; nt < 4; ++nt) { const bf16x8_t vf = *(const LAS bf16x8_t*)(vt + ((fr >> 3) + 8 * (fr & 7) + 2 * nt) * SGU_VP + sb * 2);
;                     acc[nt] = __builtin_amdgcn_mfma_f32_16x16x32_bf16(vf, wf, acc[nt], 0, 0, 0); }
;             }
;             const float bb = bbv[mt];
; #pragma unroll
;             for (int nt = 0; nt < 4; ++nt) { const v2u u2 = uu[mt][nt]; v2u w; w.x = cvt_pk_bf16(bf_lo(u2.x) * (acc[nt][0] + bb), bf_hi(u2.x) * (acc[nt][1] + bb)); w.y = cvt_pk_bf16(bf_lo(u2.y) * (acc[nt][2] + bb), bf_hi(u2.y) * (acc[nt][3] + bb));
;                 *(v2u*)(U + (size_t)(r0 + t) * 1024 + colbase + 16 * nt + 4 * fq) = w; }
	v_mfma_f32_16x16x32_bf16 v[198:201], v[198:201], v[78:81], 0
	s_waitcnt vmcnt(31)
	v_lshlrev_b32_e32 v160, 16, v158
	v_and_b32_e32 v158, 0xffff0000, v158
	s_nop 0
	v_mul_f32_e32 v140, v140, v160
	v_mul_f32_e32 v141, v141, v158
	v_cvt_pk_bf16_f32 v140, v140, v141
	v_lshlrev_b32_e32 v141, 16, v159
	v_add_f32_e32 v142, v197, v142
	v_mul_f32_e32 v141, v142, v141
	v_and_b32_e32 v142, 0xffff0000, v159
	v_add_f32_e32 v143, v197, v143
	v_mul_f32_e32 v142, v143, v142
	v_cvt_pk_bf16_f32 v141, v141, v142
	global_store_dwordx2 v[144:145], v[140:141], off
	s_waitcnt vmcnt(31)
	v_lshlrev_b32_e32 v140, 16, v210
	v_add_f32_e32 v141, v197, v198
	v_mul_f32_e32 v140, v141, v140
	v_and_b32_e32 v141, 0xffff0000, v210
	v_add_f32_e32 v142, v197, v199
	s_waitcnt lgkmcnt(1)
	v_mfma_f32_16x16x32_bf16 v[202:205], v[202:205], v[78:81], 0
	v_mul_f32_e32 v141, v142, v141
	v_cvt_pk_bf16_f32 v140, v140, v141
	v_lshlrev_b32_e32 v141, 16, v211
	v_add_f32_e32 v142, v197, v200
	v_mul_f32_e32 v141, v142, v141
	v_and_b32_e32 v142, 0xffff0000, v211
	v_add_f32_e32 v143, v197, v201
	v_mul_f32_e32 v142, v143, v142
	v_cvt_pk_bf16_f32 v141, v141, v142
	global_store_dwordx2 v[144:145], v[140:141], off offset:32
	s_waitcnt vmcnt(31)
	v_lshlrev_b32_e32 v140, 16, v212
	v_add_f32_e32 v141, v197, v202
	s_waitcnt lgkmcnt(0)
	v_mfma_f32_16x16x32_bf16 v[78:81], v[206:209], v[78:81], 0
	v_mul_f32_e32 v140, v141, v140
	v_and_b32_e32 v141, 0xffff0000, v212
	v_add_f32_e32 v142, v197, v203
	v_mul_f32_e32 v141, v142, v141
	v_cvt_pk_bf16_f32 v140, v140, v141
	v_lshlrev_b32_e32 v141, 16, v213
	v_add_f32_e32 v142, v197, v204
	v_mul_f32_e32 v141, v142, v141
	v_and_b32_e32 v142, 0xffff0000, v213
	v_add_f32_e32 v143, v197, v205
	v_mul_f32_e32 v142, v143, v142
	v_cvt_pk_bf16_f32 v141, v141, v142
	global_store_dwordx2 v[144:145], v[140:141], off offset:64
	s_waitcnt vmcnt(31)
	v_lshlrev_b32_e32 v140, 16, v214
	v_add_f32_e32 v78, v197, v78
	v_mul_f32_e32 v78, v78, v140
	v_and_b32_e32 v140, 0xffff0000, v214
	v_add_f32_e32 v79, v197, v79
	v_mul_f32_e32 v79, v79, v140
	v_cvt_pk_bf16_f32 v158, v78, v79
	v_lshlrev_b32_e32 v78, 16, v215
	v_add_f32_e32 v79, v197, v80
	v_mul_f32_e32 v78, v79, v78
	v_and_b32_e32 v79, 0xffff0000, v215
	v_add_f32_e32 v80, v197, v81
	v_mul_f32_e32 v79, v80, v79
	v_cvt_pk_bf16_f32 v159, v78, v79
	ds_read_b128 v[78:81], v182 offset:1024
	ds_read_b128 v[140:143], v182 offset:1568
	s_waitcnt lgkmcnt(1)
	v_mfma_f32_16x16x32_bf16 v[78:81], v[78:81], v[74:77], 0
	ds_read_b128 v[198:201], v182 offset:2112
	ds_read_b128 v[202:205], v182 offset:2656
	global_store_dwordx2 v[144:145], v[158:159], off offset:96
	s_waitcnt vmcnt(31)
	v_lshlrev_b32_e32 v144, 16, v218
	s_nop 2
	v_add_f32_e32 v78, v196, v78
	v_mul_f32_e32 v78, v78, v144
	v_and_b32_e32 v144, 0xffff0000, v218
	v_add_f32_e32 v79, v196, v79
	s_waitcnt lgkmcnt(2)
	v_mfma_f32_16x16x32_bf16 v[140:143], v[140:143], v[74:77], 0
	v_mul_f32_e32 v79, v79, v144
	v_cvt_pk_bf16_f32 v78, v78, v79
	v_lshlrev_b32_e32 v79, 16, v219
	v_add_f32_e32 v80, v196, v80
	v_mul_f32_e32 v79, v80, v79
	v_and_b32_e32 v80, 0xffff0000, v219
	v_add_f32_e32 v81, v196, v81
	v_mul_f32_e32 v80, v81, v80
	v_cvt_pk_bf16_f32 v79, v79, v80
	global_store_dwordx2 v[216:217], v[78:79], off
	s_waitcnt vmcnt(31)
	v_lshlrev_b32_e32 v78, 16, v220
	v_add_f32_e32 v79, v196, v140
	v_mul_f32_e32 v78, v79, v78
	v_and_b32_e32 v79, 0xffff0000, v220
	v_add_f32_e32 v80, v196, v141
	s_waitcnt lgkmcnt(1)
	v_mfma_f32_16x16x32_bf16 v[198:201], v[198:201], v[74:77], 0
	v_mul_f32_e32 v79, v80, v79
	v_cvt_pk_bf16_f32 v78, v78, v79
	v_lshlrev_b32_e32 v79, 16, v221
	v_add_f32_e32 v80, v196, v142
	v_mul_f32_e32 v79, v80, v79
	v_and_b32_e32 v80, 0xffff0000, v221
	v_add_f32_e32 v81, v196, v143
	v_mul_f32_e32 v80, v81, v80
	v_cvt_pk_bf16_f32 v79, v79, v80
	global_store_dwordx2 v[216:217], v[78:79], off offset:32
	s_waitcnt vmcnt(31)
	v_lshlrev_b32_e32 v78, 16, v222
	v_add_f32_e32 v79, v196, v198
	s_waitcnt lgkmcnt(0)
	v_mfma_f32_16x16x32_bf16 v[74:77], v[202:205], v[74:77], 0
	v_mul_f32_e32 v78, v79, v78
	v_and_b32_e32 v79, 0xffff0000, v222
	v_add_f32_e32 v80, v196, v199
	v_mul_f32_e32 v79, v80, v79
	v_cvt_pk_bf16_f32 v78, v78, v79
	v_lshlrev_b32_e32 v79, 16, v223
	v_add_f32_e32 v80, v196, v200
	v_mul_f32_e32 v79, v80, v79
	v_and_b32_e32 v80, 0xffff0000, v223
	v_add_f32_e32 v81, v196, v201
	v_mul_f32_e32 v80, v81, v80
	v_cvt_pk_bf16_f32 v79, v79, v80
	global_store_dwordx2 v[216:217], v[78:79], off offset:64
	s_waitcnt vmcnt(31)
	v_lshlrev_b32_e32 v78, 16, v224
	v_add_f32_e32 v74, v196, v74
	v_mul_f32_e32 v74, v74, v78
	v_and_b32_e32 v78, 0xffff0000, v224
	v_add_f32_e32 v75, v196, v75
	v_mul_f32_e32 v75, v75, v78
	v_cvt_pk_bf16_f32 v144, v74, v75
	v_lshlrev_b32_e32 v74, 16, v225
	v_add_f32_e32 v75, v196, v76
	v_mul_f32_e32 v74, v75, v74
	v_and_b32_e32 v75, 0xffff0000, v225
	v_add_f32_e32 v76, v196, v77
	v_mul_f32_e32 v75, v76, v75
	v_cvt_pk_bf16_f32 v145, v74, v75
	ds_read_b128 v[74:77], v182 offset:1024
	ds_read_b128 v[78:81], v182 offset:1088
	s_waitcnt lgkmcnt(1)
	v_mfma_f32_16x16x32_bf16 v[74:77], v[74:77], v[70:73], 0
	ds_read_b128 v[140:143], v182 offset:1568
	ds_read_b128 v[196:199], v182 offset:1632
	ds_read_b128 v[200:203], v182 offset:2112
	ds_read_b128 v[204:207], v182 offset:2176
	ds_read_b128 v[208:211], v182 offset:2656
	ds_read_b128 v[212:215], v182 offset:2720
	s_waitcnt lgkmcnt(5)
	v_mfma_f32_16x16x32_bf16 v[140:143], v[140:143], v[70:73], 0
	global_store_dwordx2 v[216:217], v[144:145], off offset:96
	s_waitcnt lgkmcnt(3)
	v_mfma_f32_16x16x32_bf16 v[200:203], v[200:203], v[70:73], 0
	s_waitcnt lgkmcnt(1)
; __device__ __forceinline__ unsigned cvt_pk_bf16(float lo, float hi) { unsigned r; asm volatile("v_cvt_pk_bf16_f32 %0, %1, %2" : "=v"(r) : "v"(lo), "v"(hi)); return r; }
; __device__ __forceinline__ float bf_lo(unsigned w) { return __uint_as_float(w << 16); }
; __device__ __forceinline__ float bf_hi(unsigned w) { return __uint_as_float(w & 0xffff0000u); }
; #define LAS __attribute__((address_space(3)))
; __device__ __forceinline__ void sgu_unit(LAS unsigned char* lds, bf16* U, const bf16* VS, const float* SGS, const float* lnw, const float* lnb, const v4u* WF, const float* bsl, int unit, int tid) {
;     ...
;         for (int mt = 0; mt < 8; ++mt) {
;             const int t = 16 * mt + fr;
;             f32x4 acc[4];
; #pragma unroll
;             for (int nt = 0; nt < 4; ++nt) acc[nt] = (f32x4){0.f, 0.f, 0.f, 0.f};
; #pragma unroll
;             for (int ks = 0; ks <= (mt >> 1); ++ks) {
;                 const int sb = 32 * ks + 8 * fq; const bf16x8_t wf = __builtin_bit_cast(bf16x8_t, wfr[q++]);
; #pragma unroll
;                 for (int nt = 0; nt < 4; ++nt) { const bf16x8_t vf = *(const LAS bf16x8_t*)(vt + ((fr >> 3) + 8 * (fr & 7) + 2 * nt) * SGU_VP + sb * 2);
;                     acc[nt] = __builtin_amdgcn_mfma_f32_16x16x32_bf16(vf, wf, acc[nt], 0, 0, 0); }
;             }
;             const float bb = bbv[mt];
; #pragma unroll
;             for (int nt = 0; nt < 4; ++nt) { const v2u u2 = uu[mt][nt]; v2u w; w.x = cvt_pk_bf16(bf_lo(u2.x) * (acc[nt][0] + bb), bf_hi(u2.x) * (acc[nt][1] + bb)); w.y = cvt_pk_bf16(bf_lo(u2.y) * (acc[nt][2] + bb), bf_hi(u2.y) * (acc[nt][3] + bb));
;                 *(v2u*)(U + (size_t)(r0 + t) * 1024 + colbase + 16 * nt + 4 * fq) = w; }
	v_mfma_f32_16x16x32_bf16 v[70:73], v[208:211], v[70:73], 0
	v_mfma_f32_16x16x32_bf16 v[74:77], v[78:81], v[66:69], v[74:77]
	v_mfma_f32_16x16x32_bf16 v[78:81], v[196:199], v[66:69], v[140:143]
	v_mfma_f32_16x16x32_bf16 v[140:143], v[204:207], v[66:69], v[200:203]
	s_waitcnt lgkmcnt(0)
	v_mfma_f32_16x16x32_bf16 v[66:69], v[212:215], v[66:69], v[70:73]
	s_waitcnt vmcnt(31)
	s_nop 1
	v_lshlrev_b32_e32 v70, 16, v226
	v_add_f32_e32 v71, v195, v74
	v_mul_f32_e32 v70, v71, v70
	v_and_b32_e32 v71, 0xffff0000, v226
	v_add_f32_e32 v72, v195, v75
	v_mul_f32_e32 v71, v72, v71
	v_cvt_pk_bf16_f32 v70, v70, v71
	v_lshlrev_b32_e32 v71, 16, v227
	v_add_f32_e32 v72, v195, v76
	v_mul_f32_e32 v71, v72, v71
	v_and_b32_e32 v72, 0xffff0000, v227
	v_add_f32_e32 v73, v195, v77
	v_mul_f32_e32 v72, v73, v72
	v_cvt_pk_bf16_f32 v71, v71, v72
	global_store_dwordx2 v[130:131], v[70:71], off
	s_waitcnt vmcnt(31)
	v_lshlrev_b32_e32 v70, 16, v138
	v_add_f32_e32 v71, v195, v78
	v_mul_f32_e32 v70, v71, v70
	v_and_b32_e32 v71, 0xffff0000, v138
	v_add_f32_e32 v72, v195, v79
	v_mul_f32_e32 v71, v72, v71
	v_cvt_pk_bf16_f32 v70, v70, v71
	v_lshlrev_b32_e32 v71, 16, v139
	v_add_f32_e32 v72, v195, v80
	v_mul_f32_e32 v71, v72, v71
	v_and_b32_e32 v72, 0xffff0000, v139
	v_add_f32_e32 v73, v195, v81
	v_mul_f32_e32 v72, v73, v72
	v_cvt_pk_bf16_f32 v71, v71, v72
	global_store_dwordx2 v[130:131], v[70:71], off offset:32
	s_waitcnt vmcnt(31)
	v_lshlrev_b32_e32 v70, 16, v136
	v_add_f32_e32 v71, v195, v140
	v_mul_f32_e32 v70, v71, v70
	v_and_b32_e32 v71, 0xffff0000, v136
	v_add_f32_e32 v72, v195, v141
	v_mul_f32_e32 v71, v72, v71
	v_cvt_pk_bf16_f32 v70, v70, v71
	v_lshlrev_b32_e32 v71, 16, v137
	v_add_f32_e32 v72, v195, v142
	v_mul_f32_e32 v71, v72, v71
	v_and_b32_e32 v72, 0xffff0000, v137
	v_add_f32_e32 v73, v195, v143
	v_mul_f32_e32 v72, v73, v72
	v_cvt_pk_bf16_f32 v71, v71, v72
	global_store_dwordx2 v[130:131], v[70:71], off offset:64
	s_waitcnt vmcnt(31)
	v_lshlrev_b32_e32 v70, 16, v134
	v_add_f32_e32 v66, v195, v66
	v_mul_f32_e32 v66, v66, v70
	v_and_b32_e32 v70, 0xffff0000, v134
	v_add_f32_e32 v67, v195, v67
	v_mul_f32_e32 v67, v67, v70
	v_cvt_pk_bf16_f32 v158, v66, v67
	v_lshlrev_b32_e32 v66, 16, v135
	v_add_f32_e32 v67, v195, v68
	v_mul_f32_e32 v66, v67, v66
	v_and_b32_e32 v67, 0xffff0000, v135
	v_add_f32_e32 v68, v195, v69
	v_mul_f32_e32 v67, v68, v67
	v_cvt_pk_bf16_f32 v159, v66, v67
	ds_read_b128 v[66:69], v182 offset:1024
	ds_read_b128 v[70:73], v182 offset:1088
	s_waitcnt lgkmcnt(1)
	v_mfma_f32_16x16x32_bf16 v[66:69], v[66:69], v[62:65], 0
	ds_read_b128 v[74:77], v182 offset:1568
	ds_read_b128 v[78:81], v182 offset:1632
	ds_read_b128 v[134:137], v182 offset:2112
	ds_read_b128 v[138:141], v182 offset:2176
	ds_read_b128 v[142:145], v182 offset:2656
	ds_read_b128 v[196:199], v182 offset:2720
	s_waitcnt lgkmcnt(5)
	v_mfma_f32_16x16x32_bf16 v[74:77], v[74:77], v[62:65], 0
	global_store_dwordx2 v[130:131], v[158:159], off offset:96
	s_waitcnt lgkmcnt(3)
	v_mfma_f32_16x16x32_bf16 v[134:137], v[134:137], v[62:65], 0
	s_waitcnt lgkmcnt(1)
	v_mfma_f32_16x16x32_bf16 v[62:65], v[142:145], v[62:65], 0
	v_mfma_f32_16x16x32_bf16 v[66:69], v[70:73], v[58:61], v[66:69]
	v_mfma_f32_16x16x32_bf16 v[70:73], v[78:81], v[58:61], v[74:77]
	v_mfma_f32_16x16x32_bf16 v[74:77], v[138:141], v[58:61], v[134:137]
	s_waitcnt lgkmcnt(0)
	v_mfma_f32_16x16x32_bf16 v[58:61], v[196:199], v[58:61], v[62:65]
	s_waitcnt vmcnt(31)
	s_nop 1
	v_lshlrev_b32_e32 v62, 16, v132
	v_add_f32_e32 v63, v194, v66
	v_mul_f32_e32 v62, v63, v62
	v_and_b32_e32 v63, 0xffff0000, v132
	v_add_f32_e32 v64, v194, v67
	v_mul_f32_e32 v63, v64, v63
	v_cvt_pk_bf16_f32 v62, v62, v63
	v_lshlrev_b32_e32 v63, 16, v133
	v_add_f32_e32 v64, v194, v68
	v_mul_f32_e32 v63, v64, v63
	v_and_b32_e32 v64, 0xffff0000, v133
	v_add_f32_e32 v65, v194, v69
	v_mul_f32_e32 v64, v65, v64
	v_cvt_pk_bf16_f32 v63, v63, v64
	global_store_dwordx2 v[120:121], v[62:63], off
	s_waitcnt vmcnt(31)
	v_lshlrev_b32_e32 v62, 16, v128
	v_add_f32_e32 v63, v194, v70
	v_mul_f32_e32 v62, v63, v62
	v_and_b32_e32 v63, 0xffff0000, v128
	v_add_f32_e32 v64, v194, v71
	v_mul_f32_e32 v63, v64, v63
	v_cvt_pk_bf16_f32 v62, v62, v63
	v_lshlrev_b32_e32 v63, 16, v129
	v_add_f32_e32 v64, v194, v72
	v_mul_f32_e32 v63, v64, v63
	v_and_b32_e32 v64, 0xffff0000, v129
	v_add_f32_e32 v65, v194, v73
	v_mul_f32_e32 v64, v65, v64
	v_cvt_pk_bf16_f32 v63, v63, v64
	global_store_dwordx2 v[120:121], v[62:63], off offset:32
	s_waitcnt vmcnt(31)
	v_lshlrev_b32_e32 v62, 16, v126
	v_add_f32_e32 v63, v194, v74
	v_mul_f32_e32 v62, v63, v62
	v_and_b32_e32 v63, 0xffff0000, v126
	v_add_f32_e32 v64, v194, v75
	v_mul_f32_e32 v63, v64, v63
	v_cvt_pk_bf16_f32 v62, v62, v63
	v_lshlrev_b32_e32 v63, 16, v127
	v_add_f32_e32 v64, v194, v76
	v_mul_f32_e32 v63, v64, v63
	v_and_b32_e32 v64, 0xffff0000, v127
	v_add_f32_e32 v65, v194, v77
	v_mul_f32_e32 v64, v65, v64
	v_cvt_pk_bf16_f32 v63, v63, v64
	global_store_dwordx2 v[120:121], v[62:63], off offset:64
	s_waitcnt vmcnt(31)
	v_lshlrev_b32_e32 v62, 16, v124
	v_add_f32_e32 v58, v194, v58
	v_mul_f32_e32 v58, v58, v62
	v_and_b32_e32 v62, 0xffff0000, v124
	v_add_f32_e32 v59, v194, v59
	v_mul_f32_e32 v59, v59, v62
	v_cvt_pk_bf16_f32 v132, v58, v59
	v_lshlrev_b32_e32 v58, 16, v125
	v_add_f32_e32 v59, v194, v60
	v_mul_f32_e32 v58, v59, v58
	v_and_b32_e32 v59, 0xffff0000, v125
	v_add_f32_e32 v60, v194, v61
	v_mul_f32_e32 v59, v60, v59
	v_cvt_pk_bf16_f32 v133, v58, v59
	ds_read_b128 v[58:61], v182 offset:1024
	ds_read_b128 v[62:65], v182 offset:1088
	s_waitcnt lgkmcnt(1)
; __device__ __forceinline__ unsigned cvt_pk_bf16(float lo, float hi) { unsigned r; asm volatile("v_cvt_pk_bf16_f32 %0, %1, %2" : "=v"(r) : "v"(lo), "v"(hi)); return r; }
; __device__ __forceinline__ float bf_lo(unsigned w) { return __uint_as_float(w << 16); }
; __device__ __forceinline__ float bf_hi(unsigned w) { return __uint_as_float(w & 0xffff0000u); }
; #define LAS __attribute__((address_space(3)))
; __device__ __forceinline__ void sgu_unit(LAS unsigned char* lds, bf16* U, const bf16* VS, const float* SGS, const float* lnw, const float* lnb, const v4u* WF, const float* bsl, int unit, int tid) {
;     ...
;         for (int mt = 0; mt < 8; ++mt) {
;             const int t = 16 * mt + fr;
;             f32x4 acc[4];
; #pragma unroll
;             for (int nt = 0; nt < 4; ++nt) acc[nt] = (f32x4){0.f, 0.f, 0.f, 0.f};
; #pragma unroll
;             for (int ks = 0; ks <= (mt >> 1); ++ks) {
;                 const int sb = 32 * ks + 8 * fq; const bf16x8_t wf = __builtin_bit_cast(bf16x8_t, wfr[q++]);
; #pragma unroll
;                 for (int nt = 0; nt < 4; ++nt) { const bf16x8_t vf = *(const LAS bf16x8_t*)(vt + ((fr >> 3) + 8 * (fr & 7) + 2 * nt) * SGU_VP + sb * 2);
;                     acc[nt] = __builtin_amdgcn_mfma_f32_16x16x32_bf16(vf, wf, acc[nt], 0, 0, 0); }
;             }
;             const float bb = bbv[mt];
; #pragma unroll
;             for (int nt = 0; nt < 4; ++nt) { const v2u u2 = uu[mt][nt]; v2u w; w.x = cvt_pk_bf16(bf_lo(u2.x) * (acc[nt][0] + bb), bf_hi(u2.x) * (acc[nt][1] + bb)); w.y = cvt_pk_bf16(bf_lo(u2.y) * (acc[nt][2] + bb), bf_hi(u2.y) * (acc[nt][3] + bb));
;                 *(v2u*)(U + (size_t)(r0 + t) * 1024 + colbase + 16 * nt + 4 * fq) = w; }
	v_mfma_f32_16x16x32_bf16 v[58:61], v[58:61], v[50:53], 0
	ds_read_b128 v[66:69], v182 offset:1568
	ds_read_b128 v[70:73], v182 offset:1152
	ds_read_b128 v[74:77], v182 offset:2112
	ds_read_b128 v[78:81], v182 offset:2176
	ds_read_b128 v[124:127], v182 offset:2656
	ds_read_b128 v[128:131], v182 offset:2240
	s_waitcnt lgkmcnt(5)
	v_mfma_f32_16x16x32_bf16 v[66:69], v[66:69], v[50:53], 0
	s_waitcnt lgkmcnt(3)
	v_mfma_f32_16x16x32_bf16 v[74:77], v[74:77], v[50:53], 0
	s_waitcnt lgkmcnt(1)
	v_mfma_f32_16x16x32_bf16 v[50:53], v[124:127], v[50:53], 0
	v_mfma_f32_16x16x32_bf16 v[58:61], v[62:65], v[54:57], v[58:61]
	ds_read_b128 v[62:65], v182 offset:1632
	ds_read_b128 v[124:127], v182 offset:1696
	s_waitcnt lgkmcnt(1)
	v_mfma_f32_16x16x32_bf16 v[62:65], v[62:65], v[54:57], v[66:69]
	v_mfma_f32_16x16x32_bf16 v[66:69], v[78:81], v[54:57], v[74:77]
	s_nop 2
	ds_read_b128 v[74:77], v182 offset:2720
	ds_read_b128 v[78:81], v182 offset:2784
	global_store_dwordx2 v[120:121], v[132:133], off offset:96
	s_waitcnt lgkmcnt(1)
	v_mfma_f32_16x16x32_bf16 v[50:53], v[74:77], v[54:57], v[50:53]
	v_mfma_f32_16x16x32_bf16 v[54:57], v[70:73], v[46:49], v[58:61]
	v_mfma_f32_16x16x32_bf16 v[58:61], v[124:127], v[46:49], v[62:65]
	v_mfma_f32_16x16x32_bf16 v[62:65], v[128:131], v[46:49], v[66:69]
	s_waitcnt lgkmcnt(0)
	v_mfma_f32_16x16x32_bf16 v[46:49], v[78:81], v[46:49], v[50:53]
	s_waitcnt vmcnt(31)
	s_nop 1
	v_lshlrev_b32_e32 v50, 16, v122
	v_add_f32_e32 v51, v193, v54
	v_mul_f32_e32 v50, v51, v50
	v_and_b32_e32 v51, 0xffff0000, v122
	v_add_f32_e32 v52, v193, v55
	v_mul_f32_e32 v51, v52, v51
	v_cvt_pk_bf16_f32 v50, v50, v51
	v_lshlrev_b32_e32 v51, 16, v123
	v_add_f32_e32 v52, v193, v56
	v_mul_f32_e32 v51, v52, v51
	v_and_b32_e32 v52, 0xffff0000, v123
	v_add_f32_e32 v53, v193, v57
	v_mul_f32_e32 v52, v53, v52
	v_cvt_pk_bf16_f32 v51, v51, v52
	global_store_dwordx2 v[110:111], v[50:51], off
	s_waitcnt vmcnt(31)
	v_lshlrev_b32_e32 v50, 16, v118
	v_add_f32_e32 v51, v193, v58
	v_mul_f32_e32 v50, v51, v50
	v_and_b32_e32 v51, 0xffff0000, v118
	v_add_f32_e32 v52, v193, v59
	v_mul_f32_e32 v51, v52, v51
	v_cvt_pk_bf16_f32 v50, v50, v51
	v_lshlrev_b32_e32 v51, 16, v119
	v_add_f32_e32 v52, v193, v60
	v_mul_f32_e32 v51, v52, v51
	v_and_b32_e32 v52, 0xffff0000, v119
	v_add_f32_e32 v53, v193, v61
	v_mul_f32_e32 v52, v53, v52
	v_cvt_pk_bf16_f32 v51, v51, v52
	global_store_dwordx2 v[110:111], v[50:51], off offset:32
	s_waitcnt vmcnt(31)
	v_lshlrev_b32_e32 v50, 16, v116
	v_add_f32_e32 v51, v193, v62
	v_mul_f32_e32 v50, v51, v50
	v_and_b32_e32 v51, 0xffff0000, v116
	v_add_f32_e32 v52, v193, v63
	v_mul_f32_e32 v51, v52, v51
	v_cvt_pk_bf16_f32 v50, v50, v51
	v_lshlrev_b32_e32 v51, 16, v117
	v_add_f32_e32 v52, v193, v64
	v_mul_f32_e32 v51, v52, v51
	v_and_b32_e32 v52, 0xffff0000, v117
	v_add_f32_e32 v53, v193, v65
	v_mul_f32_e32 v52, v53, v52
	v_cvt_pk_bf16_f32 v51, v51, v52
	global_store_dwordx2 v[110:111], v[50:51], off offset:64
	s_waitcnt vmcnt(31)
	v_lshlrev_b32_e32 v50, 16, v114
	v_add_f32_e32 v46, v193, v46
	v_mul_f32_e32 v46, v46, v50
	v_and_b32_e32 v50, 0xffff0000, v114
	v_add_f32_e32 v47, v193, v47
	v_mul_f32_e32 v47, v47, v50
	v_cvt_pk_bf16_f32 v78, v46, v47
	v_lshlrev_b32_e32 v46, 16, v115
	v_add_f32_e32 v47, v193, v48
	v_mul_f32_e32 v46, v47, v46
	v_and_b32_e32 v47, 0xffff0000, v115
	v_add_f32_e32 v48, v193, v49
	v_mul_f32_e32 v47, v48, v47
	v_cvt_pk_bf16_f32 v79, v46, v47
	ds_read_b128 v[46:49], v182 offset:1024
	ds_read_b128 v[50:53], v182 offset:1088
	s_waitcnt lgkmcnt(1)
	v_mfma_f32_16x16x32_bf16 v[46:49], v[46:49], v[42:45], 0
	ds_read_b128 v[54:57], v182 offset:1568
	ds_read_b128 v[58:61], v182 offset:1152
	ds_read_b128 v[62:65], v182 offset:2112
	ds_read_b128 v[66:69], v182 offset:2176
	ds_read_b128 v[70:73], v182 offset:2656
	ds_read_b128 v[74:77], v182 offset:2240
	s_waitcnt lgkmcnt(5)
	v_mfma_f32_16x16x32_bf16 v[54:57], v[54:57], v[42:45], 0
	s_waitcnt lgkmcnt(3)
	v_mfma_f32_16x16x32_bf16 v[62:65], v[62:65], v[42:45], 0
	s_waitcnt lgkmcnt(1)
	v_mfma_f32_16x16x32_bf16 v[42:45], v[70:73], v[42:45], 0
	v_mfma_f32_16x16x32_bf16 v[46:49], v[50:53], v[34:37], v[46:49]
	ds_read_b128 v[50:53], v182 offset:1632
	ds_read_b128 v[70:73], v182 offset:1696
	s_waitcnt lgkmcnt(1)
	v_mfma_f32_16x16x32_bf16 v[50:53], v[50:53], v[34:37], v[54:57]
	v_mfma_f32_16x16x32_bf16 v[54:57], v[66:69], v[34:37], v[62:65]
	s_nop 2
	ds_read_b128 v[62:65], v182 offset:2720
	ds_read_b128 v[66:69], v182 offset:2784
	global_store_dwordx2 v[110:111], v[78:79], off offset:96
	s_waitcnt lgkmcnt(1)
	v_mfma_f32_16x16x32_bf16 v[34:37], v[62:65], v[34:37], v[42:45]
	v_mfma_f32_16x16x32_bf16 v[42:45], v[58:61], v[38:41], v[46:49]
	v_mfma_f32_16x16x32_bf16 v[46:49], v[70:73], v[38:41], v[50:53]
	v_mfma_f32_16x16x32_bf16 v[50:53], v[74:77], v[38:41], v[54:57]
	s_waitcnt lgkmcnt(0)
	v_mfma_f32_16x16x32_bf16 v[34:37], v[66:69], v[38:41], v[34:37]
	s_waitcnt vmcnt(31)
	v_lshlrev_b32_e32 v38, 16, v112
	s_nop 1
	v_add_f32_e32 v39, v192, v42
	v_mul_f32_e32 v38, v39, v38
	v_and_b32_e32 v39, 0xffff0000, v112
	v_add_f32_e32 v40, v192, v43
	v_mul_f32_e32 v39, v40, v39
	v_cvt_pk_bf16_f32 v38, v38, v39
	v_lshlrev_b32_e32 v39, 16, v113
	v_add_f32_e32 v40, v192, v44
	v_mul_f32_e32 v39, v40, v39
	v_and_b32_e32 v40, 0xffff0000, v113
	v_add_f32_e32 v41, v192, v45
	v_mul_f32_e32 v40, v41, v40
	v_cvt_pk_bf16_f32 v39, v39, v40
	global_store_dwordx2 v[100:101], v[38:39], off
	s_waitcnt vmcnt(31)
; __device__ __forceinline__ unsigned cvt_pk_bf16(float lo, float hi) { unsigned r; asm volatile("v_cvt_pk_bf16_f32 %0, %1, %2" : "=v"(r) : "v"(lo), "v"(hi)); return r; }
; __device__ __forceinline__ float bf_lo(unsigned w) { return __uint_as_float(w << 16); }
; __device__ __forceinline__ float bf_hi(unsigned w) { return __uint_as_float(w & 0xffff0000u); }
; #define LAS __attribute__((address_space(3)))
; __device__ __forceinline__ void sgu_unit(LAS unsigned char* lds, bf16* U, const bf16* VS, const float* SGS, const float* lnw, const float* lnb, const v4u* WF, const float* bsl, int unit, int tid) {
;     ...
;         for (int mt = 0; mt < 8; ++mt) {
;             const int t = 16 * mt + fr;
;             f32x4 acc[4];
; #pragma unroll
;             for (int nt = 0; nt < 4; ++nt) acc[nt] = (f32x4){0.f, 0.f, 0.f, 0.f};
; #pragma unroll
;             for (int ks = 0; ks <= (mt >> 1); ++ks) {
;                 const int sb = 32 * ks + 8 * fq; const bf16x8_t wf = __builtin_bit_cast(bf16x8_t, wfr[q++]);
; #pragma unroll
;                 for (int nt = 0; nt < 4; ++nt) { const bf16x8_t vf = *(const LAS bf16x8_t*)(vt + ((fr >> 3) + 8 * (fr & 7) + 2 * nt) * SGU_VP + sb * 2);
;                     acc[nt] = __builtin_amdgcn_mfma_f32_16x16x32_bf16(vf, wf, acc[nt], 0, 0, 0); }
;             }
;             const float bb = bbv[mt];
; #pragma unroll
;             for (int nt = 0; nt < 4; ++nt) { const v2u u2 = uu[mt][nt]; v2u w; w.x = cvt_pk_bf16(bf_lo(u2.x) * (acc[nt][0] + bb), bf_hi(u2.x) * (acc[nt][1] + bb)); w.y = cvt_pk_bf16(bf_lo(u2.y) * (acc[nt][2] + bb), bf_hi(u2.y) * (acc[nt][3] + bb));
;                 *(v2u*)(U + (size_t)(r0 + t) * 1024 + colbase + 16 * nt + 4 * fq) = w; }
	v_lshlrev_b32_e32 v38, 16, v108
	v_add_f32_e32 v39, v192, v46
	v_mul_f32_e32 v38, v39, v38
	v_and_b32_e32 v39, 0xffff0000, v108
	v_add_f32_e32 v40, v192, v47
	v_mul_f32_e32 v39, v40, v39
	v_cvt_pk_bf16_f32 v38, v38, v39
	v_lshlrev_b32_e32 v39, 16, v109
	v_add_f32_e32 v40, v192, v48
	v_mul_f32_e32 v39, v40, v39
	v_and_b32_e32 v40, 0xffff0000, v109
	v_add_f32_e32 v41, v192, v49
	v_mul_f32_e32 v40, v41, v40
	v_cvt_pk_bf16_f32 v39, v39, v40
	global_store_dwordx2 v[100:101], v[38:39], off offset:32
	s_waitcnt vmcnt(31)
	v_lshlrev_b32_e32 v38, 16, v106
	v_add_f32_e32 v39, v192, v50
	v_mul_f32_e32 v38, v39, v38
	v_and_b32_e32 v39, 0xffff0000, v106
	v_add_f32_e32 v40, v192, v51
	v_mul_f32_e32 v39, v40, v39
	v_cvt_pk_bf16_f32 v38, v38, v39
	v_lshlrev_b32_e32 v39, 16, v107
	v_add_f32_e32 v40, v192, v52
	v_mul_f32_e32 v39, v40, v39
	v_and_b32_e32 v40, 0xffff0000, v107
	v_add_f32_e32 v41, v192, v53
	v_mul_f32_e32 v40, v41, v40
	v_cvt_pk_bf16_f32 v39, v39, v40
	global_store_dwordx2 v[100:101], v[38:39], off offset:64
	s_waitcnt vmcnt(31)
	v_lshlrev_b32_e32 v38, 16, v104
	v_add_f32_e32 v34, v192, v34
	v_mul_f32_e32 v34, v34, v38
	v_and_b32_e32 v38, 0xffff0000, v104
	v_add_f32_e32 v35, v192, v35
	v_mul_f32_e32 v35, v35, v38
	v_cvt_pk_bf16_f32 v66, v34, v35
	v_lshlrev_b32_e32 v34, 16, v105
	v_add_f32_e32 v35, v192, v36
	v_mul_f32_e32 v34, v35, v34
	v_and_b32_e32 v35, 0xffff0000, v105
	v_add_f32_e32 v36, v192, v37
	v_mul_f32_e32 v35, v36, v35
	v_cvt_pk_bf16_f32 v67, v34, v35
	ds_read_b128 v[34:37], v182 offset:1024
	ds_read_b128 v[38:41], v182 offset:1088
	ds_read_b128 v[42:45], v182 offset:1568
	ds_read_b128 v[46:49], v182 offset:1632
	ds_read_b128 v[50:53], v182 offset:2112
	ds_read_b128 v[54:57], v182 offset:2176
	ds_read_b128 v[58:61], v182 offset:2656
	ds_read_b128 v[62:65], v182 offset:2720
	s_waitcnt lgkmcnt(7)
	v_mfma_f32_16x16x32_bf16 v[34:37], v[34:37], v[30:33], 0
	s_waitcnt lgkmcnt(5)
	v_mfma_f32_16x16x32_bf16 v[42:45], v[42:45], v[30:33], 0
	s_waitcnt lgkmcnt(3)
	v_mfma_f32_16x16x32_bf16 v[50:53], v[50:53], v[30:33], 0
	s_waitcnt lgkmcnt(1)
	v_mfma_f32_16x16x32_bf16 v[30:33], v[58:61], v[30:33], 0
	v_mfma_f32_16x16x32_bf16 v[34:37], v[38:41], v[26:29], v[34:37]
	v_mfma_f32_16x16x32_bf16 v[38:41], v[46:49], v[26:29], v[42:45]
	v_mfma_f32_16x16x32_bf16 v[42:45], v[54:57], v[26:29], v[50:53]
	s_waitcnt lgkmcnt(0)
	v_mfma_f32_16x16x32_bf16 v[26:29], v[62:65], v[26:29], v[30:33]
	s_nop 2
	ds_read_b128 v[30:33], v182 offset:1152
	ds_read_b128 v[46:49], v182 offset:1216
	s_waitcnt lgkmcnt(1)
	v_mfma_f32_16x16x32_bf16 v[30:33], v[30:33], v[22:25], v[34:37]
	s_nop 2
	ds_read_b128 v[34:37], v182 offset:1696
	ds_read_b128 v[50:53], v182 offset:1760
	s_waitcnt lgkmcnt(1)
	v_mfma_f32_16x16x32_bf16 v[34:37], v[34:37], v[22:25], v[38:41]
	s_nop 2
	ds_read_b128 v[38:41], v182 offset:2240
	ds_read_b128 v[54:57], v182 offset:2304
	s_waitcnt lgkmcnt(1)
	v_mfma_f32_16x16x32_bf16 v[38:41], v[38:41], v[22:25], v[42:45]
	s_nop 2
	ds_read_b128 v[42:45], v182 offset:2784
	ds_read_b128 v[58:61], v182 offset:2848
	global_store_dwordx2 v[100:101], v[66:67], off offset:96
	s_waitcnt lgkmcnt(1)
	v_mfma_f32_16x16x32_bf16 v[22:25], v[42:45], v[22:25], v[26:29]
	v_mfma_f32_16x16x32_bf16 v[26:29], v[46:49], v[18:21], v[30:33]
	v_mfma_f32_16x16x32_bf16 v[30:33], v[50:53], v[18:21], v[34:37]
	v_mfma_f32_16x16x32_bf16 v[34:37], v[54:57], v[18:21], v[38:41]
	s_waitcnt lgkmcnt(0)
	v_mfma_f32_16x16x32_bf16 v[18:21], v[58:61], v[18:21], v[22:25]
	s_waitcnt vmcnt(31)
	s_nop 1
	v_lshlrev_b32_e32 v22, 16, v102
	v_add_f32_e32 v23, v191, v26
	v_mul_f32_e32 v22, v23, v22
	v_and_b32_e32 v23, 0xffff0000, v102
	v_add_f32_e32 v24, v191, v27
	v_mul_f32_e32 v23, v24, v23
	v_cvt_pk_bf16_f32 v22, v22, v23
	v_lshlrev_b32_e32 v23, 16, v103
	v_add_f32_e32 v24, v191, v28
	v_mul_f32_e32 v23, v24, v23
	v_and_b32_e32 v24, 0xffff0000, v103
	v_add_f32_e32 v25, v191, v29
	v_mul_f32_e32 v24, v25, v24
	v_cvt_pk_bf16_f32 v23, v23, v24
	global_store_dwordx2 v[90:91], v[22:23], off
	s_waitcnt vmcnt(31)
	v_lshlrev_b32_e32 v22, 16, v98
	v_add_f32_e32 v23, v191, v30
	v_mul_f32_e32 v22, v23, v22
	v_and_b32_e32 v23, 0xffff0000, v98
	v_add_f32_e32 v24, v191, v31
	v_mul_f32_e32 v23, v24, v23
	v_cvt_pk_bf16_f32 v22, v22, v23
	v_lshlrev_b32_e32 v23, 16, v99
	v_add_f32_e32 v24, v191, v32
	v_mul_f32_e32 v23, v24, v23
	v_and_b32_e32 v24, 0xffff0000, v99
	v_add_f32_e32 v25, v191, v33
	v_mul_f32_e32 v24, v25, v24
	v_cvt_pk_bf16_f32 v23, v23, v24
	global_store_dwordx2 v[90:91], v[22:23], off offset:32
	s_waitcnt vmcnt(31)
; __device__ __forceinline__ unsigned cvt_pk_bf16(float lo, float hi) { unsigned r; asm volatile("v_cvt_pk_bf16_f32 %0, %1, %2" : "=v"(r) : "v"(lo), "v"(hi)); return r; }
; __device__ __forceinline__ float bf_lo(unsigned w) { return __uint_as_float(w << 16); }
; __device__ __forceinline__ float bf_hi(unsigned w) { return __uint_as_float(w & 0xffff0000u); }
; #define LAS __attribute__((address_space(3)))
; __device__ __forceinline__ void sgu_unit(LAS unsigned char* lds, bf16* U, const bf16* VS, const float* SGS, const float* lnw, const float* lnb, const v4u* WF, const float* bsl, int unit, int tid) {
;     ...
;         for (int mt = 0; mt < 8; ++mt) {
;             const int t = 16 * mt + fr;
;             f32x4 acc[4];
; #pragma unroll
;             for (int nt = 0; nt < 4; ++nt) acc[nt] = (f32x4){0.f, 0.f, 0.f, 0.f};
; #pragma unroll
;             for (int ks = 0; ks <= (mt >> 1); ++ks) {
;                 const int sb = 32 * ks + 8 * fq; const bf16x8_t wf = __builtin_bit_cast(bf16x8_t, wfr[q++]);
; #pragma unroll
;                 for (int nt = 0; nt < 4; ++nt) { const bf16x8_t vf = *(const LAS bf16x8_t*)(vt + ((fr >> 3) + 8 * (fr & 7) + 2 * nt) * SGU_VP + sb * 2);
;                     acc[nt] = __builtin_amdgcn_mfma_f32_16x16x32_bf16(vf, wf, acc[nt], 0, 0, 0); }
;             }
;             const float bb = bbv[mt];
; #pragma unroll
;             for (int nt = 0; nt < 4; ++nt) { const v2u u2 = uu[mt][nt]; v2u w; w.x = cvt_pk_bf16(bf_lo(u2.x) * (acc[nt][0] + bb), bf_hi(u2.x) * (acc[nt][1] + bb)); w.y = cvt_pk_bf16(bf_lo(u2.y) * (acc[nt][2] + bb), bf_hi(u2.y) * (acc[nt][3] + bb));
;                 *(v2u*)(U + (size_t)(r0 + t) * 1024 + colbase + 16 * nt + 4 * fq) = w; }
;         }
;     }
;     __syncthreads();
	v_lshlrev_b32_e32 v22, 16, v96
	v_add_f32_e32 v23, v191, v34
	v_mul_f32_e32 v22, v23, v22
	v_and_b32_e32 v23, 0xffff0000, v96
	v_add_f32_e32 v24, v191, v35
	v_mul_f32_e32 v23, v24, v23
	v_cvt_pk_bf16_f32 v22, v22, v23
	v_lshlrev_b32_e32 v23, 16, v97
	v_add_f32_e32 v24, v191, v36
	v_mul_f32_e32 v23, v24, v23
	v_and_b32_e32 v24, 0xffff0000, v97
	v_add_f32_e32 v25, v191, v37
	v_mul_f32_e32 v24, v25, v24
	v_cvt_pk_bf16_f32 v23, v23, v24
	global_store_dwordx2 v[90:91], v[22:23], off offset:64
	s_waitcnt vmcnt(31)
	v_lshlrev_b32_e32 v22, 16, v94
	v_add_f32_e32 v18, v191, v18
	v_mul_f32_e32 v18, v18, v22
	v_and_b32_e32 v22, 0xffff0000, v94
	v_add_f32_e32 v19, v191, v19
	v_mul_f32_e32 v19, v19, v22
	v_cvt_pk_bf16_f32 v50, v18, v19
	v_lshlrev_b32_e32 v18, 16, v95
	v_add_f32_e32 v19, v191, v20
	v_mul_f32_e32 v18, v19, v18
	v_and_b32_e32 v19, 0xffff0000, v95
	v_add_f32_e32 v20, v191, v21
	v_mul_f32_e32 v19, v20, v19
	v_cvt_pk_bf16_f32 v51, v18, v19
	ds_read_b128 v[18:21], v182 offset:1024
	ds_read_b128 v[22:25], v182 offset:1088
	ds_read_b128 v[26:29], v182 offset:1568
	ds_read_b128 v[30:33], v182 offset:1632
	ds_read_b128 v[34:37], v182 offset:2112
	ds_read_b128 v[38:41], v182 offset:2176
	ds_read_b128 v[42:45], v182 offset:2656
	ds_read_b128 v[46:49], v182 offset:2720
	s_waitcnt lgkmcnt(7)
	v_mfma_f32_16x16x32_bf16 v[18:21], v[18:21], v[14:17], 0
	s_waitcnt lgkmcnt(5)
	v_mfma_f32_16x16x32_bf16 v[26:29], v[26:29], v[14:17], 0
	s_waitcnt lgkmcnt(3)
	v_mfma_f32_16x16x32_bf16 v[34:37], v[34:37], v[14:17], 0
	s_waitcnt lgkmcnt(1)
	v_mfma_f32_16x16x32_bf16 v[14:17], v[42:45], v[14:17], 0
	v_mfma_f32_16x16x32_bf16 v[18:21], v[22:25], v[10:13], v[18:21]
	v_mfma_f32_16x16x32_bf16 v[22:25], v[30:33], v[10:13], v[26:29]
	v_mfma_f32_16x16x32_bf16 v[26:29], v[38:41], v[10:13], v[34:37]
	s_waitcnt lgkmcnt(0)
	v_mfma_f32_16x16x32_bf16 v[10:13], v[46:49], v[10:13], v[14:17]
	s_nop 2
	ds_read_b128 v[14:17], v182 offset:1152
	ds_read_b128 v[30:33], v182 offset:1216
	s_waitcnt lgkmcnt(1)
	v_mfma_f32_16x16x32_bf16 v[14:17], v[14:17], v[6:9], v[18:21]
	s_nop 2
	ds_read_b128 v[18:21], v182 offset:1696
	ds_read_b128 v[34:37], v182 offset:1760
	s_waitcnt lgkmcnt(1)
	v_mfma_f32_16x16x32_bf16 v[18:21], v[18:21], v[6:9], v[22:25]
	s_nop 2
	ds_read_b128 v[22:25], v182 offset:2240
	ds_read_b128 v[38:41], v182 offset:2304
	s_waitcnt lgkmcnt(1)
	v_mfma_f32_16x16x32_bf16 v[22:25], v[22:25], v[6:9], v[26:29]
	s_nop 2
	ds_read_b128 v[26:29], v182 offset:2784
	ds_read_b128 v[42:45], v182 offset:2848
	global_store_dwordx2 v[90:91], v[50:51], off offset:96
	s_waitcnt lgkmcnt(1)
	v_mfma_f32_16x16x32_bf16 v[6:9], v[26:29], v[6:9], v[10:13]
	v_mfma_f32_16x16x32_bf16 v[10:13], v[30:33], v[2:5], v[14:17]
	v_mfma_f32_16x16x32_bf16 v[14:17], v[34:37], v[2:5], v[18:21]
	v_mfma_f32_16x16x32_bf16 v[18:21], v[38:41], v[2:5], v[22:25]
	s_waitcnt lgkmcnt(0)
	v_mfma_f32_16x16x32_bf16 v[2:5], v[42:45], v[2:5], v[6:9]
	s_waitcnt vmcnt(31)
	s_nop 1
	v_lshlrev_b32_e32 v6, 16, v92
	v_add_f32_e32 v7, v157, v10
	v_mul_f32_e32 v6, v7, v6
	v_and_b32_e32 v7, 0xffff0000, v92
	v_add_f32_e32 v8, v157, v11
	v_mul_f32_e32 v7, v8, v7
	v_cvt_pk_bf16_f32 v6, v6, v7
	v_lshlrev_b32_e32 v7, 16, v93
	v_add_f32_e32 v8, v157, v12
	v_mul_f32_e32 v7, v8, v7
	v_and_b32_e32 v8, 0xffff0000, v93
	v_add_f32_e32 v9, v157, v13
	v_mul_f32_e32 v8, v9, v8
	v_cvt_pk_bf16_f32 v7, v7, v8
	global_store_dwordx2 v[82:83], v[6:7], off
	s_waitcnt vmcnt(31)
	v_lshlrev_b32_e32 v6, 16, v88
	v_add_f32_e32 v7, v157, v14
	v_mul_f32_e32 v6, v7, v6
	v_and_b32_e32 v7, 0xffff0000, v88
	v_add_f32_e32 v8, v157, v15
	v_mul_f32_e32 v7, v8, v7
	v_cvt_pk_bf16_f32 v6, v6, v7
	v_lshlrev_b32_e32 v7, 16, v89
	v_add_f32_e32 v8, v157, v16
	v_mul_f32_e32 v7, v8, v7
	v_and_b32_e32 v8, 0xffff0000, v89
	v_add_f32_e32 v9, v157, v17
	v_mul_f32_e32 v8, v9, v8
	v_cvt_pk_bf16_f32 v7, v7, v8
	global_store_dwordx2 v[82:83], v[6:7], off offset:32
	s_waitcnt vmcnt(31)
	v_lshlrev_b32_e32 v6, 16, v86
	v_add_f32_e32 v7, v157, v18
	v_mul_f32_e32 v6, v7, v6
	v_and_b32_e32 v7, 0xffff0000, v86
	v_add_f32_e32 v8, v157, v19
	v_mul_f32_e32 v7, v8, v7
	v_cvt_pk_bf16_f32 v6, v6, v7
	v_lshlrev_b32_e32 v7, 16, v87
	v_add_f32_e32 v8, v157, v20
	v_mul_f32_e32 v7, v8, v7
	v_and_b32_e32 v8, 0xffff0000, v87
	v_add_f32_e32 v9, v157, v21
	v_mul_f32_e32 v8, v9, v8
	v_cvt_pk_bf16_f32 v7, v7, v8
	global_store_dwordx2 v[82:83], v[6:7], off offset:64
	s_waitcnt vmcnt(31)
	v_lshlrev_b32_e32 v6, 16, v84
	v_add_f32_e32 v2, v157, v2
	v_mul_f32_e32 v2, v2, v6
	v_and_b32_e32 v6, 0xffff0000, v84
	v_add_f32_e32 v3, v157, v3
	v_mul_f32_e32 v3, v3, v6
	v_cvt_pk_bf16_f32 v2, v2, v3
	v_lshlrev_b32_e32 v3, 16, v85
	v_add_f32_e32 v4, v157, v4
	v_mul_f32_e32 v3, v4, v3
	v_and_b32_e32 v4, 0xffff0000, v85
	v_add_f32_e32 v5, v157, v5
	v_mul_f32_e32 v4, v5, v4
	v_cvt_pk_bf16_f32 v3, v3, v4
	global_store_dwordx2 v[82:83], v[2:3], off offset:96
	s_barrier
